# wave reductions in the attention and LayerNorm epilogues: serialized ds_bpermute round trips replaced by DPP moves (xor 1,2,4,8) and v_permlane16/32_swap (xor 16,32)
# speedup vs baseline: 1.0163x; 1.0163x over previous
; #define SBAR() __builtin_amdgcn_sched_barrier(0)
; #define NAM(P0, P1, t) do { if constexpr (NA) na_mask(P0, P1, kr_lo + (t), r0, qrow, qc, c0, hi, bl); } while (0)
; #define PSM(P0, P1, MN, AL) do { if constexpr (NA) partialSM(P0, P1, m_reg, MN, AL); else { AL = 1.f; _Pragma("unroll") for (int r = 0; r < 16; ++r) P0[r] = __builtin_amdgcn_exp2f(P0[r]); } } while (0)
; #define RESCN(a) do { if constexpr (NA) RESC(a); } while (0)
; #define NAM(P0, P1, t) do { if constexpr (NA) na_mask(P0, P1, kr_lo + (t), r0, qrow, qc, c0, hi, bl); } while (0)
; #define PSM(P0, P1, MN, AL) do { if constexpr (NA) partialSM(P0, P1, m_reg, MN, AL); else { AL = 1.f; _Pragma("unroll") for (int r = 0; r < 16; ++r) P0[r] = __builtin_amdgcn_exp2f(P0[r]); } } while (0)
; #define RESCN(a) do { if constexpr (NA) RESC(a); } while (0)
; __device__ __forceinline__ void finishSM(f32x16& p0, f32x16& p1, float alpha, float& l_reg, bf16x8& pa0, bf16x8& pa1, bf16x8& pa2, bf16x8& pa3) {
;   for (int r = 0; r < 16; ++r) p1[r] = __builtin_amdgcn_exp2f(p1[r]);
;   float ps = 0; for (int r = 0; r < 16; ++r) ps += p0[r]; for (int r = 0; r < 16; ++r) ps += p1[r];
;   { auto rr = __builtin_amdgcn_permlane32_swap(__float_as_uint(ps), __float_as_uint(ps), false, false);
;     ps = __uint_as_float(rr[0]) + __uint_as_float(rr[1]); }
;   l_reg = l_reg * alpha + ps;
;     ...
;   PK4(p0, 0, pa0); PK4(p0, 8, pa1); PK4(p1, 0, pa2); PK4(p1, 8, pa3);
; template <bool NA, int ROWB>
; __device__ __forceinline__ void attn_dma(const bf16* __restrict__ Qb, const bf16* __restrict__ Kh, const bf16* __restrict__ Vh, bf16* __restrict__ Ob, int NT, char* lds, const int tid, float* __restrict__ ssb, int qrow0, int kr_lo, const float* bl) {
;     ...
;   SBAR(); qkt<false>(pB0, pB1, (const bf16*)(K_lds + bc * SHM_K), qr, nullptr, r32, hi); NAM(pB0, pB1, NT - 1);
;   finishSM(pA0, pA1, alA, l_reg, pa0, pa1, pa2, pa3); SBAR();
;   pv_d0(o, vb0 + bp * (int)SHM_V, pa0, pa1, pa2, pa3); PSM(pB0, pB1, mnB, alB); RESCN(alB);
;   finishSM(pB0, pB1, alB, l_reg, pa0, pa1, pa2, pa3); SBAR();
.Lgqa_trail:
	s_nop 15
	v_exp_f32_e32 v212, v80
	v_exp_f32_e32 v214, v81
	v_exp_f32_e32 v210, v82
	v_exp_f32_e32 v213, v83
	v_exp_f32_e32 v208, v84
	v_exp_f32_e32 v211, v85
	v_exp_f32_e32 v207, v86
	v_exp_f32_e32 v209, v87
	v_exp_f32_e32 v203, v88
	v_exp_f32_e32 v206, v89
	v_exp_f32_e32 v198, v90
	v_exp_f32_e32 v205, v91
	v_exp_f32_e32 v196, v92
	v_exp_f32_e32 v199, v93
	v_exp_f32_e32 v175, v94
	v_exp_f32_e32 v197, v95
	v_exp_f32_e32 v64, v64
	v_exp_f32_e32 v65, v65
	v_exp_f32_e32 v66, v66
	v_exp_f32_e32 v67, v67
	v_exp_f32_e32 v68, v68
	v_exp_f32_e32 v69, v69
	v_exp_f32_e32 v70, v70
	v_exp_f32_e32 v71, v71
	v_exp_f32_e32 v72, v72
	v_exp_f32_e32 v73, v73
	v_exp_f32_e32 v74, v74
	v_exp_f32_e32 v75, v75
	v_exp_f32_e32 v76, v76
	v_exp_f32_e32 v77, v77
	v_exp_f32_e32 v78, v78
	v_exp_f32_e32 v79, v79
	v_mov_b32_e32 v228, v112
	s_nop 1
	v_permlane32_swap_b32_e32 v112, v228
	v_add_f32_e32 v112, v112, v228
	s_add_i32 s0, 0, 0x10000
	v_add_u32_e32 v84, s0, v187
	ds_read_b128 v[80:83], v84
	ds_read_b128 v[154:157], v84 offset:8192
	v_add_u32_e32 v100, s0, v188
	ds_read_b128 v[96:99], v100
	ds_read_b128 v[158:161], v100 offset:8192
	v_add_u32_e32 v100, s0, v189
	s_waitcnt lgkmcnt(3)
	v_mfma_f32_32x32x16_bf16 v[80:95], v[80:83], v[138:141], 0
	s_nop 0
	v_mov_b32_e32 v180, v66
	v_mov_b32_e32 v181, v67
	v_mov_b32_e32 v182, v68
	v_mov_b32_e32 v183, v69
	v_mov_b32_e32 v215, v70
	v_mov_b32_e32 v216, v71
	v_mov_b32_e32 v217, v72
	s_waitcnt lgkmcnt(1)
	v_mfma_f32_32x32x16_bf16 v[80:95], v[96:99], v[142:145], v[80:95]
	ds_read_b128 v[96:99], v100
	ds_read_b128 v[150:153], v100 offset:8192
	v_mov_b32_e32 v218, v73
	v_mov_b32_e32 v219, v74
	v_mov_b32_e32 v220, v75
	v_mov_b32_e32 v221, v76
	v_mov_b32_e32 v222, v77
	v_mov_b32_e32 v223, v78
	s_waitcnt lgkmcnt(1)
	v_mfma_f32_32x32x16_bf16 v[80:95], v[96:99], v[134:137], v[80:95]
	v_add_u32_e32 v96, s0, v190
	ds_read_b128 v[100:103], v96
	ds_read_b128 v[96:99], v96 offset:8192
	v_mov_b32_e32 v79, v79
	s_waitcnt lgkmcnt(1)
	v_mfma_f32_32x32x16_bf16 v[80:95], v[100:103], v[114:117], v[80:95]
	v_add_u32_e32 v100, s0, v191
	ds_read_b128 v[104:107], v100
	ds_read_b128 v[100:103], v100 offset:8192
	s_waitcnt lgkmcnt(1)
	v_mfma_f32_32x32x16_bf16 v[80:95], v[104:107], v[118:121], v[80:95]
	v_add_u32_e32 v104, s0, v192
	ds_read_b128 v[108:111], v104
	ds_read_b128 v[104:107], v104 offset:8192
	s_waitcnt lgkmcnt(1)
	v_mfma_f32_32x32x16_bf16 v[80:95], v[108:111], v[122:125], v[80:95]
	v_add_u32_e32 v108, s0, v193
	ds_read_b128 v[146:149], v108
	ds_read_b128 v[108:111], v108 offset:8192
	s_waitcnt lgkmcnt(1)
	v_mfma_f32_32x32x16_bf16 v[80:95], v[146:149], v[126:129], v[80:95]
	v_add_u32_e32 v146, s0, v194
	ds_read_b128 v[176:179], v146
	ds_read_b128 v[146:149], v146 offset:8192
	s_waitcnt lgkmcnt(1)
	v_mfma_f32_32x32x16_bf16 v[80:95], v[176:179], v[130:133], v[80:95]
	v_mov_b32_e32 v177, v64
	v_add_f32_e32 v64, 0, v212
	v_add_f32_e32 v64, v214, v64
	v_add_f32_e32 v64, v210, v64
	v_add_f32_e32 v64, v213, v64
	v_add_f32_e32 v64, v208, v64
	v_add_f32_e32 v64, v211, v64
	v_add_f32_e32 v64, v207, v64
	v_add_f32_e32 v64, v209, v64
	v_add_f32_e32 v64, v203, v64
	v_add_f32_e32 v64, v206, v64
	v_add_f32_e32 v64, v198, v64
	v_add_f32_e32 v64, v205, v64
	v_add_f32_e32 v64, v196, v64
	v_mov_b32_e32 v179, v65
	v_add_f32_e32 v64, v199, v64
	v_add_f32_e32 v64, v175, v64
	v_add_f32_e32 v64, v197, v64
	v_add_f32_e32 v64, v64, v177
	v_add_f32_e32 v64, v179, v64
	v_add_f32_e32 v64, v180, v64
	v_add_f32_e32 v64, v181, v64
	v_add_f32_e32 v64, v182, v64
	v_add_f32_e32 v64, v183, v64
	v_add_f32_e32 v64, v215, v64
	v_add_f32_e32 v64, v216, v64
	v_add_f32_e32 v64, v217, v64
	v_add_f32_e32 v64, v218, v64
	v_add_f32_e32 v64, v219, v64
	v_add_f32_e32 v64, v220, v64
	v_add_f32_e32 v64, v221, v64
	v_add_f32_e32 v64, v222, v64
	v_add_f32_e32 v64, v223, v64
	v_add_f32_e32 v176, v79, v64
	v_mov_b32_e32 v178, v176
	s_nop 1
	v_permlane32_swap_b32_e32 v176, v178
	v_cvt_pk_bf16_f32 v64, v212, v214
	v_cvt_pk_bf16_f32 v65, v210, v213
	v_cvt_pk_bf16_f32 v66, v208, v211
	v_cvt_pk_bf16_f32 v67, v207, v209
	v_cvt_pk_bf16_f32 v68, v203, v206
	v_cvt_pk_bf16_f32 v69, v198, v205
	v_cvt_pk_bf16_f32 v70, v196, v199
	v_cvt_pk_bf16_f32 v71, v175, v197
	v_cvt_pk_bf16_f32 v72, v177, v179
	v_cvt_pk_bf16_f32 v73, v180, v181
	v_cvt_pk_bf16_f32 v74, v182, v183
	v_cvt_pk_bf16_f32 v75, v215, v216
	v_cvt_pk_bf16_f32 v76, v217, v218
	v_cvt_pk_bf16_f32 v77, v219, v220
	v_cvt_pk_bf16_f32 v78, v221, v222
	v_cvt_pk_bf16_f32 v79, v223, v79
	s_nop 0
	ds_read_b64_tr_b16 v[180:181], v195 offset:0
	ds_read_b64_tr_b16 v[182:183], v195 offset:0x800
	ds_read_b64_tr_b16 v[196:197], v195 offset:0x1000
	ds_read_b64_tr_b16 v[198:199], v195 offset:0x1800
	ds_read_b64_tr_b16 v[206:207], v195 offset:0x2000
	ds_read_b64_tr_b16 v[208:209], v195 offset:0x2800
	ds_read_b64_tr_b16 v[210:211], v195 offset:0x3000
	ds_read_b64_tr_b16 v[212:213], v195 offset:0x3800
	s_waitcnt lgkmcnt(0)
	s_nop 0
	v_mfma_f32_32x32x16_bf16 v[0:15], v[64:67], v[180:183], v[0:15]
	ds_read_b64_tr_b16 v[180:181], v195 offset:0x200
	ds_read_b64_tr_b16 v[182:183], v195 offset:0xa00
	v_mfma_f32_32x32x16_bf16 v[0:15], v[68:71], v[196:199], v[0:15]
	ds_read_b64_tr_b16 v[196:197], v195 offset:0x1200
	ds_read_b64_tr_b16 v[198:199], v195 offset:0x1a00
	v_mfma_f32_32x32x16_bf16 v[0:15], v[72:75], v[206:209], v[0:15]
	ds_read_b64_tr_b16 v[206:207], v195 offset:0x2200
	ds_read_b64_tr_b16 v[208:209], v195 offset:0x2a00
	v_mfma_f32_32x32x16_bf16 v[0:15], v[76:79], v[210:213], v[0:15]
	ds_read_b64_tr_b16 v[210:211], v195 offset:0x3200
	ds_read_b64_tr_b16 v[212:213], v195 offset:0x3a00
	s_waitcnt lgkmcnt(0)
; #define SBAR() __builtin_amdgcn_sched_barrier(0)
; #define NAM(P0, P1, t) do { if constexpr (NA) na_mask(P0, P1, kr_lo + (t), r0, qrow, qc, c0, hi, bl); } while (0)
; #define PSM(P0, P1, MN, AL) do { if constexpr (NA) partialSM(P0, P1, m_reg, MN, AL); else { AL = 1.f; _Pragma("unroll") for (int r = 0; r < 16; ++r) P0[r] = __builtin_amdgcn_exp2f(P0[r]); } } while (0)
; #define RESCN(a) do { if constexpr (NA) RESC(a); } while (0)
; #define NAM(P0, P1, t) do { if constexpr (NA) na_mask(P0, P1, kr_lo + (t), r0, qrow, qc, c0, hi, bl); } while (0)
; #define PSM(P0, P1, MN, AL) do { if constexpr (NA) partialSM(P0, P1, m_reg, MN, AL); else { AL = 1.f; _Pragma("unroll") for (int r = 0; r < 16; ++r) P0[r] = __builtin_amdgcn_exp2f(P0[r]); } } while (0)
; #define RESCN(a) do { if constexpr (NA) RESC(a); } while (0)
; __device__ __forceinline__ void finishSM(f32x16& p0, f32x16& p1, float alpha, float& l_reg, bf16x8& pa0, bf16x8& pa1, bf16x8& pa2, bf16x8& pa3) {
;   for (int r = 0; r < 16; ++r) p1[r] = __builtin_amdgcn_exp2f(p1[r]);
;   float ps = 0; for (int r = 0; r < 16; ++r) ps += p0[r]; for (int r = 0; r < 16; ++r) ps += p1[r];
;   { auto rr = __builtin_amdgcn_permlane32_swap(__float_as_uint(ps), __float_as_uint(ps), false, false);
;     ps = __uint_as_float(rr[0]) + __uint_as_float(rr[1]); }
;   l_reg = l_reg * alpha + ps;
;     ...
;   PK4(p0, 0, pa0); PK4(p0, 8, pa1); PK4(p1, 0, pa2); PK4(p1, 8, pa3);
; template <bool NA, int ROWB>
; __device__ __forceinline__ void attn_dma(const bf16* __restrict__ Qb, const bf16* __restrict__ Kh, const bf16* __restrict__ Vh, bf16* __restrict__ Ob, int NT, char* lds, const int tid, float* __restrict__ ssb, int qrow0, int kr_lo, const float* bl) {
;     ...
;   SBAR(); qkt<false>(pB0, pB1, (const bf16*)(K_lds + bc * SHM_K), qr, nullptr, r32, hi); NAM(pB0, pB1, NT - 1);
;   finishSM(pA0, pA1, alA, l_reg, pa0, pa1, pa2, pa3); SBAR();
;   pv_d0(o, vb0 + bp * (int)SHM_V, pa0, pa1, pa2, pa3); PSM(pB0, pB1, mnB, alB); RESCN(alB);
;   finishSM(pB0, pB1, alB, l_reg, pa0, pa1, pa2, pa3); SBAR();
;   pv_d0(o, vb0 + bc * (int)SHM_V, pa0, pa1, pa2, pa3);
	v_mfma_f32_32x32x16_bf16 v[16:31], v[64:67], v[180:183], v[16:31]
	ds_read_b64_tr_b16 v[180:181], v195 offset:0x400
	ds_read_b64_tr_b16 v[182:183], v195 offset:0xc00
	v_mfma_f32_32x32x16_bf16 v[16:31], v[68:71], v[196:199], v[16:31]
	ds_read_b64_tr_b16 v[196:197], v195 offset:0x1400
	ds_read_b64_tr_b16 v[198:199], v195 offset:0x1c00
	v_mfma_f32_32x32x16_bf16 v[16:31], v[72:75], v[206:209], v[16:31]
	ds_read_b64_tr_b16 v[206:207], v195 offset:0x2400
	ds_read_b64_tr_b16 v[208:209], v195 offset:0x2c00
	v_mfma_f32_32x32x16_bf16 v[16:31], v[76:79], v[210:213], v[16:31]
	ds_read_b64_tr_b16 v[210:211], v195 offset:0x3400
	ds_read_b64_tr_b16 v[212:213], v195 offset:0x3c00
	s_waitcnt lgkmcnt(0)
	v_mfma_f32_32x32x16_bf16 v[32:47], v[64:67], v[180:183], v[32:47]
	ds_read_b64_tr_b16 v[180:181], v195 offset:0x600
	ds_read_b64_tr_b16 v[182:183], v195 offset:0xe00
	v_mfma_f32_32x32x16_bf16 v[32:47], v[68:71], v[196:199], v[32:47]
	ds_read_b64_tr_b16 v[196:197], v195 offset:0x1600
	ds_read_b64_tr_b16 v[198:199], v195 offset:0x1e00
	v_mfma_f32_32x32x16_bf16 v[32:47], v[72:75], v[206:209], v[32:47]
	ds_read_b64_tr_b16 v[206:207], v195 offset:0x2600
	ds_read_b64_tr_b16 v[208:209], v195 offset:0x2e00
	v_mfma_f32_32x32x16_bf16 v[32:47], v[76:79], v[210:213], v[32:47]
	ds_read_b64_tr_b16 v[210:211], v195 offset:0x3600
	ds_read_b64_tr_b16 v[212:213], v195 offset:0x3e00
	s_waitcnt lgkmcnt(0)
	v_mfma_f32_32x32x16_bf16 v[48:63], v[64:67], v[180:183], v[48:63]
	v_exp_f32_e32 v175, v80
	v_exp_f32_e32 v180, v81
	v_exp_f32_e32 v181, v82
	v_exp_f32_e32 v182, v83
	v_exp_f32_e32 v183, v84
	v_exp_f32_e32 v80, v90
	v_exp_f32_e32 v86, v86
	v_mfma_f32_32x32x16_bf16 v[48:63], v[68:71], v[196:199], v[48:63]
	v_exp_f32_e32 v196, v85
	v_exp_f32_e32 v87, v87
	v_exp_f32_e32 v88, v88
	v_exp_f32_e32 v89, v89
	v_exp_f32_e32 v81, v91
	v_exp_f32_e32 v82, v92
	v_exp_f32_e32 v83, v93
	v_mfma_f32_32x32x16_bf16 v[48:63], v[72:75], v[206:209], v[48:63]
	v_exp_f32_e32 v84, v94
	v_exp_f32_e32 v85, v95
	v_mfma_f32_32x32x16_bf16 v[48:63], v[76:79], v[210:213], v[48:63]
	v_mfma_f32_32x32x16_bf16 v[64:79], v[154:157], v[138:141], 0
	v_mfma_f32_32x32x16_bf16 v[64:79], v[158:161], v[142:145], v[64:79]
	v_mfma_f32_32x32x16_bf16 v[64:79], v[150:153], v[134:137], v[64:79]
	v_mfma_f32_32x32x16_bf16 v[64:79], v[96:99], v[114:117], v[64:79]
	v_mfma_f32_32x32x16_bf16 v[64:79], v[100:103], v[118:121], v[64:79]
	v_mfma_f32_32x32x16_bf16 v[64:79], v[104:107], v[122:125], v[64:79]
	v_mfma_f32_32x32x16_bf16 v[64:79], v[108:111], v[126:129], v[64:79]
	s_waitcnt lgkmcnt(0)
	v_mfma_f32_32x32x16_bf16 v[64:79], v[146:149], v[130:133], v[64:79]
	s_nop 11
	v_exp_f32_e32 v90, v64
	v_add_f32_e32 v64, 0, v175
	v_add_f32_e32 v64, v180, v64
	v_add_f32_e32 v64, v181, v64
	v_add_f32_e32 v64, v182, v64
	v_add_f32_e32 v64, v183, v64
	v_add_f32_e32 v64, v196, v64
	v_add_f32_e32 v64, v86, v64
	v_add_f32_e32 v64, v87, v64
	v_add_f32_e32 v64, v88, v64
	v_add_f32_e32 v64, v89, v64
	v_add_f32_e32 v64, v80, v64
	v_add_f32_e32 v64, v81, v64
	v_add_f32_e32 v64, v82, v64
	v_exp_f32_e32 v91, v65
	v_add_f32_e32 v64, v83, v64
	v_exp_f32_e32 v92, v66
	v_add_f32_e32 v64, v84, v64
	v_exp_f32_e32 v93, v67
	v_add_f32_e32 v64, v85, v64
	v_exp_f32_e32 v94, v68
	v_add_f32_e32 v64, v64, v90
	v_exp_f32_e32 v95, v69
	v_add_f32_e32 v64, v91, v64
	v_exp_f32_e32 v96, v70
	v_add_f32_e32 v64, v92, v64
	v_exp_f32_e32 v97, v71
	v_add_f32_e32 v64, v93, v64
	v_exp_f32_e32 v98, v72
	v_add_f32_e32 v64, v94, v64
	v_exp_f32_e32 v99, v73
	v_add_f32_e32 v64, v95, v64
	v_exp_f32_e32 v100, v74
	v_add_f32_e32 v64, v96, v64
	v_exp_f32_e32 v101, v75
	v_add_f32_e32 v64, v97, v64
	v_exp_f32_e32 v102, v76
	v_add_f32_e32 v64, v98, v64
	v_exp_f32_e32 v103, v77
	v_add_f32_e32 v64, v99, v64
	v_exp_f32_e32 v104, v78
	v_add_f32_e32 v64, v100, v64
	v_exp_f32_e32 v79, v79
	v_add_f32_e32 v64, v101, v64
	v_add_f32_e32 v64, v102, v64
	v_add_f32_e32 v64, v103, v64
	v_add_f32_e32 v64, v104, v64
	v_add_f32_e32 v177, v79, v64
	v_mov_b32_e32 v179, v177
	s_nop 1
	v_permlane32_swap_b32_e32 v177, v179
	v_cvt_pk_bf16_f32 v64, v175, v180
	v_cvt_pk_bf16_f32 v65, v181, v182
	v_cvt_pk_bf16_f32 v66, v183, v196
	v_cvt_pk_bf16_f32 v67, v86, v87
	v_cvt_pk_bf16_f32 v68, v88, v89
	v_cvt_pk_bf16_f32 v69, v80, v81
	v_cvt_pk_bf16_f32 v70, v82, v83
	v_cvt_pk_bf16_f32 v71, v84, v85
	v_cvt_pk_bf16_f32 v72, v90, v91
	v_cvt_pk_bf16_f32 v73, v92, v93
	v_cvt_pk_bf16_f32 v74, v94, v95
	v_cvt_pk_bf16_f32 v75, v96, v97
	v_cvt_pk_bf16_f32 v76, v98, v99
	v_cvt_pk_bf16_f32 v77, v100, v101
	v_cvt_pk_bf16_f32 v78, v102, v103
	v_cvt_pk_bf16_f32 v79, v104, v79
	s_nop 0
	ds_read_b64_tr_b16 v[80:81], v201 offset:0
	ds_read_b64_tr_b16 v[82:83], v201 offset:0x800
	ds_read_b64_tr_b16 v[84:85], v201 offset:0x1000
	ds_read_b64_tr_b16 v[86:87], v201 offset:0x1800
	ds_read_b64_tr_b16 v[88:89], v201 offset:0x2000
	ds_read_b64_tr_b16 v[90:91], v201 offset:0x2800
	ds_read_b64_tr_b16 v[92:93], v201 offset:0x3000
	ds_read_b64_tr_b16 v[94:95], v201 offset:0x3800
	s_waitcnt lgkmcnt(0)
	s_nop 0
	v_mfma_f32_32x32x16_bf16 v[0:15], v[64:67], v[80:83], v[0:15]
	ds_read_b64_tr_b16 v[80:81], v201 offset:0x200
	ds_read_b64_tr_b16 v[82:83], v201 offset:0xa00
	v_mfma_f32_32x32x16_bf16 v[0:15], v[68:71], v[84:87], v[0:15]
	ds_read_b64_tr_b16 v[84:85], v201 offset:0x1200
	ds_read_b64_tr_b16 v[86:87], v201 offset:0x1a00
	v_mfma_f32_32x32x16_bf16 v[0:15], v[72:75], v[88:91], v[0:15]
	ds_read_b64_tr_b16 v[88:89], v201 offset:0x2200
	ds_read_b64_tr_b16 v[90:91], v201 offset:0x2a00
	v_mfma_f32_32x32x16_bf16 v[0:15], v[76:79], v[92:95], v[0:15]
	ds_read_b64_tr_b16 v[92:93], v201 offset:0x3200
	ds_read_b64_tr_b16 v[94:95], v201 offset:0x3a00
	s_waitcnt lgkmcnt(0)
; __device__ __forceinline__ int crow(int r, int hi) { return (r & 3) + 8 * (r >> 2) + 4 * hi; }
; template <bool NA, int ROWB>
; __device__ __forceinline__ void attn_dma(const bf16* __restrict__ Qb, const bf16* __restrict__ Kh, const bf16* __restrict__ Vh, bf16* __restrict__ Ob, int NT, char* lds, const int tid, float* __restrict__ ssb, int qrow0, int kr_lo, const float* bl) {
;     ...
;   pv_d0(o, vb0 + bc * (int)SHM_V, pa0, pa1, pa2, pa3);
;   if (hi == 0) li_l[r32] = l_reg; asm volatile("s_waitcnt lgkmcnt(0)" ::: "memory");
;   float rli[16];
; #pragma unroll
;   for (int r = 0; r < 16; ++r) rli[r] = __builtin_amdgcn_rcpf(li_l[crow(r, hi)]);
;   bf16* Ow = Ob + (long)(wid * QBLK) * LDO;
;     ...
;   int tid_e = tid; asm volatile("" : "+v"(tid_e));
;   const int lane_e = tid_e & 63, wid_e = tid_e >> 6, r32_e = lane_e & 31, hi_e = lane_e >> 5;
;   char* sg = lds + 100 * 1024 + wid_e * 4096;
; #pragma unroll
;   for (int half = 0; half < 2; ++half) {
;     char* wb_e = sg + hi_e * 1024 + r32_e * 2 + hi_e * 64;
;     char* wb_o = sg + hi_e * 1024 + r32_e * 2 - hi_e * 64;
; #pragma unroll
;     for (int rr = 0; rr < 8; ++rr) { const int r = half * 8 + rr; const int rc = ((rr & 3) + 8 * (rr >> 2)) * 256;
; #pragma unroll
;       for (int d0 = 0; d0 < 4; ++d0) { const float v = o[d0][r] * rli[r]; *(bf16*)(((d0 & 1) ? wb_o : wb_e) + rc + d0 * 64) = (bf16)(cvtpk(v, v) & 0xffffu); } }
	v_mfma_f32_32x32x16_bf16 v[16:31], v[64:67], v[80:83], v[16:31]
	ds_read_b64_tr_b16 v[80:81], v201 offset:0x400
	ds_read_b64_tr_b16 v[82:83], v201 offset:0xc00
	v_mfma_f32_32x32x16_bf16 v[16:31], v[68:71], v[84:87], v[16:31]
	ds_read_b64_tr_b16 v[84:85], v201 offset:0x1400
	ds_read_b64_tr_b16 v[86:87], v201 offset:0x1c00
	v_mfma_f32_32x32x16_bf16 v[16:31], v[72:75], v[88:91], v[16:31]
	ds_read_b64_tr_b16 v[88:89], v201 offset:0x2400
	ds_read_b64_tr_b16 v[90:91], v201 offset:0x2c00
	v_mfma_f32_32x32x16_bf16 v[16:31], v[76:79], v[92:95], v[16:31]
	ds_read_b64_tr_b16 v[92:93], v201 offset:0x3400
	ds_read_b64_tr_b16 v[94:95], v201 offset:0x3c00
	s_waitcnt lgkmcnt(0)
	v_mfma_f32_32x32x16_bf16 v[32:47], v[64:67], v[80:83], v[32:47]
	ds_read_b64_tr_b16 v[80:81], v201 offset:0x600
	ds_read_b64_tr_b16 v[82:83], v201 offset:0xe00
	v_mfma_f32_32x32x16_bf16 v[32:47], v[68:71], v[84:87], v[32:47]
	ds_read_b64_tr_b16 v[84:85], v201 offset:0x1600
	ds_read_b64_tr_b16 v[86:87], v201 offset:0x1e00
	v_mfma_f32_32x32x16_bf16 v[32:47], v[72:75], v[88:91], v[32:47]
	ds_read_b64_tr_b16 v[88:89], v201 offset:0x2600
	ds_read_b64_tr_b16 v[90:91], v201 offset:0x2e00
	v_mfma_f32_32x32x16_bf16 v[32:47], v[76:79], v[92:95], v[32:47]
	ds_read_b64_tr_b16 v[92:93], v201 offset:0x3600
	ds_read_b64_tr_b16 v[94:95], v201 offset:0x3e00
	s_waitcnt lgkmcnt(0)
	v_mfma_f32_32x32x16_bf16 v[48:63], v[64:67], v[80:83], v[48:63]
	v_mfma_f32_32x32x16_bf16 v[48:63], v[68:71], v[84:87], v[48:63]
	v_mfma_f32_32x32x16_bf16 v[48:63], v[72:75], v[88:91], v[48:63]
	v_mfma_f32_32x32x16_bf16 v[48:63], v[76:79], v[92:95], v[48:63]
	s_and_saveexec_b64 s[4:5], vcc
	v_pk_add_f32 v[64:65], v[176:177], v[178:179]
	s_nop 0
	v_add_f32_e32 v64, v112, v64
	v_add_f32_e32 v64, v64, v65
	ds_write_b32 v204, v64
	s_or_b64 exec, exec, s[4:5]
	s_lshl_b64 s[0:1], s[6:7], 12
	v_readlane_b32 s4, v254, 41
	s_waitcnt lgkmcnt(0)
	v_add_u32_e32 v72, v185, v186
	s_add_u32 s4, s4, s0
	v_readlane_b32 s0, v254, 42
	ds_read_b128 v[64:67], v72
	ds_read_b128 v[68:71], v72 offset:32
	s_addc_u32 s5, s0, s1
	s_lshl_b64 s[0:1], s[6:7], 6
	v_readlane_b32 s6, v254, 32
	v_readlane_b32 s7, v254, 33
	s_add_u32 s6, s6, s0
	s_addc_u32 s7, s7, s1
	s_lshl_b32 s0, s15, 1
	s_add_u32 s0, s4, s0
	s_waitcnt lgkmcnt(1)
	v_rcp_f32_e32 v84, v64
	s_addc_u32 s1, s5, 0
	v_mov_b32_e32 v74, v200
	v_rcp_f32_e32 v85, v65
	v_rcp_f32_e32 v86, v66
	v_rcp_f32_e32 v87, v67
	s_waitcnt lgkmcnt(0)
	v_rcp_f32_e32 v88, v68
	v_rcp_f32_e32 v89, v69
	v_rcp_f32_e32 v90, v70
	v_rcp_f32_e32 v91, v71
	ds_read_b128 v[68:71], v72 offset:64
	ds_read_b128 v[64:67], v72 offset:96
	v_lshl_add_u64 v[72:73], s[0:1], 0, v[172:173]
	v_readlane_b32 s0, v254, 20
	v_ashrrev_i32_e32 v78, 6, v74
	v_bfe_u32 v76, v74, 5, 1
	v_lshlrev_b32_e32 v80, 1, v74
	v_and_b32_e32 v93, 15, v74
	v_and_b32_e32 v75, 63, v74
	v_lshl_add_u32 v77, v78, 12, s0
	v_lshlrev_b32_e32 v79, 10, v76
	v_and_b32_e32 v80, 62, v80
	v_lshlrev_b32_e32 v112, 4, v93
	v_add3_u32 v79, v77, v79, v80
	v_lshlrev_b32_e32 v80, 6, v76
	v_bfe_u32 v92, v74, 4, 2
	v_lshl_add_u64 v[82:83], v[72:73], 0, v[112:113]
	v_lshlrev_b32_e32 v72, 2, v75
	v_mul_f32_e32 v0, v0, v84
	v_lshl_add_u32 v81, v92, 8, v77
	v_xor_b32_e32 v77, 4, v72
	v_xor_b32_e32 v76, 8, v72
	v_xor_b32_e32 v75, 16, v72
	v_xor_b32_e32 v74, 32, v72
	v_lshl_or_b32 v72, v78, 5, v92
	v_cvt_pk_bf16_f32 v0, v0, v0
	v_add_u32_e32 v78, v79, v80
	ds_write_b16 v78, v0
	v_mul_f32_e32 v0, v16, v84
	v_cvt_pk_bf16_f32 v0, v0, v0
	v_sub_u32_e32 v16, v79, v80
	ds_write_b16 v16, v0 offset:64
	v_mul_f32_e32 v0, v32, v84
	v_cvt_pk_bf16_f32 v0, v0, v0
	ds_write_b16 v78, v0 offset:128
	v_mul_f32_e32 v0, v48, v84
	v_cvt_pk_bf16_f32 v0, v0, v0
	ds_write_b16 v16, v0 offset:192
	v_mul_f32_e32 v0, v1, v85
	v_cvt_pk_bf16_f32 v0, v0, v0
	ds_write_b16 v78, v0 offset:256
	v_mul_f32_e32 v0, v17, v85
	v_cvt_pk_bf16_f32 v0, v0, v0
	ds_write_b16 v16, v0 offset:320
	v_mul_f32_e32 v0, v33, v85
	v_cvt_pk_bf16_f32 v0, v0, v0
	ds_write_b16 v78, v0 offset:384
	v_mul_f32_e32 v0, v49, v85
	v_cvt_pk_bf16_f32 v0, v0, v0
	ds_write_b16 v16, v0 offset:448
	v_mul_f32_e32 v0, v2, v86
	v_cvt_pk_bf16_f32 v0, v0, v0
	ds_write_b16 v78, v0 offset:512
	v_mul_f32_e32 v0, v18, v86
	v_cvt_pk_bf16_f32 v0, v0, v0
	ds_write_b16 v16, v0 offset:576
	v_mul_f32_e32 v0, v34, v86
	v_cvt_pk_bf16_f32 v0, v0, v0
	ds_write_b16 v78, v0 offset:640
	v_mul_f32_e32 v0, v50, v86
	v_cvt_pk_bf16_f32 v0, v0, v0
	ds_write_b16 v16, v0 offset:704
	v_mul_f32_e32 v0, v3, v87
	v_cvt_pk_bf16_f32 v0, v0, v0
	ds_write_b16 v78, v0 offset:768
	v_mul_f32_e32 v0, v19, v87
	v_cvt_pk_bf16_f32 v0, v0, v0
	ds_write_b16 v16, v0 offset:832
	v_mul_f32_e32 v0, v35, v87
	v_cvt_pk_bf16_f32 v0, v0, v0
	ds_write_b16 v78, v0 offset:896
	v_mul_f32_e32 v0, v51, v87
	v_cvt_pk_bf16_f32 v0, v0, v0
	ds_write_b16 v16, v0 offset:960
	v_mul_f32_e32 v0, v4, v88
	v_cvt_pk_bf16_f32 v0, v0, v0
	ds_write_b16 v78, v0 offset:2048
	v_mul_f32_e32 v0, v20, v88
	v_cvt_pk_bf16_f32 v0, v0, v0
	ds_write_b16 v16, v0 offset:2112
	v_mul_f32_e32 v0, v36, v88
	v_cvt_pk_bf16_f32 v0, v0, v0
	ds_write_b16 v78, v0 offset:2176
	v_mul_f32_e32 v0, v52, v88
	v_cvt_pk_bf16_f32 v0, v0, v0
	ds_write_b16 v16, v0 offset:2240
	v_mul_f32_e32 v0, v5, v89
	v_cvt_pk_bf16_f32 v0, v0, v0
	ds_write_b16 v78, v0 offset:2304
	v_mul_f32_e32 v0, v21, v89
	v_cvt_pk_bf16_f32 v0, v0, v0
	ds_write_b16 v16, v0 offset:2368
	v_mul_f32_e32 v0, v37, v89
	v_cvt_pk_bf16_f32 v0, v0, v0
	ds_write_b16 v78, v0 offset:2432
	v_mul_f32_e32 v0, v53, v89
	v_cvt_pk_bf16_f32 v0, v0, v0
	ds_write_b16 v16, v0 offset:2496
	v_mul_f32_e32 v0, v6, v90
	v_cvt_pk_bf16_f32 v0, v0, v0
	ds_write_b16 v78, v0 offset:2560
	v_mul_f32_e32 v0, v22, v90
	v_cvt_pk_bf16_f32 v0, v0, v0
	ds_write_b16 v16, v0 offset:2624
	v_mul_f32_e32 v0, v38, v90
	v_cvt_pk_bf16_f32 v0, v0, v0
	ds_write_b16 v78, v0 offset:2688
	v_mul_f32_e32 v0, v54, v90
	v_cvt_pk_bf16_f32 v0, v0, v0
	ds_write_b16 v16, v0 offset:2752
	v_mul_f32_e32 v0, v7, v91
	v_cvt_pk_bf16_f32 v0, v0, v0
	ds_write_b16 v78, v0 offset:2816
	v_mul_f32_e32 v0, v23, v91
	v_cvt_pk_bf16_f32 v0, v0, v0
	ds_write_b16 v16, v0 offset:2880
	v_mul_f32_e32 v0, v39, v91
	v_cvt_pk_bf16_f32 v0, v0, v0
	ds_write_b16 v78, v0 offset:2944
	v_mul_f32_e32 v0, v55, v91
	v_cvt_pk_bf16_f32 v0, v0, v0
	ds_write_b16 v16, v0 offset:3008
	s_waitcnt lgkmcnt(0)
; __device__ __forceinline__ float xs(float v, int o, int lane) { return __int_as_float(__builtin_amdgcn_ds_bpermute((lane ^ o) << 2, __float_as_int(v))); }
; __device__ __forceinline__ void st16_wt(void* p, u32x4 v) { asm volatile("global_store_dwordx4 %0, %1, off sc0 sc1\n\ts_nop 1" :: "v"(p), "v"(v) : "memory"); }
; template <bool NA, int ROWB>
; __device__ __forceinline__ void attn_dma(const bf16* __restrict__ Qb, const bf16* __restrict__ Kh, const bf16* __restrict__ Vh, bf16* __restrict__ Ob, int NT, char* lds, const int tid, float* __restrict__ ssb, int qrow0, int kr_lo, const float* bl) {
;     ...
;     const char* rb_e = sg + (lane_e >> 4) * 256 + (lane_e & 15) * 16;
;     const char* rb_o = sg + (lane_e >> 4) * 256 + (((lane_e & 15) * 16) ^ 64);
;     bf16* gb = Ow + (long)(half * 16 + (lane_e >> 4)) * LDO + (lane_e & 15) * 8;
; #pragma unroll
;     for (int i = 0; i < 4; ++i) { const u32x4 w = *(const u32x4*)(((i & 1) ? rb_o : rb_e) + i * 1024); st16_wt(gb + (long)i * 4 * LDO, w);
;       float q = sumsq8(w); q += xs(q, 1, lane_e); q += xs(q, 2, lane_e); q += xs(q, 4, lane_e); q += xs(q, 8, lane_e);
;       if ((lane_e & 15) == 0) ssb[(size_t)(wid_e * QBLK + half * 16 + (lane_e >> 4) + 4 * i) * 16] = q; }
	v_add_u32_e32 v2, v81, v112
	ds_read_b128 v[4:7], v2
	v_lshlrev_b32_e32 v0, 12, v92
	v_mov_b32_e32 v1, v113
	v_lshl_add_u64 v[0:1], v[82:83], 0, v[0:1]
	s_mov_b64 s[0:1], 0x800
	v_lshl_add_u64 v[0:1], v[0:1], 0, s[0:1]
	s_waitcnt lgkmcnt(0)
	global_store_dwordx4 v[0:1], v[4:7], off sc0 sc1
	s_nop 1
	v_lshlrev_b32_e32 v3, 16, v4
	v_and_b32_e32 v4, 0xffff0000, v4
	v_mul_f32_e32 v4, v4, v4
	v_fmac_f32_e32 v4, v3, v3
	v_lshlrev_b32_e32 v3, 16, v5
	v_and_b32_e32 v5, 0xffff0000, v5
	v_mul_f32_e32 v5, v5, v5
	v_fmac_f32_e32 v5, v3, v3
	v_add_f32_e32 v3, v4, v5
	v_and_b32_e32 v5, 0xffff0000, v6
	v_lshlrev_b32_e32 v4, 16, v6
	v_mul_f32_e32 v5, v5, v5
	v_fmac_f32_e32 v5, v4, v4
	v_add_f32_e32 v3, v5, v3
	v_and_b32_e32 v5, 0xffff0000, v7
	v_lshlrev_b32_e32 v4, 16, v7
	v_mul_f32_e32 v5, v5, v5
	v_fmac_f32_e32 v5, v4, v4
	v_add_f32_e32 v3, v5, v3
	s_nop 1
	v_mov_b32_dpp v4, v3 quad_perm:[1,0,3,2] row_mask:0xf bank_mask:0xf
	s_lshl_b32 s4, s14, 2
	s_add_u32 s4, s6, s4
	s_addc_u32 s5, s7, 0
	s_add_u32 s6, s4, 0x25cc0020
	s_waitcnt lgkmcnt(0)
	v_add_f32_e32 v3, v3, v4
	s_nop 1
	v_mov_b32_dpp v4, v3 quad_perm:[2,3,0,1] row_mask:0xf bank_mask:0xf
	s_addc_u32 s7, s5, 0
	v_cmp_eq_u32_e64 s[4:5], 0, v93
	s_waitcnt lgkmcnt(0)
	v_add_f32_e32 v3, v3, v4
	s_nop 1
	v_mov_b32_dpp v4, v3 row_half_mirror row_mask:0xf bank_mask:0xf
	s_waitcnt lgkmcnt(0)
	v_add_f32_e32 v3, v3, v4
	s_nop 1
	v_mov_b32_dpp v4, v3 row_mirror row_mask:0xf bank_mask:0xf
	s_and_saveexec_b64 s[14:15], s[4:5]
	v_readlane_b32 s16, v254, 47
	v_readlane_b32 s28, v254, 34
	s_mov_b32 s36, s38
	v_readlane_b32 s17, v254, 48
	v_readlane_b32 s29, v254, 35
	s_cbranch_execz .LBB0_111
	v_ashrrev_i32_e32 v73, 31, v72
	v_lshlrev_b64 v[6:7], 6, v[72:73]
	v_lshl_add_u64 v[6:7], s[6:7], 0, v[6:7]
	s_waitcnt lgkmcnt(0)
	v_add_f32_e32 v3, v3, v4
	global_store_dword v[6:7], v3, off
.LBB0_111:
	s_or_b64 exec, exec, s[14:15]
	v_xor_b32_e32 v3, 64, v112
	v_add_u32_e32 v3, v81, v3
	s_waitcnt lgkmcnt(0)
	ds_read_b128 v[4:7], v3 offset:1024
	s_mov_b64 s[0:1], 0x4000
	v_lshl_add_u64 v[16:17], v[0:1], 0, s[0:1]
	s_waitcnt lgkmcnt(0)
	global_store_dwordx4 v[16:17], v[4:7], off sc0 sc1
	s_nop 1
	v_lshlrev_b32_e32 v16, 16, v4
	v_and_b32_e32 v4, 0xffff0000, v4
	v_mul_f32_e32 v4, v4, v4
	v_fmac_f32_e32 v4, v16, v16
	v_lshlrev_b32_e32 v16, 16, v5
	v_and_b32_e32 v5, 0xffff0000, v5
	v_mul_f32_e32 v5, v5, v5
	v_fmac_f32_e32 v5, v16, v16
	v_add_f32_e32 v4, v4, v5
	v_lshlrev_b32_e32 v5, 16, v6
	v_and_b32_e32 v6, 0xffff0000, v6
	v_mul_f32_e32 v6, v6, v6
	v_fmac_f32_e32 v6, v5, v5
	v_add_f32_e32 v4, v6, v4
	v_and_b32_e32 v6, 0xffff0000, v7
	v_lshlrev_b32_e32 v5, 16, v7
	v_mul_f32_e32 v6, v6, v6
	v_fmac_f32_e32 v6, v5, v5
	v_add_f32_e32 v4, v6, v4
	s_nop 1
	v_mov_b32_dpp v5, v4 quad_perm:[1,0,3,2] row_mask:0xf bank_mask:0xf
	s_waitcnt lgkmcnt(0)
	v_add_f32_e32 v4, v4, v5
	s_nop 1
	v_mov_b32_dpp v5, v4 quad_perm:[2,3,0,1] row_mask:0xf bank_mask:0xf
	s_waitcnt lgkmcnt(0)
	v_add_f32_e32 v4, v4, v5
	s_nop 1
	v_mov_b32_dpp v5, v4 row_half_mirror row_mask:0xf bank_mask:0xf
	s_waitcnt lgkmcnt(0)
	v_add_f32_e32 v4, v4, v5
	s_nop 1
	v_mov_b32_dpp v5, v4 row_mirror row_mask:0xf bank_mask:0xf
	s_and_saveexec_b64 s[14:15], s[4:5]
	s_cbranch_execz .LBB0_113
	v_or_b32_e32 v6, 4, v72
	v_ashrrev_i32_e32 v7, 31, v6
	v_lshlrev_b64 v[6:7], 6, v[6:7]
	v_lshl_add_u64 v[6:7], s[6:7], 0, v[6:7]
	s_waitcnt lgkmcnt(0)
	v_add_f32_e32 v4, v4, v5
	global_store_dword v[6:7], v4, off
.LBB0_113:
	s_or_b64 exec, exec, s[14:15]
	s_waitcnt lgkmcnt(0)
	ds_read_b128 v[4:7], v2 offset:2048
	s_mov_b64 s[0:1], 0x8000
	v_lshl_add_u64 v[16:17], v[0:1], 0, s[0:1]
	s_waitcnt lgkmcnt(0)
	global_store_dwordx4 v[16:17], v[4:7], off sc0 sc1
	s_nop 1
	v_lshlrev_b32_e32 v16, 16, v4
	v_and_b32_e32 v4, 0xffff0000, v4
	v_mul_f32_e32 v4, v4, v4
	v_fmac_f32_e32 v4, v16, v16
	v_lshlrev_b32_e32 v16, 16, v5
	v_and_b32_e32 v5, 0xffff0000, v5
	v_mul_f32_e32 v5, v5, v5
	v_fmac_f32_e32 v5, v16, v16
	v_add_f32_e32 v4, v4, v5
	v_lshlrev_b32_e32 v5, 16, v6
	v_and_b32_e32 v6, 0xffff0000, v6
	v_mul_f32_e32 v6, v6, v6
	v_fmac_f32_e32 v6, v5, v5
	v_add_f32_e32 v4, v6, v4
	v_and_b32_e32 v6, 0xffff0000, v7
	v_lshlrev_b32_e32 v5, 16, v7
	v_mul_f32_e32 v6, v6, v6
	v_fmac_f32_e32 v6, v5, v5
	v_add_f32_e32 v4, v6, v4
	s_nop 1
	v_mov_b32_dpp v5, v4 quad_perm:[1,0,3,2] row_mask:0xf bank_mask:0xf
	s_waitcnt lgkmcnt(0)
	v_add_f32_e32 v4, v4, v5
	s_nop 1
	v_mov_b32_dpp v5, v4 quad_perm:[2,3,0,1] row_mask:0xf bank_mask:0xf
	s_waitcnt lgkmcnt(0)
	v_add_f32_e32 v4, v4, v5
	s_nop 1
	v_mov_b32_dpp v5, v4 row_half_mirror row_mask:0xf bank_mask:0xf
	s_waitcnt lgkmcnt(0)
	v_add_f32_e32 v4, v4, v5
	s_nop 1
	v_mov_b32_dpp v5, v4 row_mirror row_mask:0xf bank_mask:0xf
	s_and_saveexec_b64 s[14:15], s[4:5]
	s_cbranch_execz .LBB0_115
	v_or_b32_e32 v6, 8, v72
	v_ashrrev_i32_e32 v7, 31, v6
	v_lshlrev_b64 v[6:7], 6, v[6:7]
	v_lshl_add_u64 v[6:7], s[6:7], 0, v[6:7]
	s_waitcnt lgkmcnt(0)
	v_add_f32_e32 v4, v4, v5
	global_store_dword v[6:7], v4, off
; __device__ __forceinline__ float xs(float v, int o, int lane) { return __int_as_float(__builtin_amdgcn_ds_bpermute((lane ^ o) << 2, __float_as_int(v))); }
; __device__ __forceinline__ void st16_wt(void* p, u32x4 v) { asm volatile("global_store_dwordx4 %0, %1, off sc0 sc1\n\ts_nop 1" :: "v"(p), "v"(v) : "memory"); }
; template <bool NA, int ROWB>
; __device__ __forceinline__ void attn_dma(const bf16* __restrict__ Qb, const bf16* __restrict__ Kh, const bf16* __restrict__ Vh, bf16* __restrict__ Ob, int NT, char* lds, const int tid, float* __restrict__ ssb, int qrow0, int kr_lo, const float* bl) {
;     ...
;   for (int half = 0; half < 2; ++half) {
;     char* wb_e = sg + hi_e * 1024 + r32_e * 2 + hi_e * 64;
;     char* wb_o = sg + hi_e * 1024 + r32_e * 2 - hi_e * 64;
; #pragma unroll
;     for (int rr = 0; rr < 8; ++rr) { const int r = half * 8 + rr; const int rc = ((rr & 3) + 8 * (rr >> 2)) * 256;
; #pragma unroll
;       for (int d0 = 0; d0 < 4; ++d0) { const float v = o[d0][r] * rli[r]; *(bf16*)(((d0 & 1) ? wb_o : wb_e) + rc + d0 * 64) = (bf16)(cvtpk(v, v) & 0xffffu); } }
;     asm volatile("s_waitcnt lgkmcnt(0)" ::: "memory");
;     const char* rb_e = sg + (lane_e >> 4) * 256 + (lane_e & 15) * 16;
;     const char* rb_o = sg + (lane_e >> 4) * 256 + (((lane_e & 15) * 16) ^ 64);
;     bf16* gb = Ow + (long)(half * 16 + (lane_e >> 4)) * LDO + (lane_e & 15) * 8;
; #pragma unroll
;     for (int i = 0; i < 4; ++i) { const u32x4 w = *(const u32x4*)(((i & 1) ? rb_o : rb_e) + i * 1024); st16_wt(gb + (long)i * 4 * LDO, w);
;       float q = sumsq8(w); q += xs(q, 1, lane_e); q += xs(q, 2, lane_e); q += xs(q, 4, lane_e); q += xs(q, 8, lane_e);
;       if ((lane_e & 15) == 0) ssb[(size_t)(wid_e * QBLK + half * 16 + (lane_e >> 4) + 4 * i) * 16] = q; }
.LBB0_115:
	s_or_b64 exec, exec, s[14:15]
	s_waitcnt lgkmcnt(0)
	ds_read_b128 v[4:7], v3 offset:3072
	s_mov_b64 s[0:1], 0xc000
	v_lshl_add_u64 v[16:17], v[0:1], 0, s[0:1]
	s_waitcnt lgkmcnt(0)
	global_store_dwordx4 v[16:17], v[4:7], off sc0 sc1
	s_nop 1
	v_lshlrev_b32_e32 v16, 16, v4
	v_and_b32_e32 v4, 0xffff0000, v4
	v_mul_f32_e32 v4, v4, v4
	v_fmac_f32_e32 v4, v16, v16
	v_lshlrev_b32_e32 v16, 16, v5
	v_and_b32_e32 v5, 0xffff0000, v5
	v_mul_f32_e32 v5, v5, v5
	v_fmac_f32_e32 v5, v16, v16
	v_add_f32_e32 v4, v4, v5
	v_lshlrev_b32_e32 v5, 16, v6
	v_and_b32_e32 v6, 0xffff0000, v6
	v_mul_f32_e32 v6, v6, v6
	v_fmac_f32_e32 v6, v5, v5
	v_add_f32_e32 v4, v6, v4
	v_and_b32_e32 v6, 0xffff0000, v7
	v_lshlrev_b32_e32 v5, 16, v7
	v_mul_f32_e32 v6, v6, v6
	v_fmac_f32_e32 v6, v5, v5
	v_add_f32_e32 v4, v6, v4
	s_nop 1
	v_mov_b32_dpp v5, v4 quad_perm:[1,0,3,2] row_mask:0xf bank_mask:0xf
	s_waitcnt lgkmcnt(0)
	v_add_f32_e32 v4, v4, v5
	s_nop 1
	v_mov_b32_dpp v5, v4 quad_perm:[2,3,0,1] row_mask:0xf bank_mask:0xf
	s_waitcnt lgkmcnt(0)
	v_add_f32_e32 v4, v4, v5
	s_nop 1
	v_mov_b32_dpp v5, v4 row_half_mirror row_mask:0xf bank_mask:0xf
	s_waitcnt lgkmcnt(0)
	v_add_f32_e32 v4, v4, v5
	s_nop 1
	v_mov_b32_dpp v5, v4 row_mirror row_mask:0xf bank_mask:0xf
	s_and_saveexec_b64 s[14:15], s[4:5]
	s_cbranch_execz .LBB0_117
	v_or_b32_e32 v6, 12, v72
	v_ashrrev_i32_e32 v7, 31, v6
	v_lshlrev_b64 v[6:7], 6, v[6:7]
	v_lshl_add_u64 v[6:7], s[6:7], 0, v[6:7]
	s_waitcnt lgkmcnt(0)
	v_add_f32_e32 v4, v4, v5
	global_store_dword v[6:7], v4, off
.LBB0_117:
	s_or_b64 exec, exec, s[14:15]
	s_waitcnt lgkmcnt(0)
	v_rcp_f32_e32 v5, v68
	s_waitcnt lgkmcnt(0)
	v_sub_u32_e32 v4, 0, v80
	v_rcp_f32_e32 v6, v69
	v_mul_f32_e32 v8, v8, v5
	v_cvt_pk_bf16_f32 v8, v8, v8
	ds_write_b16 v78, v8
	v_mul_f32_e32 v8, v24, v5
	v_cvt_pk_bf16_f32 v8, v8, v8
	v_add_u32_e32 v4, v79, v4
	ds_write_b16 v4, v8 offset:64
	v_mul_f32_e32 v8, v40, v5
	v_mul_f32_e32 v5, v56, v5
	v_cvt_pk_bf16_f32 v8, v8, v8
	ds_write_b16 v78, v8 offset:128
	v_cvt_pk_bf16_f32 v5, v5, v5
	ds_write_b16 v4, v5 offset:192
	v_mul_f32_e32 v5, v9, v6
	v_cvt_pk_bf16_f32 v5, v5, v5
	ds_write_b16 v78, v5 offset:256
	v_mul_f32_e32 v5, v25, v6
	v_cvt_pk_bf16_f32 v5, v5, v5
	v_rcp_f32_e32 v7, v70
	ds_write_b16 v4, v5 offset:320
	v_mul_f32_e32 v5, v41, v6
	v_cvt_pk_bf16_f32 v5, v5, v5
	ds_write_b16 v78, v5 offset:384
	v_mul_f32_e32 v5, v57, v6
	v_cvt_pk_bf16_f32 v5, v5, v5
	ds_write_b16 v4, v5 offset:448
	v_mul_f32_e32 v5, v10, v7
	v_cvt_pk_bf16_f32 v5, v5, v5
	ds_write_b16 v78, v5 offset:512
	v_mul_f32_e32 v5, v26, v7
	v_cvt_pk_bf16_f32 v5, v5, v5
	v_rcp_f32_e32 v16, v71
	ds_write_b16 v4, v5 offset:576
	v_mul_f32_e32 v5, v42, v7
	v_cvt_pk_bf16_f32 v5, v5, v5
	ds_write_b16 v78, v5 offset:640
	v_mul_f32_e32 v5, v58, v7
	v_cvt_pk_bf16_f32 v5, v5, v5
	ds_write_b16 v4, v5 offset:704
	v_mul_f32_e32 v5, v11, v16
	v_cvt_pk_bf16_f32 v5, v5, v5
	ds_write_b16 v78, v5 offset:768
	v_mul_f32_e32 v5, v27, v16
	v_cvt_pk_bf16_f32 v5, v5, v5
	v_rcp_f32_e32 v17, v64
	ds_write_b16 v4, v5 offset:832
	v_mul_f32_e32 v5, v43, v16
	v_cvt_pk_bf16_f32 v5, v5, v5
	ds_write_b16 v78, v5 offset:896
	v_mul_f32_e32 v5, v59, v16
	v_cvt_pk_bf16_f32 v5, v5, v5
	ds_write_b16 v4, v5 offset:960
	v_mul_f32_e32 v5, v12, v17
	v_cvt_pk_bf16_f32 v5, v5, v5
	ds_write_b16 v78, v5 offset:2048
	v_mul_f32_e32 v5, v28, v17
	v_cvt_pk_bf16_f32 v5, v5, v5
	v_rcp_f32_e32 v18, v65
	ds_write_b16 v4, v5 offset:2112
	v_mul_f32_e32 v5, v44, v17
	v_cvt_pk_bf16_f32 v5, v5, v5
	ds_write_b16 v78, v5 offset:2176
	v_mul_f32_e32 v5, v60, v17
	v_cvt_pk_bf16_f32 v5, v5, v5
	ds_write_b16 v4, v5 offset:2240
	v_mul_f32_e32 v5, v13, v18
	v_cvt_pk_bf16_f32 v5, v5, v5
	ds_write_b16 v78, v5 offset:2304
	v_mul_f32_e32 v5, v29, v18
	v_cvt_pk_bf16_f32 v5, v5, v5
	v_rcp_f32_e32 v19, v66
	ds_write_b16 v4, v5 offset:2368
	v_mul_f32_e32 v5, v45, v18
	v_cvt_pk_bf16_f32 v5, v5, v5
	ds_write_b16 v78, v5 offset:2432
	v_mul_f32_e32 v5, v61, v18
	v_cvt_pk_bf16_f32 v5, v5, v5
	ds_write_b16 v4, v5 offset:2496
	v_mul_f32_e32 v5, v14, v19
	v_cvt_pk_bf16_f32 v5, v5, v5
	ds_write_b16 v78, v5 offset:2560
	v_mul_f32_e32 v5, v30, v19
	v_cvt_pk_bf16_f32 v5, v5, v5
	v_rcp_f32_e32 v20, v67
	ds_write_b16 v4, v5 offset:2624
	v_mul_f32_e32 v5, v46, v19
	v_cvt_pk_bf16_f32 v5, v5, v5
	ds_write_b16 v78, v5 offset:2688
	v_mul_f32_e32 v5, v62, v19
	v_cvt_pk_bf16_f32 v5, v5, v5
	ds_write_b16 v4, v5 offset:2752
	v_mul_f32_e32 v5, v15, v20
	v_cvt_pk_bf16_f32 v5, v5, v5
	ds_write_b16 v78, v5 offset:2816
	v_mul_f32_e32 v5, v31, v20
	v_cvt_pk_bf16_f32 v5, v5, v5
	ds_write_b16 v4, v5 offset:2880
	v_mul_f32_e32 v5, v47, v20
	v_cvt_pk_bf16_f32 v5, v5, v5
	ds_write_b16 v78, v5 offset:2944
	v_mul_f32_e32 v5, v63, v20
	v_cvt_pk_bf16_f32 v5, v5, v5
	ds_write_b16 v4, v5 offset:3008
	s_waitcnt lgkmcnt(0)
	ds_read_b128 v[6:9], v2
	s_mov_b64 s[0:1], 0x10000
	s_waitcnt lgkmcnt(0)
	v_and_b32_e32 v5, 0xffff0000, v6
	v_lshlrev_b32_e32 v4, 16, v6
	v_mul_f32_e32 v5, v5, v5
	v_and_b32_e32 v10, 0xffff0000, v7
	v_fmac_f32_e32 v5, v4, v4
	v_lshlrev_b32_e32 v4, 16, v7
	v_mul_f32_e32 v10, v10, v10
	v_fmac_f32_e32 v10, v4, v4
	v_add_f32_e32 v4, v5, v10
	v_and_b32_e32 v10, 0xffff0000, v8
	v_lshlrev_b32_e32 v5, 16, v8
	v_mul_f32_e32 v10, v10, v10
	v_fmac_f32_e32 v10, v5, v5
	v_add_f32_e32 v4, v10, v4
	v_and_b32_e32 v10, 0xffff0000, v9
	v_lshlrev_b32_e32 v5, 16, v9
	v_mul_f32_e32 v10, v10, v10
	v_fmac_f32_e32 v10, v5, v5
	v_add_f32_e32 v4, v10, v4
	s_nop 1
	v_mov_b32_dpp v5, v4 quad_perm:[1,0,3,2] row_mask:0xf bank_mask:0xf
	v_lshl_add_u64 v[10:11], v[0:1], 0, s[0:1]
	global_store_dwordx4 v[10:11], v[6:9], off sc0 sc1
	s_nop 1
	s_waitcnt lgkmcnt(0)
	v_add_f32_e32 v4, v4, v5
	s_nop 1
	v_mov_b32_dpp v5, v4 quad_perm:[2,3,0,1] row_mask:0xf bank_mask:0xf
	s_waitcnt lgkmcnt(0)
	v_add_f32_e32 v4, v4, v5
	s_nop 1
	v_mov_b32_dpp v5, v4 row_half_mirror row_mask:0xf bank_mask:0xf
	s_waitcnt lgkmcnt(0)
	v_add_f32_e32 v4, v4, v5
	s_nop 1
	v_mov_b32_dpp v5, v4 row_mirror row_mask:0xf bank_mask:0xf
	s_and_saveexec_b64 s[14:15], s[4:5]
	s_cbranch_execz .LBB0_119
	v_or_b32_e32 v6, 16, v72
	v_ashrrev_i32_e32 v7, 31, v6
	v_lshlrev_b64 v[6:7], 6, v[6:7]
	v_lshl_add_u64 v[6:7], s[6:7], 0, v[6:7]
	s_waitcnt lgkmcnt(0)
	v_add_f32_e32 v4, v4, v5
	global_store_dword v[6:7], v4, off
; __device__ __forceinline__ float xs(float v, int o, int lane) { return __int_as_float(__builtin_amdgcn_ds_bpermute((lane ^ o) << 2, __float_as_int(v))); }
; __device__ __forceinline__ void st16_wt(void* p, u32x4 v) { asm volatile("global_store_dwordx4 %0, %1, off sc0 sc1\n\ts_nop 1" :: "v"(p), "v"(v) : "memory"); }
; template <bool NA, int ROWB>
; __device__ __forceinline__ void attn_dma(const bf16* __restrict__ Qb, const bf16* __restrict__ Kh, const bf16* __restrict__ Vh, bf16* __restrict__ Ob, int NT, char* lds, const int tid, float* __restrict__ ssb, int qrow0, int kr_lo, const float* bl) {
;     ...
;     const char* rb_e = sg + (lane_e >> 4) * 256 + (lane_e & 15) * 16;
;     const char* rb_o = sg + (lane_e >> 4) * 256 + (((lane_e & 15) * 16) ^ 64);
;     bf16* gb = Ow + (long)(half * 16 + (lane_e >> 4)) * LDO + (lane_e & 15) * 8;
; #pragma unroll
;     for (int i = 0; i < 4; ++i) { const u32x4 w = *(const u32x4*)(((i & 1) ? rb_o : rb_e) + i * 1024); st16_wt(gb + (long)i * 4 * LDO, w);
;       float q = sumsq8(w); q += xs(q, 1, lane_e); q += xs(q, 2, lane_e); q += xs(q, 4, lane_e); q += xs(q, 8, lane_e);
;       if ((lane_e & 15) == 0) ssb[(size_t)(wid_e * QBLK + half * 16 + (lane_e >> 4) + 4 * i) * 16] = q; }
.LBB0_119:
	s_or_b64 exec, exec, s[14:15]
	s_waitcnt lgkmcnt(0)
	ds_read_b128 v[4:7], v3 offset:1024
	s_mov_b64 s[0:1], 0x14000
	v_lshl_add_u64 v[8:9], v[0:1], 0, s[0:1]
	s_waitcnt lgkmcnt(0)
	global_store_dwordx4 v[8:9], v[4:7], off sc0 sc1
	s_nop 1
	v_lshlrev_b32_e32 v8, 16, v4
	v_and_b32_e32 v4, 0xffff0000, v4
	v_mul_f32_e32 v4, v4, v4
	v_fmac_f32_e32 v4, v8, v8
	v_lshlrev_b32_e32 v8, 16, v5
	v_and_b32_e32 v5, 0xffff0000, v5
	v_mul_f32_e32 v5, v5, v5
	v_fmac_f32_e32 v5, v8, v8
	v_add_f32_e32 v4, v4, v5
	v_lshlrev_b32_e32 v5, 16, v6
	v_and_b32_e32 v6, 0xffff0000, v6
	v_mul_f32_e32 v6, v6, v6
	v_fmac_f32_e32 v6, v5, v5
	v_add_f32_e32 v4, v6, v4
	v_and_b32_e32 v6, 0xffff0000, v7
	v_lshlrev_b32_e32 v5, 16, v7
	v_mul_f32_e32 v6, v6, v6
	v_fmac_f32_e32 v6, v5, v5
	v_add_f32_e32 v4, v6, v4
	s_nop 1
	v_mov_b32_dpp v5, v4 quad_perm:[1,0,3,2] row_mask:0xf bank_mask:0xf
	s_waitcnt lgkmcnt(0)
	v_add_f32_e32 v4, v4, v5
	s_nop 1
	v_mov_b32_dpp v5, v4 quad_perm:[2,3,0,1] row_mask:0xf bank_mask:0xf
	s_waitcnt lgkmcnt(0)
	v_add_f32_e32 v4, v4, v5
	s_nop 1
	v_mov_b32_dpp v5, v4 row_half_mirror row_mask:0xf bank_mask:0xf
	s_waitcnt lgkmcnt(0)
	v_add_f32_e32 v4, v4, v5
	s_nop 1
	v_mov_b32_dpp v5, v4 row_mirror row_mask:0xf bank_mask:0xf
	s_and_saveexec_b64 s[14:15], s[4:5]
	s_cbranch_execz .LBB0_121
	v_or_b32_e32 v6, 20, v72
	v_ashrrev_i32_e32 v7, 31, v6
	v_lshlrev_b64 v[6:7], 6, v[6:7]
	v_lshl_add_u64 v[6:7], s[6:7], 0, v[6:7]
	s_waitcnt lgkmcnt(0)
	v_add_f32_e32 v4, v4, v5
	global_store_dword v[6:7], v4, off
.LBB0_121:
	s_or_b64 exec, exec, s[14:15]
	s_waitcnt lgkmcnt(0)
	ds_read_b128 v[4:7], v2 offset:2048
	s_mov_b64 s[0:1], 0x18000
	v_lshl_add_u64 v[8:9], v[0:1], 0, s[0:1]
	s_waitcnt lgkmcnt(0)
	global_store_dwordx4 v[8:9], v[4:7], off sc0 sc1
	s_nop 1
	v_lshlrev_b32_e32 v2, 16, v4
	v_and_b32_e32 v4, 0xffff0000, v4
	v_mul_f32_e32 v4, v4, v4
	v_fmac_f32_e32 v4, v2, v2
	v_lshlrev_b32_e32 v2, 16, v5
	v_and_b32_e32 v5, 0xffff0000, v5
	v_mul_f32_e32 v5, v5, v5
	v_fmac_f32_e32 v5, v2, v2
	v_add_f32_e32 v2, v4, v5
	v_and_b32_e32 v5, 0xffff0000, v6
	v_lshlrev_b32_e32 v4, 16, v6
	v_mul_f32_e32 v5, v5, v5
	v_fmac_f32_e32 v5, v4, v4
	v_add_f32_e32 v2, v5, v2
	v_and_b32_e32 v5, 0xffff0000, v7
	v_lshlrev_b32_e32 v4, 16, v7
	v_mul_f32_e32 v5, v5, v5
	v_fmac_f32_e32 v5, v4, v4
	v_add_f32_e32 v2, v5, v2
	s_nop 1
	v_mov_b32_dpp v4, v2 quad_perm:[1,0,3,2] row_mask:0xf bank_mask:0xf
	s_waitcnt lgkmcnt(0)
	v_add_f32_e32 v2, v2, v4
	s_nop 1
	v_mov_b32_dpp v4, v2 quad_perm:[2,3,0,1] row_mask:0xf bank_mask:0xf
	s_waitcnt lgkmcnt(0)
	v_add_f32_e32 v2, v2, v4
	s_nop 1
	v_mov_b32_dpp v4, v2 row_half_mirror row_mask:0xf bank_mask:0xf
	s_waitcnt lgkmcnt(0)
	v_add_f32_e32 v2, v2, v4
	s_nop 1
	v_mov_b32_dpp v4, v2 row_mirror row_mask:0xf bank_mask:0xf
	s_and_saveexec_b64 s[14:15], s[4:5]
	s_cbranch_execz .LBB0_123
	v_or_b32_e32 v6, 24, v72
	v_ashrrev_i32_e32 v7, 31, v6
	v_lshlrev_b64 v[6:7], 6, v[6:7]
	v_lshl_add_u64 v[6:7], s[6:7], 0, v[6:7]
	s_waitcnt lgkmcnt(0)
	v_add_f32_e32 v2, v2, v4
	global_store_dword v[6:7], v2, off
.LBB0_123:
	s_or_b64 exec, exec, s[14:15]
	s_waitcnt lgkmcnt(0)
	ds_read_b128 v[2:5], v3 offset:3072
	s_mov_b64 s[0:1], 0x1c000
	v_lshl_add_u64 v[0:1], v[0:1], 0, s[0:1]
	s_waitcnt lgkmcnt(0)
	global_store_dwordx4 v[0:1], v[2:5], off sc0 sc1
	s_nop 1
	v_and_b32_e32 v1, 0xffff0000, v2
	v_lshlrev_b32_e32 v0, 16, v2
	v_mul_f32_e32 v1, v1, v1
	v_and_b32_e32 v2, 0xffff0000, v3
	v_fmac_f32_e32 v1, v0, v0
	v_lshlrev_b32_e32 v0, 16, v3
	v_mul_f32_e32 v2, v2, v2
	v_fmac_f32_e32 v2, v0, v0
	v_add_f32_e32 v0, v1, v2
	v_and_b32_e32 v2, 0xffff0000, v4
	v_lshlrev_b32_e32 v1, 16, v4
	v_mul_f32_e32 v2, v2, v2
	v_fmac_f32_e32 v2, v1, v1
	v_add_f32_e32 v0, v2, v0
	v_and_b32_e32 v2, 0xffff0000, v5
	v_lshlrev_b32_e32 v1, 16, v5
	v_mul_f32_e32 v2, v2, v2
	v_fmac_f32_e32 v2, v1, v1
	v_add_f32_e32 v0, v2, v0
	s_nop 1
	v_mov_b32_dpp v1, v0 quad_perm:[1,0,3,2] row_mask:0xf bank_mask:0xf
	s_waitcnt lgkmcnt(0)
	v_add_f32_e32 v0, v0, v1
	s_nop 1
	v_mov_b32_dpp v1, v0 quad_perm:[2,3,0,1] row_mask:0xf bank_mask:0xf
	s_waitcnt lgkmcnt(0)
	v_add_f32_e32 v0, v0, v1
	s_nop 1
	v_mov_b32_dpp v1, v0 row_half_mirror row_mask:0xf bank_mask:0xf
	s_waitcnt lgkmcnt(0)
	v_add_f32_e32 v0, v0, v1
	s_nop 1
	v_mov_b32_dpp v1, v0 row_mirror row_mask:0xf bank_mask:0xf
	s_and_saveexec_b64 s[14:15], s[4:5]
	s_cbranch_execz .LBB0_104
	v_or_b32_e32 v2, 28, v72
	v_ashrrev_i32_e32 v3, 31, v2
	v_lshlrev_b64 v[2:3], 6, v[2:3]
	v_lshl_add_u64 v[2:3], s[6:7], 0, v[2:3]
	s_waitcnt lgkmcnt(0)
	v_add_f32_e32 v0, v0, v1
	global_store_dword v[2:3], v0, off
	s_branch .LBB0_104

; #define SBAR() __builtin_amdgcn_sched_barrier(0)
; __device__ __forceinline__ void finishSM(f32x16& p0, f32x16& p1, float alpha, float& l_reg, bf16x8& pa0, bf16x8& pa1, bf16x8& pa2, bf16x8& pa3) {
;   for (int r = 0; r < 16; ++r) p1[r] = __builtin_amdgcn_exp2f(p1[r]);
;   float ps = 0; for (int r = 0; r < 16; ++r) ps += p0[r]; for (int r = 0; r < 16; ++r) ps += p1[r];
;   { auto rr = __builtin_amdgcn_permlane32_swap(__float_as_uint(ps), __float_as_uint(ps), false, false);
;     ps = __uint_as_float(rr[0]) + __uint_as_float(rr[1]); }
;   l_reg = l_reg * alpha + ps;
;     ...
;   PK4(p0, 0, pa0); PK4(p0, 8, pa1); PK4(p1, 0, pa2); PK4(p1, 8, pa3);
; template <bool NA, int ROWB>
; __device__ __forceinline__ void attn_dma(const bf16* __restrict__ Qb, const bf16* __restrict__ Kh, const bf16* __restrict__ Vh, bf16* __restrict__ Ob, int NT, char* lds, const int tid, float* __restrict__ ssb, int qrow0, int kr_lo, const float* bl) {
;     ...
;   finishSM(pB0, pB1, alB, l_reg, pa0, pa1, pa2, pa3); SBAR();
;   pv_d0(o, vb0 + bc * (int)SHM_V, pa0, pa1, pa2, pa3);
.LBB0_303:
	v_cndmask_b32_e64 v67, v67, v192, s[18:19]
	v_mul_f32_e32 v67, 0xbe0293ee, v67
	v_fmamk_f32 v68, v97, 0x3e0293ee, v67
	v_fmamk_f32 v69, v96, 0x3e0293ee, v67
	v_fmamk_f32 v70, v99, 0x3e0293ee, v67
	v_exp_f32_e32 v99, v68
	v_exp_f32_e32 v69, v69
	v_fmamk_f32 v71, v98, 0x3e0293ee, v67
	v_fmamk_f32 v73, v100, 0x3e0293ee, v67
	v_exp_f32_e32 v100, v70
	v_fmamk_f32 v72, v101, 0x3e0293ee, v67
	v_fmamk_f32 v74, v103, 0x3e0293ee, v67
	v_fmamk_f32 v75, v102, 0x3e0293ee, v67
	v_fmamk_f32 v76, v105, 0x3e0293ee, v67
	v_fmamk_f32 v77, v104, 0x3e0293ee, v67
	v_fmamk_f32 v78, v107, 0x3e0293ee, v67
	v_fmamk_f32 v79, v106, 0x3e0293ee, v67
	v_fmamk_f32 v80, v109, 0x3e0293ee, v67
	v_fmamk_f32 v81, v108, 0x3e0293ee, v67
	v_fmamk_f32 v82, v116, 0x3e0293ee, v67
	v_fmamk_f32 v83, v115, 0x3e0293ee, v67
	v_fmamk_f32 v84, v128, 0x3e0293ee, v67
	v_fmamk_f32 v85, v127, 0x3e0293ee, v67
	v_fmamk_f32 v86, v126, 0x3e0293ee, v67
	v_fmamk_f32 v87, v125, 0x3e0293ee, v67
	v_fmamk_f32 v88, v124, 0x3e0293ee, v67
	v_fmamk_f32 v89, v123, 0x3e0293ee, v67
	v_fmamk_f32 v90, v122, 0x3e0293ee, v67
	v_fmamk_f32 v91, v121, 0x3e0293ee, v67
	v_fmamk_f32 v92, v120, 0x3e0293ee, v67
	v_fmamk_f32 v93, v119, 0x3e0293ee, v67
	v_fmamk_f32 v94, v118, 0x3e0293ee, v67
	v_fmamk_f32 v95, v117, 0x3e0293ee, v67
	v_fmamk_f32 v96, v114, 0x3e0293ee, v67
	v_fmamk_f32 v97, v111, 0x3e0293ee, v67
	v_fmamk_f32 v98, v110, 0x3e0293ee, v67
	v_fmac_f32_e32 v67, 0x3e0293ee, v129
	v_exp_f32_e32 v71, v71
	v_exp_f32_e32 v72, v72
	v_exp_f32_e32 v101, v67
	v_add_f32_e32 v67, 0, v99
	v_exp_f32_e32 v73, v73
	v_add_f32_e32 v67, v69, v67
	v_exp_f32_e32 v74, v74
	v_add_f32_e32 v67, v100, v67
	v_exp_f32_e32 v75, v75
	v_add_f32_e32 v67, v71, v67
	v_exp_f32_e32 v76, v76
	v_add_f32_e32 v67, v72, v67
	v_exp_f32_e32 v77, v77
	v_add_f32_e32 v67, v73, v67
	v_exp_f32_e32 v78, v78
	v_add_f32_e32 v67, v74, v67
	v_exp_f32_e32 v79, v79
	v_add_f32_e32 v67, v75, v67
	v_exp_f32_e32 v80, v80
	v_add_f32_e32 v67, v76, v67
	v_exp_f32_e32 v81, v81
	v_add_f32_e32 v67, v77, v67
	v_exp_f32_e32 v82, v82
	v_add_f32_e32 v67, v78, v67
	v_exp_f32_e32 v83, v83
	v_add_f32_e32 v67, v79, v67
	v_exp_f32_e32 v84, v84
	v_add_f32_e32 v67, v80, v67
	v_exp_f32_e32 v85, v85
	v_add_f32_e32 v67, v81, v67
	v_exp_f32_e32 v86, v86
	v_add_f32_e32 v67, v82, v67
	v_exp_f32_e32 v87, v87
	v_add_f32_e32 v67, v83, v67
	v_exp_f32_e32 v88, v88
	v_add_f32_e32 v67, v84, v67
	v_exp_f32_e32 v89, v89
	v_add_f32_e32 v67, v85, v67
	v_exp_f32_e32 v90, v90
	v_add_f32_e32 v67, v86, v67
	v_exp_f32_e32 v91, v91
	v_add_f32_e32 v67, v87, v67
	v_exp_f32_e32 v92, v92
	v_add_f32_e32 v67, v88, v67
	v_exp_f32_e32 v93, v93
	v_add_f32_e32 v67, v89, v67
	v_exp_f32_e32 v94, v94
	v_add_f32_e32 v67, v90, v67
	v_exp_f32_e32 v95, v95
	v_add_f32_e32 v67, v91, v67
	v_exp_f32_e32 v96, v96
	v_add_f32_e32 v67, v92, v67
	v_exp_f32_e32 v97, v97
	v_add_f32_e32 v67, v93, v67
	v_exp_f32_e32 v98, v98
	v_add_f32_e32 v67, v94, v67
	v_add_f32_e32 v67, v95, v67
	v_add_f32_e32 v67, v96, v67
	v_add_f32_e32 v67, v97, v67
	v_add_f32_e32 v67, v98, v67
	v_add_f32_e32 v67, v101, v67
	v_mov_b32_e32 v68, v67
	s_nop 1
	v_permlane32_swap_b32_e32 v67, v68
	v_cvt_pk_bf16_f32 v70, v99, v69
	v_cvt_pk_bf16_f32 v71, v100, v71
	v_cvt_pk_bf16_f32 v72, v72, v73
	v_cvt_pk_bf16_f32 v73, v74, v75
	v_cvt_pk_bf16_f32 v74, v76, v77
	v_cvt_pk_bf16_f32 v75, v78, v79
	v_cvt_pk_bf16_f32 v76, v80, v81
	v_cvt_pk_bf16_f32 v77, v82, v83
	v_cvt_pk_bf16_f32 v78, v84, v85
	v_cvt_pk_bf16_f32 v79, v86, v87
	v_cvt_pk_bf16_f32 v80, v88, v89
	v_cvt_pk_bf16_f32 v81, v90, v91
	v_cvt_pk_bf16_f32 v82, v92, v93
	v_cvt_pk_bf16_f32 v83, v94, v95
	v_cvt_pk_bf16_f32 v84, v96, v97
	v_cvt_pk_bf16_f32 v85, v98, v101
	s_nop 0
	v_permlane32_swap_b32_e32 v70, v72
	v_permlane32_swap_b32_e32 v71, v73
	v_permlane32_swap_b32_e32 v74, v76
	v_permlane32_swap_b32_e32 v75, v77
	v_permlane32_swap_b32_e32 v78, v80
	v_permlane32_swap_b32_e32 v79, v81
	v_permlane32_swap_b32_e32 v82, v84
	v_permlane32_swap_b32_e32 v83, v85
	v_add_u32_e32 v69, s0, v171
	ds_read_b64_tr_b16 v[86:87], v69 offset:0
	ds_read_b64_tr_b16 v[88:89], v69 offset:0x800
	ds_read_b64_tr_b16 v[90:91], v69 offset:0x1000
	ds_read_b64_tr_b16 v[92:93], v69 offset:0x1800
	ds_read_b64_tr_b16 v[94:95], v69 offset:0x2000
	ds_read_b64_tr_b16 v[96:97], v69 offset:0x2800
	ds_read_b64_tr_b16 v[98:99], v69 offset:0x3000
	ds_read_b64_tr_b16 v[100:101], v69 offset:0x3800
	s_waitcnt lgkmcnt(0)
	s_nop 0
	v_mfma_f32_32x32x16_bf16 v[0:15], v[70:73], v[86:89], v[0:15]
	ds_read_b64_tr_b16 v[86:87], v69 offset:0x200
	ds_read_b64_tr_b16 v[88:89], v69 offset:0xa00
	v_mfma_f32_32x32x16_bf16 v[0:15], v[74:77], v[90:93], v[0:15]
	ds_read_b64_tr_b16 v[90:91], v69 offset:0x1200
	ds_read_b64_tr_b16 v[92:93], v69 offset:0x1a00
	v_mfma_f32_32x32x16_bf16 v[0:15], v[78:81], v[94:97], v[0:15]
	ds_read_b64_tr_b16 v[94:95], v69 offset:0x2200
	ds_read_b64_tr_b16 v[96:97], v69 offset:0x2a00
	v_mfma_f32_32x32x16_bf16 v[0:15], v[82:85], v[98:101], v[0:15]
	ds_read_b64_tr_b16 v[98:99], v69 offset:0x3200
	ds_read_b64_tr_b16 v[100:101], v69 offset:0x3a00
	s_waitcnt lgkmcnt(0)
	v_mfma_f32_32x32x16_bf16 v[48:63], v[70:73], v[86:89], v[48:63]
	ds_read_b64_tr_b16 v[86:87], v69 offset:0x400
	ds_read_b64_tr_b16 v[88:89], v69 offset:0xc00
	v_mfma_f32_32x32x16_bf16 v[48:63], v[74:77], v[90:93], v[48:63]
	ds_read_b64_tr_b16 v[90:91], v69 offset:0x1400
	ds_read_b64_tr_b16 v[92:93], v69 offset:0x1c00
	v_mfma_f32_32x32x16_bf16 v[48:63], v[78:81], v[94:97], v[48:63]
	ds_read_b64_tr_b16 v[94:95], v69 offset:0x2400
	ds_read_b64_tr_b16 v[96:97], v69 offset:0x2c00
	v_mfma_f32_32x32x16_bf16 v[48:63], v[82:85], v[98:101], v[48:63]
	ds_read_b64_tr_b16 v[98:99], v69 offset:0x3400
	ds_read_b64_tr_b16 v[100:101], v69 offset:0x3c00
	s_waitcnt lgkmcnt(0)
; #define SBAR() __builtin_amdgcn_sched_barrier(0)
; __device__ __forceinline__ int crow(int r, int hi) { return (r & 3) + 8 * (r >> 2) + 4 * hi; }
; template <bool NA, int ROWB>
; __device__ __forceinline__ void attn_dma(const bf16* __restrict__ Qb, const bf16* __restrict__ Kh, const bf16* __restrict__ Vh, bf16* __restrict__ Ob, int NT, char* lds, const int tid, float* __restrict__ ssb, int qrow0, int kr_lo, const float* bl) {
;     ...
;   finishSM(pB0, pB1, alB, l_reg, pa0, pa1, pa2, pa3); SBAR();
;   pv_d0(o, vb0 + bc * (int)SHM_V, pa0, pa1, pa2, pa3);
;   if (hi == 0) li_l[r32] = l_reg; asm volatile("s_waitcnt lgkmcnt(0)" ::: "memory");
;   float rli[16];
; #pragma unroll
;   for (int r = 0; r < 16; ++r) rli[r] = __builtin_amdgcn_rcpf(li_l[crow(r, hi)]);
;   bf16* Ow = Ob + (long)(wid * QBLK) * LDO;
;     ...
;   int tid_e = tid; asm volatile("" : "+v"(tid_e));
;   const int lane_e = tid_e & 63, wid_e = tid_e >> 6, r32_e = lane_e & 31, hi_e = lane_e >> 5;
;   char* sg = lds + 100 * 1024 + wid_e * 4096;
; #pragma unroll
;   for (int half = 0; half < 2; ++half) {
;     char* wb_e = sg + hi_e * 1024 + r32_e * 2 + hi_e * 64;
;     char* wb_o = sg + hi_e * 1024 + r32_e * 2 - hi_e * 64;
; #pragma unroll
;     for (int rr = 0; rr < 8; ++rr) { const int r = half * 8 + rr; const int rc = ((rr & 3) + 8 * (rr >> 2)) * 256;
; #pragma unroll
;       for (int d0 = 0; d0 < 4; ++d0) { const float v = o[d0][r] * rli[r]; *(bf16*)(((d0 & 1) ? wb_o : wb_e) + rc + d0 * 64) = (bf16)(cvtpk(v, v) & 0xffffu); } }
	v_mfma_f32_32x32x16_bf16 v[32:47], v[70:73], v[86:89], v[32:47]
	ds_read_b64_tr_b16 v[86:87], v69 offset:0x600
	ds_read_b64_tr_b16 v[88:89], v69 offset:0xe00
	v_mfma_f32_32x32x16_bf16 v[32:47], v[74:77], v[90:93], v[32:47]
	ds_read_b64_tr_b16 v[90:91], v69 offset:0x1600
	ds_read_b64_tr_b16 v[92:93], v69 offset:0x1e00
	v_mfma_f32_32x32x16_bf16 v[32:47], v[78:81], v[94:97], v[32:47]
	ds_read_b64_tr_b16 v[94:95], v69 offset:0x2600
	ds_read_b64_tr_b16 v[96:97], v69 offset:0x2e00
	v_mfma_f32_32x32x16_bf16 v[32:47], v[82:85], v[98:101], v[32:47]
	ds_read_b64_tr_b16 v[98:99], v69 offset:0x3600
	ds_read_b64_tr_b16 v[100:101], v69 offset:0x3e00
	s_waitcnt lgkmcnt(0)
	v_mfma_f32_32x32x16_bf16 v[16:31], v[70:73], v[86:89], v[16:31]
	v_mfma_f32_32x32x16_bf16 v[16:31], v[74:77], v[90:93], v[16:31]
	v_mfma_f32_32x32x16_bf16 v[16:31], v[78:81], v[94:97], v[16:31]
	v_mfma_f32_32x32x16_bf16 v[16:31], v[82:85], v[98:101], v[16:31]
	s_and_saveexec_b64 s[14:15], s[12:13]
	v_add_f32_e32 v64, v64, v65
	v_fmac_f32_e32 v64, v160, v188
	v_add_f32_e32 v65, v67, v68
	v_fmac_f32_e32 v65, v64, v66
	ds_write_b32 v181, v65
	s_or_b64 exec, exec, s[14:15]
	v_readlane_b32 s16, v254, 51
	v_readlane_b32 s17, v254, 52
	s_waitcnt lgkmcnt(0)
	v_add_u32_e32 v72, v169, v172
	s_lshl_b64 s[0:1], s[16:17], 12
	v_readlane_b32 s14, v254, 41
	ds_read_b128 v[64:67], v72
	ds_read_b128 v[68:71], v72 offset:32
	s_add_u32 s0, s14, s0
	v_readlane_b32 s14, v254, 42
	s_addc_u32 s1, s14, s1
	v_readlane_b32 s14, v254, 53
	s_lshl_b32 s14, s14, 1
	s_add_u32 s0, s0, s14
	s_waitcnt lgkmcnt(1)
	v_rcp_f32_e32 v83, v64
	s_addc_u32 s1, s1, 0
	v_mov_b32_e32 v74, v200
	v_rcp_f32_e32 v86, v65
	v_rcp_f32_e32 v87, v66
	v_rcp_f32_e32 v88, v67
	s_waitcnt lgkmcnt(0)
	v_rcp_f32_e32 v89, v68
	v_rcp_f32_e32 v90, v69
	v_rcp_f32_e32 v91, v70
	v_rcp_f32_e32 v92, v71
	ds_read_b128 v[68:71], v72 offset:64
	ds_read_b128 v[64:67], v72 offset:96
	v_lshl_add_u64 v[72:73], s[0:1], 0, v[140:141]
	v_readlane_b32 s0, v254, 20
	v_ashrrev_i32_e32 v79, 6, v74
	v_bfe_u32 v75, v74, 5, 1
	v_lshlrev_b32_e32 v80, 1, v74
	v_and_b32_e32 v94, 15, v74
	v_and_b32_e32 v76, 63, v74
	v_lshl_add_u32 v77, v79, 12, s0
	v_lshlrev_b32_e32 v78, 10, v75
	v_and_b32_e32 v80, 62, v80
	v_lshlrev_b32_e32 v81, 6, v75
	v_bfe_u32 v93, v74, 4, 2
	v_lshlrev_b32_e32 v74, 4, v94
	v_mov_b32_e32 v75, v113
	v_add3_u32 v80, v77, v78, v80
	v_lshl_add_u64 v[84:85], v[72:73], 0, v[74:75]
	v_lshlrev_b32_e32 v72, 2, v76
	v_mul_f32_e32 v0, v0, v83
	v_lshl_add_u32 v82, v93, 8, v77
	v_xor_b32_e32 v78, 4, v72
	v_xor_b32_e32 v77, 8, v72
	v_xor_b32_e32 v76, 16, v72
	v_xor_b32_e32 v75, 32, v72
	v_lshl_or_b32 v72, v79, 5, v93
	v_cvt_pk_bf16_f32 v0, v0, v0
	v_add_u32_e32 v79, v80, v81
	ds_write_b16 v79, v0
	v_mul_f32_e32 v0, v48, v83
	v_cvt_pk_bf16_f32 v0, v0, v0
	v_sub_u32_e32 v48, v80, v81
	ds_write_b16 v48, v0 offset:64
	v_mul_f32_e32 v0, v32, v83
	v_cvt_pk_bf16_f32 v0, v0, v0
	ds_write_b16 v79, v0 offset:128
	v_mul_f32_e32 v0, v16, v83
	v_cvt_pk_bf16_f32 v0, v0, v0
	ds_write_b16 v48, v0 offset:192
	v_mul_f32_e32 v0, v1, v86
	v_cvt_pk_bf16_f32 v0, v0, v0
	ds_write_b16 v79, v0 offset:256
	v_mul_f32_e32 v0, v49, v86
	v_cvt_pk_bf16_f32 v0, v0, v0
	ds_write_b16 v48, v0 offset:320
	v_mul_f32_e32 v0, v33, v86
	v_cvt_pk_bf16_f32 v0, v0, v0
	ds_write_b16 v79, v0 offset:384
	v_mul_f32_e32 v0, v17, v86
	v_cvt_pk_bf16_f32 v0, v0, v0
	ds_write_b16 v48, v0 offset:448
	v_mul_f32_e32 v0, v2, v87
	v_cvt_pk_bf16_f32 v0, v0, v0
	ds_write_b16 v79, v0 offset:512
	v_mul_f32_e32 v0, v50, v87
	v_cvt_pk_bf16_f32 v0, v0, v0
	ds_write_b16 v48, v0 offset:576
	v_mul_f32_e32 v0, v34, v87
	v_cvt_pk_bf16_f32 v0, v0, v0
	ds_write_b16 v79, v0 offset:640
	v_mul_f32_e32 v0, v18, v87
	v_cvt_pk_bf16_f32 v0, v0, v0
	ds_write_b16 v48, v0 offset:704
	v_mul_f32_e32 v0, v3, v88
	v_cvt_pk_bf16_f32 v0, v0, v0
	ds_write_b16 v79, v0 offset:768
	v_mul_f32_e32 v0, v51, v88
	v_cvt_pk_bf16_f32 v0, v0, v0
	ds_write_b16 v48, v0 offset:832
	v_mul_f32_e32 v0, v35, v88
	v_cvt_pk_bf16_f32 v0, v0, v0
	ds_write_b16 v79, v0 offset:896
	v_mul_f32_e32 v0, v19, v88
	v_cvt_pk_bf16_f32 v0, v0, v0
	ds_write_b16 v48, v0 offset:960
	v_mul_f32_e32 v0, v4, v89
	v_cvt_pk_bf16_f32 v0, v0, v0
	ds_write_b16 v79, v0 offset:2048
	v_mul_f32_e32 v0, v52, v89
	v_cvt_pk_bf16_f32 v0, v0, v0
	ds_write_b16 v48, v0 offset:2112
	v_mul_f32_e32 v0, v36, v89
	v_cvt_pk_bf16_f32 v0, v0, v0
	ds_write_b16 v79, v0 offset:2176
	v_mul_f32_e32 v0, v20, v89
	v_cvt_pk_bf16_f32 v0, v0, v0
	ds_write_b16 v48, v0 offset:2240
	v_mul_f32_e32 v0, v5, v90
	v_cvt_pk_bf16_f32 v0, v0, v0
	ds_write_b16 v79, v0 offset:2304
	v_mul_f32_e32 v0, v53, v90
	v_cvt_pk_bf16_f32 v0, v0, v0
	ds_write_b16 v48, v0 offset:2368
	v_mul_f32_e32 v0, v37, v90
	v_cvt_pk_bf16_f32 v0, v0, v0
	ds_write_b16 v79, v0 offset:2432
	v_mul_f32_e32 v0, v21, v90
	v_cvt_pk_bf16_f32 v0, v0, v0
	ds_write_b16 v48, v0 offset:2496
	v_mul_f32_e32 v0, v6, v91
	v_cvt_pk_bf16_f32 v0, v0, v0
	ds_write_b16 v79, v0 offset:2560
	v_mul_f32_e32 v0, v54, v91
	v_cvt_pk_bf16_f32 v0, v0, v0
	ds_write_b16 v48, v0 offset:2624
	v_mul_f32_e32 v0, v38, v91
	v_cvt_pk_bf16_f32 v0, v0, v0
	ds_write_b16 v79, v0 offset:2688
	v_mul_f32_e32 v0, v22, v91
	v_cvt_pk_bf16_f32 v0, v0, v0
	ds_write_b16 v48, v0 offset:2752
	v_mul_f32_e32 v0, v7, v92
	v_cvt_pk_bf16_f32 v0, v0, v0
	ds_write_b16 v79, v0 offset:2816
	v_mul_f32_e32 v0, v55, v92
	v_cvt_pk_bf16_f32 v0, v0, v0
	ds_write_b16 v48, v0 offset:2880
	v_mul_f32_e32 v0, v39, v92
	v_cvt_pk_bf16_f32 v0, v0, v0
	ds_write_b16 v79, v0 offset:2944
	v_mul_f32_e32 v0, v23, v92
	v_cvt_pk_bf16_f32 v0, v0, v0
	ds_write_b16 v48, v0 offset:3008
	s_waitcnt lgkmcnt(0)
; __device__ __forceinline__ float xs(float v, int o, int lane) { return __int_as_float(__builtin_amdgcn_ds_bpermute((lane ^ o) << 2, __float_as_int(v))); }
; __device__ __forceinline__ void st16_wt(void* p, u32x4 v) { asm volatile("global_store_dwordx4 %0, %1, off sc0 sc1\n\ts_nop 1" :: "v"(p), "v"(v) : "memory"); }
; template <bool NA, int ROWB>
; __device__ __forceinline__ void attn_dma(const bf16* __restrict__ Qb, const bf16* __restrict__ Kh, const bf16* __restrict__ Vh, bf16* __restrict__ Ob, int NT, char* lds, const int tid, float* __restrict__ ssb, int qrow0, int kr_lo, const float* bl) {
;     ...
;     const char* rb_e = sg + (lane_e >> 4) * 256 + (lane_e & 15) * 16;
;     const char* rb_o = sg + (lane_e >> 4) * 256 + (((lane_e & 15) * 16) ^ 64);
;     bf16* gb = Ow + (long)(half * 16 + (lane_e >> 4)) * LDO + (lane_e & 15) * 8;
; #pragma unroll
;     for (int i = 0; i < 4; ++i) { const u32x4 w = *(const u32x4*)(((i & 1) ? rb_o : rb_e) + i * 1024); st16_wt(gb + (long)i * 4 * LDO, w);
;       float q = sumsq8(w); q += xs(q, 1, lane_e); q += xs(q, 2, lane_e); q += xs(q, 4, lane_e); q += xs(q, 8, lane_e);
;       if ((lane_e & 15) == 0) ssb[(size_t)(wid_e * QBLK + half * 16 + (lane_e >> 4) + 4 * i) * 16] = q; }
	v_add_u32_e32 v2, v82, v74
	ds_read_b128 v[4:7], v2
	v_lshlrev_b32_e32 v0, 12, v93
	v_mov_b32_e32 v1, v113
	v_lshl_add_u64 v[0:1], v[84:85], 0, v[0:1]
	s_waitcnt lgkmcnt(0)
	global_store_dwordx4 v[0:1], v[4:7], off sc0 sc1
	s_nop 1
	v_lshlrev_b32_e32 v3, 16, v4
	v_and_b32_e32 v4, 0xffff0000, v4
	v_mul_f32_e32 v4, v4, v4
	v_fmac_f32_e32 v4, v3, v3
	v_lshlrev_b32_e32 v3, 16, v5
	v_and_b32_e32 v5, 0xffff0000, v5
	v_mul_f32_e32 v5, v5, v5
	v_fmac_f32_e32 v5, v3, v3
	v_add_f32_e32 v3, v4, v5
	v_and_b32_e32 v5, 0xffff0000, v6
	v_lshlrev_b32_e32 v4, 16, v6
	v_mul_f32_e32 v5, v5, v5
	v_fmac_f32_e32 v5, v4, v4
	v_add_f32_e32 v3, v5, v3
	v_and_b32_e32 v5, 0xffff0000, v7
	v_lshlrev_b32_e32 v4, 16, v7
	v_mul_f32_e32 v5, v5, v5
	v_fmac_f32_e32 v5, v4, v4
	v_add_f32_e32 v3, v5, v3
	s_nop 1
	v_mov_b32_dpp v4, v3 quad_perm:[1,0,3,2] row_mask:0xf bank_mask:0xf
	s_lshl_b64 s[14:15], s[16:17], 6
	v_readlane_b32 s16, v254, 58
	s_add_u32 s14, s16, s14
	v_readlane_b32 s16, v254, 59
	s_waitcnt lgkmcnt(0)
	v_add_f32_e32 v3, v3, v4
	s_nop 1
	v_mov_b32_dpp v4, v3 quad_perm:[2,3,0,1] row_mask:0xf bank_mask:0xf
	s_addc_u32 s15, s16, s15
	s_lshl_b32 s16, s36, 2
	s_add_u32 s18, s14, s16
	s_addc_u32 s19, s15, 0
	s_waitcnt lgkmcnt(0)
	v_add_f32_e32 v3, v3, v4
	s_nop 1
	v_mov_b32_dpp v4, v3 row_half_mirror row_mask:0xf bank_mask:0xf
	v_cmp_eq_u32_e32 vcc, 0, v94
	s_waitcnt lgkmcnt(0)
	v_add_f32_e32 v3, v3, v4
	s_nop 1
	v_mov_b32_dpp v4, v3 row_mirror row_mask:0xf bank_mask:0xf
	s_and_saveexec_b64 s[14:15], vcc
	s_cbranch_execz .LBB0_307
	v_ashrrev_i32_e32 v73, 31, v72
	v_lshlrev_b64 v[6:7], 6, v[72:73]
	v_lshl_add_u64 v[6:7], s[18:19], 0, v[6:7]
	s_waitcnt lgkmcnt(0)
	v_add_f32_e32 v3, v3, v4
	global_store_dword v[6:7], v3, off
.LBB0_307:
	s_or_b64 exec, exec, s[14:15]
	v_xor_b32_e32 v3, 64, v74
	v_add_u32_e32 v3, v82, v3
	s_waitcnt lgkmcnt(0)
	ds_read_b128 v[4:7], v3 offset:1024
	s_mov_b64 s[0:1], 0x4000
	v_lshl_add_u64 v[16:17], v[0:1], 0, s[0:1]
	s_waitcnt lgkmcnt(0)
	global_store_dwordx4 v[16:17], v[4:7], off sc0 sc1
	s_nop 1
	v_lshlrev_b32_e32 v16, 16, v4
	v_and_b32_e32 v4, 0xffff0000, v4
	v_mul_f32_e32 v4, v4, v4
	v_fmac_f32_e32 v4, v16, v16
	v_lshlrev_b32_e32 v16, 16, v5
	v_and_b32_e32 v5, 0xffff0000, v5
	v_mul_f32_e32 v5, v5, v5
	v_fmac_f32_e32 v5, v16, v16
	v_add_f32_e32 v4, v4, v5
	v_lshlrev_b32_e32 v5, 16, v6
	v_and_b32_e32 v6, 0xffff0000, v6
	v_mul_f32_e32 v6, v6, v6
	v_fmac_f32_e32 v6, v5, v5
	v_add_f32_e32 v4, v6, v4
	v_and_b32_e32 v6, 0xffff0000, v7
	v_lshlrev_b32_e32 v5, 16, v7
	v_mul_f32_e32 v6, v6, v6
	v_fmac_f32_e32 v6, v5, v5
	v_add_f32_e32 v4, v6, v4
	s_nop 1
	v_mov_b32_dpp v5, v4 quad_perm:[1,0,3,2] row_mask:0xf bank_mask:0xf
	s_waitcnt lgkmcnt(0)
	v_add_f32_e32 v4, v4, v5
	s_nop 1
	v_mov_b32_dpp v5, v4 quad_perm:[2,3,0,1] row_mask:0xf bank_mask:0xf
	s_waitcnt lgkmcnt(0)
	v_add_f32_e32 v4, v4, v5
	s_nop 1
	v_mov_b32_dpp v5, v4 row_half_mirror row_mask:0xf bank_mask:0xf
	s_waitcnt lgkmcnt(0)
	v_add_f32_e32 v4, v4, v5
	s_nop 1
	v_mov_b32_dpp v5, v4 row_mirror row_mask:0xf bank_mask:0xf
	s_and_saveexec_b64 s[14:15], vcc
	s_cbranch_execz .LBB0_309
	v_or_b32_e32 v6, 4, v72
	v_ashrrev_i32_e32 v7, 31, v6
	v_lshlrev_b64 v[6:7], 6, v[6:7]
	v_lshl_add_u64 v[6:7], s[18:19], 0, v[6:7]
	s_waitcnt lgkmcnt(0)
	v_add_f32_e32 v4, v4, v5
	global_store_dword v[6:7], v4, off
.LBB0_309:
	s_or_b64 exec, exec, s[14:15]
	s_waitcnt lgkmcnt(0)
	ds_read_b128 v[4:7], v2 offset:2048
	s_mov_b64 s[0:1], 0x8000
	v_lshl_add_u64 v[16:17], v[0:1], 0, s[0:1]
	s_waitcnt lgkmcnt(0)
	global_store_dwordx4 v[16:17], v[4:7], off sc0 sc1
	s_nop 1
	v_lshlrev_b32_e32 v16, 16, v4
	v_and_b32_e32 v4, 0xffff0000, v4
	v_mul_f32_e32 v4, v4, v4
	v_fmac_f32_e32 v4, v16, v16
	v_lshlrev_b32_e32 v16, 16, v5
	v_and_b32_e32 v5, 0xffff0000, v5
	v_mul_f32_e32 v5, v5, v5
	v_fmac_f32_e32 v5, v16, v16
	v_add_f32_e32 v4, v4, v5
	v_lshlrev_b32_e32 v5, 16, v6
	v_and_b32_e32 v6, 0xffff0000, v6
	v_mul_f32_e32 v6, v6, v6
	v_fmac_f32_e32 v6, v5, v5
	v_add_f32_e32 v4, v6, v4
	v_and_b32_e32 v6, 0xffff0000, v7
	v_lshlrev_b32_e32 v5, 16, v7
	v_mul_f32_e32 v6, v6, v6
	v_fmac_f32_e32 v6, v5, v5
	v_add_f32_e32 v4, v6, v4
	s_nop 1
	v_mov_b32_dpp v5, v4 quad_perm:[1,0,3,2] row_mask:0xf bank_mask:0xf
	s_waitcnt lgkmcnt(0)
	v_add_f32_e32 v4, v4, v5
	s_nop 1
	v_mov_b32_dpp v5, v4 quad_perm:[2,3,0,1] row_mask:0xf bank_mask:0xf
	s_waitcnt lgkmcnt(0)
	v_add_f32_e32 v4, v4, v5
	s_nop 1
	v_mov_b32_dpp v5, v4 row_half_mirror row_mask:0xf bank_mask:0xf
	s_waitcnt lgkmcnt(0)
	v_add_f32_e32 v4, v4, v5
	s_nop 1
	v_mov_b32_dpp v5, v4 row_mirror row_mask:0xf bank_mask:0xf
	s_and_saveexec_b64 s[14:15], vcc
	s_cbranch_execz .LBB0_311
	v_or_b32_e32 v6, 8, v72
	v_ashrrev_i32_e32 v7, 31, v6
	v_lshlrev_b64 v[6:7], 6, v[6:7]
	v_lshl_add_u64 v[6:7], s[18:19], 0, v[6:7]
	s_waitcnt lgkmcnt(0)
	v_add_f32_e32 v4, v4, v5
	global_store_dword v[6:7], v4, off
.LBB0_311:
	s_or_b64 exec, exec, s[14:15]
	s_waitcnt lgkmcnt(0)
	ds_read_b128 v[4:7], v3 offset:3072
	s_mov_b64 s[0:1], 0xc000
	v_lshl_add_u64 v[16:17], v[0:1], 0, s[0:1]
	s_waitcnt lgkmcnt(0)
	global_store_dwordx4 v[16:17], v[4:7], off sc0 sc1
	s_nop 1
	v_lshlrev_b32_e32 v16, 16, v4
	v_and_b32_e32 v4, 0xffff0000, v4
	v_mul_f32_e32 v4, v4, v4
	v_fmac_f32_e32 v4, v16, v16
	v_lshlrev_b32_e32 v16, 16, v5
	v_and_b32_e32 v5, 0xffff0000, v5
	v_mul_f32_e32 v5, v5, v5
	v_fmac_f32_e32 v5, v16, v16
	v_add_f32_e32 v4, v4, v5
	v_lshlrev_b32_e32 v5, 16, v6
	v_and_b32_e32 v6, 0xffff0000, v6
	v_mul_f32_e32 v6, v6, v6
	v_fmac_f32_e32 v6, v5, v5
	v_add_f32_e32 v4, v6, v4
	v_and_b32_e32 v6, 0xffff0000, v7
	v_lshlrev_b32_e32 v5, 16, v7
	v_mul_f32_e32 v6, v6, v6
	v_fmac_f32_e32 v6, v5, v5
	v_add_f32_e32 v4, v6, v4
	s_nop 1
	v_mov_b32_dpp v5, v4 quad_perm:[1,0,3,2] row_mask:0xf bank_mask:0xf
	s_waitcnt lgkmcnt(0)
	v_add_f32_e32 v4, v4, v5
	s_nop 1
	v_mov_b32_dpp v5, v4 quad_perm:[2,3,0,1] row_mask:0xf bank_mask:0xf
	s_waitcnt lgkmcnt(0)
	v_add_f32_e32 v4, v4, v5
	s_nop 1
	v_mov_b32_dpp v5, v4 row_half_mirror row_mask:0xf bank_mask:0xf
	s_waitcnt lgkmcnt(0)
	v_add_f32_e32 v4, v4, v5
	s_nop 1
	v_mov_b32_dpp v5, v4 row_mirror row_mask:0xf bank_mask:0xf
	s_and_saveexec_b64 s[14:15], vcc
	s_cbranch_execz .LBB0_313
	v_or_b32_e32 v6, 12, v72
	v_ashrrev_i32_e32 v7, 31, v6
	v_lshlrev_b64 v[6:7], 6, v[6:7]
	v_lshl_add_u64 v[6:7], s[18:19], 0, v[6:7]
	s_waitcnt lgkmcnt(0)
	v_add_f32_e32 v4, v4, v5
	global_store_dword v[6:7], v4, off
; __device__ __forceinline__ float xs(float v, int o, int lane) { return __int_as_float(__builtin_amdgcn_ds_bpermute((lane ^ o) << 2, __float_as_int(v))); }
; __device__ __forceinline__ void st16_wt(void* p, u32x4 v) { asm volatile("global_store_dwordx4 %0, %1, off sc0 sc1\n\ts_nop 1" :: "v"(p), "v"(v) : "memory"); }
; template <bool NA, int ROWB>
; __device__ __forceinline__ void attn_dma(const bf16* __restrict__ Qb, const bf16* __restrict__ Kh, const bf16* __restrict__ Vh, bf16* __restrict__ Ob, int NT, char* lds, const int tid, float* __restrict__ ssb, int qrow0, int kr_lo, const float* bl) {
;     ...
;   for (int half = 0; half < 2; ++half) {
;     char* wb_e = sg + hi_e * 1024 + r32_e * 2 + hi_e * 64;
;     char* wb_o = sg + hi_e * 1024 + r32_e * 2 - hi_e * 64;
; #pragma unroll
;     for (int rr = 0; rr < 8; ++rr) { const int r = half * 8 + rr; const int rc = ((rr & 3) + 8 * (rr >> 2)) * 256;
; #pragma unroll
;       for (int d0 = 0; d0 < 4; ++d0) { const float v = o[d0][r] * rli[r]; *(bf16*)(((d0 & 1) ? wb_o : wb_e) + rc + d0 * 64) = (bf16)(cvtpk(v, v) & 0xffffu); } }
;     asm volatile("s_waitcnt lgkmcnt(0)" ::: "memory");
;     const char* rb_e = sg + (lane_e >> 4) * 256 + (lane_e & 15) * 16;
;     const char* rb_o = sg + (lane_e >> 4) * 256 + (((lane_e & 15) * 16) ^ 64);
;     bf16* gb = Ow + (long)(half * 16 + (lane_e >> 4)) * LDO + (lane_e & 15) * 8;
; #pragma unroll
;     for (int i = 0; i < 4; ++i) { const u32x4 w = *(const u32x4*)(((i & 1) ? rb_o : rb_e) + i * 1024); st16_wt(gb + (long)i * 4 * LDO, w);
;       float q = sumsq8(w); q += xs(q, 1, lane_e); q += xs(q, 2, lane_e); q += xs(q, 4, lane_e); q += xs(q, 8, lane_e);
;       if ((lane_e & 15) == 0) ssb[(size_t)(wid_e * QBLK + half * 16 + (lane_e >> 4) + 4 * i) * 16] = q; }
.LBB0_313:
	s_or_b64 exec, exec, s[14:15]
	s_waitcnt lgkmcnt(0)
	v_rcp_f32_e32 v5, v68
	s_waitcnt lgkmcnt(0)
	v_sub_u32_e32 v4, 0, v81
	v_rcp_f32_e32 v6, v69
	v_mul_f32_e32 v8, v8, v5
	v_cvt_pk_bf16_f32 v8, v8, v8
	ds_write_b16 v79, v8
	v_mul_f32_e32 v8, v56, v5
	v_cvt_pk_bf16_f32 v8, v8, v8
	v_add_u32_e32 v4, v80, v4
	ds_write_b16 v4, v8 offset:64
	v_mul_f32_e32 v8, v40, v5
	v_mul_f32_e32 v5, v24, v5
	v_cvt_pk_bf16_f32 v8, v8, v8
	ds_write_b16 v79, v8 offset:128
	v_cvt_pk_bf16_f32 v5, v5, v5
	ds_write_b16 v4, v5 offset:192
	v_mul_f32_e32 v5, v9, v6
	v_cvt_pk_bf16_f32 v5, v5, v5
	ds_write_b16 v79, v5 offset:256
	v_mul_f32_e32 v5, v57, v6
	v_cvt_pk_bf16_f32 v5, v5, v5
	v_rcp_f32_e32 v7, v70
	ds_write_b16 v4, v5 offset:320
	v_mul_f32_e32 v5, v41, v6
	v_cvt_pk_bf16_f32 v5, v5, v5
	ds_write_b16 v79, v5 offset:384
	v_mul_f32_e32 v5, v25, v6
	v_cvt_pk_bf16_f32 v5, v5, v5
	ds_write_b16 v4, v5 offset:448
	v_mul_f32_e32 v5, v10, v7
	v_cvt_pk_bf16_f32 v5, v5, v5
	ds_write_b16 v79, v5 offset:512
	v_mul_f32_e32 v5, v58, v7
	v_cvt_pk_bf16_f32 v5, v5, v5
	v_rcp_f32_e32 v16, v71
	ds_write_b16 v4, v5 offset:576
	v_mul_f32_e32 v5, v42, v7
	v_cvt_pk_bf16_f32 v5, v5, v5
	ds_write_b16 v79, v5 offset:640
	v_mul_f32_e32 v5, v26, v7
	v_cvt_pk_bf16_f32 v5, v5, v5
	ds_write_b16 v4, v5 offset:704
	v_mul_f32_e32 v5, v11, v16
	v_cvt_pk_bf16_f32 v5, v5, v5
	ds_write_b16 v79, v5 offset:768
	v_mul_f32_e32 v5, v59, v16
	v_cvt_pk_bf16_f32 v5, v5, v5
	v_rcp_f32_e32 v17, v64
	ds_write_b16 v4, v5 offset:832
	v_mul_f32_e32 v5, v43, v16
	v_cvt_pk_bf16_f32 v5, v5, v5
	ds_write_b16 v79, v5 offset:896
	v_mul_f32_e32 v5, v27, v16
	v_cvt_pk_bf16_f32 v5, v5, v5
	ds_write_b16 v4, v5 offset:960
	v_mul_f32_e32 v5, v12, v17
	v_cvt_pk_bf16_f32 v5, v5, v5
	ds_write_b16 v79, v5 offset:2048
	v_mul_f32_e32 v5, v60, v17
	v_cvt_pk_bf16_f32 v5, v5, v5
	v_rcp_f32_e32 v18, v65
	ds_write_b16 v4, v5 offset:2112
	v_mul_f32_e32 v5, v44, v17
	v_cvt_pk_bf16_f32 v5, v5, v5
	ds_write_b16 v79, v5 offset:2176
	v_mul_f32_e32 v5, v28, v17
	v_cvt_pk_bf16_f32 v5, v5, v5
	ds_write_b16 v4, v5 offset:2240
	v_mul_f32_e32 v5, v13, v18
	v_cvt_pk_bf16_f32 v5, v5, v5
	ds_write_b16 v79, v5 offset:2304
	v_mul_f32_e32 v5, v61, v18
	v_cvt_pk_bf16_f32 v5, v5, v5
	v_rcp_f32_e32 v19, v66
	ds_write_b16 v4, v5 offset:2368
	v_mul_f32_e32 v5, v45, v18
	v_cvt_pk_bf16_f32 v5, v5, v5
	ds_write_b16 v79, v5 offset:2432
	v_mul_f32_e32 v5, v29, v18
	v_cvt_pk_bf16_f32 v5, v5, v5
	ds_write_b16 v4, v5 offset:2496
	v_mul_f32_e32 v5, v14, v19
	v_cvt_pk_bf16_f32 v5, v5, v5
	ds_write_b16 v79, v5 offset:2560
	v_mul_f32_e32 v5, v62, v19
	v_cvt_pk_bf16_f32 v5, v5, v5
	v_rcp_f32_e32 v20, v67
	ds_write_b16 v4, v5 offset:2624
	v_mul_f32_e32 v5, v46, v19
	v_cvt_pk_bf16_f32 v5, v5, v5
	ds_write_b16 v79, v5 offset:2688
	v_mul_f32_e32 v5, v30, v19
	v_cvt_pk_bf16_f32 v5, v5, v5
	ds_write_b16 v4, v5 offset:2752
	v_mul_f32_e32 v5, v15, v20
	v_cvt_pk_bf16_f32 v5, v5, v5
	ds_write_b16 v79, v5 offset:2816
	v_mul_f32_e32 v5, v63, v20
	v_cvt_pk_bf16_f32 v5, v5, v5
	ds_write_b16 v4, v5 offset:2880
	v_mul_f32_e32 v5, v47, v20
	v_cvt_pk_bf16_f32 v5, v5, v5
	ds_write_b16 v79, v5 offset:2944
	v_mul_f32_e32 v5, v31, v20
	v_cvt_pk_bf16_f32 v5, v5, v5
	ds_write_b16 v4, v5 offset:3008
	s_waitcnt lgkmcnt(0)
	ds_read_b128 v[6:9], v2
	s_mov_b64 s[0:1], 0x10000
	s_waitcnt lgkmcnt(0)
	v_and_b32_e32 v5, 0xffff0000, v6
	v_lshlrev_b32_e32 v4, 16, v6
	v_mul_f32_e32 v5, v5, v5
	v_and_b32_e32 v10, 0xffff0000, v7
	v_fmac_f32_e32 v5, v4, v4
	v_lshlrev_b32_e32 v4, 16, v7
	v_mul_f32_e32 v10, v10, v10
	v_fmac_f32_e32 v10, v4, v4
	v_add_f32_e32 v4, v5, v10
	v_and_b32_e32 v10, 0xffff0000, v8
	v_lshlrev_b32_e32 v5, 16, v8
	v_mul_f32_e32 v10, v10, v10
	v_fmac_f32_e32 v10, v5, v5
	v_add_f32_e32 v4, v10, v4
	v_and_b32_e32 v10, 0xffff0000, v9
	v_lshlrev_b32_e32 v5, 16, v9
	v_mul_f32_e32 v10, v10, v10
	v_fmac_f32_e32 v10, v5, v5
	v_add_f32_e32 v4, v10, v4
	s_nop 1
	v_mov_b32_dpp v5, v4 quad_perm:[1,0,3,2] row_mask:0xf bank_mask:0xf
	v_lshl_add_u64 v[10:11], v[0:1], 0, s[0:1]
	global_store_dwordx4 v[10:11], v[6:9], off sc0 sc1
	s_nop 1
	s_waitcnt lgkmcnt(0)
	v_add_f32_e32 v4, v4, v5
	s_nop 1
	v_mov_b32_dpp v5, v4 quad_perm:[2,3,0,1] row_mask:0xf bank_mask:0xf
	s_waitcnt lgkmcnt(0)
	v_add_f32_e32 v4, v4, v5
	s_nop 1
	v_mov_b32_dpp v5, v4 row_half_mirror row_mask:0xf bank_mask:0xf
	s_waitcnt lgkmcnt(0)
	v_add_f32_e32 v4, v4, v5
	s_nop 1
	v_mov_b32_dpp v5, v4 row_mirror row_mask:0xf bank_mask:0xf
	s_and_saveexec_b64 s[14:15], vcc
	s_cbranch_execz .LBB0_315
	v_or_b32_e32 v6, 16, v72
	v_ashrrev_i32_e32 v7, 31, v6
	v_lshlrev_b64 v[6:7], 6, v[6:7]
	v_lshl_add_u64 v[6:7], s[18:19], 0, v[6:7]
	s_waitcnt lgkmcnt(0)
	v_add_f32_e32 v4, v4, v5
	global_store_dword v[6:7], v4, off
; __device__ __forceinline__ float xs(float v, int o, int lane) { return __int_as_float(__builtin_amdgcn_ds_bpermute((lane ^ o) << 2, __float_as_int(v))); }
; __device__ __forceinline__ void st16_wt(void* p, u32x4 v) { asm volatile("global_store_dwordx4 %0, %1, off sc0 sc1\n\ts_nop 1" :: "v"(p), "v"(v) : "memory"); }
; template <bool NA, int ROWB>
; __device__ __forceinline__ void attn_dma(const bf16* __restrict__ Qb, const bf16* __restrict__ Kh, const bf16* __restrict__ Vh, bf16* __restrict__ Ob, int NT, char* lds, const int tid, float* __restrict__ ssb, int qrow0, int kr_lo, const float* bl) {
;     ...
;     const char* rb_e = sg + (lane_e >> 4) * 256 + (lane_e & 15) * 16;
;     const char* rb_o = sg + (lane_e >> 4) * 256 + (((lane_e & 15) * 16) ^ 64);
;     bf16* gb = Ow + (long)(half * 16 + (lane_e >> 4)) * LDO + (lane_e & 15) * 8;
; #pragma unroll
;     for (int i = 0; i < 4; ++i) { const u32x4 w = *(const u32x4*)(((i & 1) ? rb_o : rb_e) + i * 1024); st16_wt(gb + (long)i * 4 * LDO, w);
;       float q = sumsq8(w); q += xs(q, 1, lane_e); q += xs(q, 2, lane_e); q += xs(q, 4, lane_e); q += xs(q, 8, lane_e);
;       if ((lane_e & 15) == 0) ssb[(size_t)(wid_e * QBLK + half * 16 + (lane_e >> 4) + 4 * i) * 16] = q; }
.LBB0_315:
	s_or_b64 exec, exec, s[14:15]
	s_waitcnt lgkmcnt(0)
	ds_read_b128 v[4:7], v3 offset:1024
	s_mov_b64 s[0:1], 0x14000
	v_lshl_add_u64 v[8:9], v[0:1], 0, s[0:1]
	s_waitcnt lgkmcnt(0)
	global_store_dwordx4 v[8:9], v[4:7], off sc0 sc1
	s_nop 1
	v_lshlrev_b32_e32 v8, 16, v4
	v_and_b32_e32 v4, 0xffff0000, v4
	v_mul_f32_e32 v4, v4, v4
	v_fmac_f32_e32 v4, v8, v8
	v_lshlrev_b32_e32 v8, 16, v5
	v_and_b32_e32 v5, 0xffff0000, v5
	v_mul_f32_e32 v5, v5, v5
	v_fmac_f32_e32 v5, v8, v8
	v_add_f32_e32 v4, v4, v5
	v_lshlrev_b32_e32 v5, 16, v6
	v_and_b32_e32 v6, 0xffff0000, v6
	v_mul_f32_e32 v6, v6, v6
	v_fmac_f32_e32 v6, v5, v5
	v_add_f32_e32 v4, v6, v4
	v_and_b32_e32 v6, 0xffff0000, v7
	v_lshlrev_b32_e32 v5, 16, v7
	v_mul_f32_e32 v6, v6, v6
	v_fmac_f32_e32 v6, v5, v5
	v_add_f32_e32 v4, v6, v4
	s_nop 1
	v_mov_b32_dpp v5, v4 quad_perm:[1,0,3,2] row_mask:0xf bank_mask:0xf
	s_waitcnt lgkmcnt(0)
	v_add_f32_e32 v4, v4, v5
	s_nop 1
	v_mov_b32_dpp v5, v4 quad_perm:[2,3,0,1] row_mask:0xf bank_mask:0xf
	s_waitcnt lgkmcnt(0)
	v_add_f32_e32 v4, v4, v5
	s_nop 1
	v_mov_b32_dpp v5, v4 row_half_mirror row_mask:0xf bank_mask:0xf
	s_waitcnt lgkmcnt(0)
	v_add_f32_e32 v4, v4, v5
	s_nop 1
	v_mov_b32_dpp v5, v4 row_mirror row_mask:0xf bank_mask:0xf
	s_and_saveexec_b64 s[14:15], vcc
	s_cbranch_execz .LBB0_317
	v_or_b32_e32 v6, 20, v72
	v_ashrrev_i32_e32 v7, 31, v6
	v_lshlrev_b64 v[6:7], 6, v[6:7]
	v_lshl_add_u64 v[6:7], s[18:19], 0, v[6:7]
	s_waitcnt lgkmcnt(0)
	v_add_f32_e32 v4, v4, v5
	global_store_dword v[6:7], v4, off
.LBB0_317:
	s_or_b64 exec, exec, s[14:15]
	s_waitcnt lgkmcnt(0)
	ds_read_b128 v[4:7], v2 offset:2048
	s_mov_b64 s[0:1], 0x18000
	v_lshl_add_u64 v[8:9], v[0:1], 0, s[0:1]
	s_waitcnt lgkmcnt(0)
	global_store_dwordx4 v[8:9], v[4:7], off sc0 sc1
	s_nop 1
	v_lshlrev_b32_e32 v2, 16, v4
	v_and_b32_e32 v4, 0xffff0000, v4
	v_mul_f32_e32 v4, v4, v4
	v_fmac_f32_e32 v4, v2, v2
	v_lshlrev_b32_e32 v2, 16, v5
	v_and_b32_e32 v5, 0xffff0000, v5
	v_mul_f32_e32 v5, v5, v5
	v_fmac_f32_e32 v5, v2, v2
	v_add_f32_e32 v2, v4, v5
	v_and_b32_e32 v5, 0xffff0000, v6
	v_lshlrev_b32_e32 v4, 16, v6
	v_mul_f32_e32 v5, v5, v5
	v_fmac_f32_e32 v5, v4, v4
	v_add_f32_e32 v2, v5, v2
	v_and_b32_e32 v5, 0xffff0000, v7
	v_lshlrev_b32_e32 v4, 16, v7
	v_mul_f32_e32 v5, v5, v5
	v_fmac_f32_e32 v5, v4, v4
	v_add_f32_e32 v2, v5, v2
	s_nop 1
	v_mov_b32_dpp v4, v2 quad_perm:[1,0,3,2] row_mask:0xf bank_mask:0xf
	s_waitcnt lgkmcnt(0)
	v_add_f32_e32 v2, v2, v4
	s_nop 1
	v_mov_b32_dpp v4, v2 quad_perm:[2,3,0,1] row_mask:0xf bank_mask:0xf
	s_waitcnt lgkmcnt(0)
	v_add_f32_e32 v2, v2, v4
	s_nop 1
	v_mov_b32_dpp v4, v2 row_half_mirror row_mask:0xf bank_mask:0xf
	s_waitcnt lgkmcnt(0)
	v_add_f32_e32 v2, v2, v4
	s_nop 1
	v_mov_b32_dpp v4, v2 row_mirror row_mask:0xf bank_mask:0xf
	s_and_saveexec_b64 s[14:15], vcc
	s_cbranch_execz .LBB0_319
	v_or_b32_e32 v6, 24, v72
	v_ashrrev_i32_e32 v7, 31, v6
	v_lshlrev_b64 v[6:7], 6, v[6:7]
	v_lshl_add_u64 v[6:7], s[18:19], 0, v[6:7]
	s_waitcnt lgkmcnt(0)
	v_add_f32_e32 v2, v2, v4
	global_store_dword v[6:7], v2, off
.LBB0_319:
	s_or_b64 exec, exec, s[14:15]
	s_waitcnt lgkmcnt(0)
	ds_read_b128 v[2:5], v3 offset:3072
	s_mov_b64 s[0:1], 0x1c000
	v_lshl_add_u64 v[0:1], v[0:1], 0, s[0:1]
	s_waitcnt lgkmcnt(0)
	global_store_dwordx4 v[0:1], v[2:5], off sc0 sc1
	s_nop 1
	v_and_b32_e32 v1, 0xffff0000, v2
	v_lshlrev_b32_e32 v0, 16, v2
	v_mul_f32_e32 v1, v1, v1
	v_and_b32_e32 v2, 0xffff0000, v3
	v_fmac_f32_e32 v1, v0, v0
	v_lshlrev_b32_e32 v0, 16, v3
	v_mul_f32_e32 v2, v2, v2
	v_fmac_f32_e32 v2, v0, v0
	v_add_f32_e32 v0, v1, v2
	v_and_b32_e32 v2, 0xffff0000, v4
	v_lshlrev_b32_e32 v1, 16, v4
	v_mul_f32_e32 v2, v2, v2
	v_fmac_f32_e32 v2, v1, v1
	v_add_f32_e32 v0, v2, v0
	v_and_b32_e32 v2, 0xffff0000, v5
	v_lshlrev_b32_e32 v1, 16, v5
	v_mul_f32_e32 v2, v2, v2
	v_fmac_f32_e32 v2, v1, v1
	v_add_f32_e32 v0, v2, v0
	s_nop 1
	v_mov_b32_dpp v1, v0 quad_perm:[1,0,3,2] row_mask:0xf bank_mask:0xf
	s_waitcnt lgkmcnt(0)
	v_add_f32_e32 v0, v0, v1
	s_nop 1
	v_mov_b32_dpp v1, v0 quad_perm:[2,3,0,1] row_mask:0xf bank_mask:0xf
	s_waitcnt lgkmcnt(0)
	v_add_f32_e32 v0, v0, v1
	s_nop 1
	v_mov_b32_dpp v1, v0 row_half_mirror row_mask:0xf bank_mask:0xf
	s_waitcnt lgkmcnt(0)
	v_add_f32_e32 v0, v0, v1
	s_nop 1
	v_mov_b32_dpp v1, v0 row_mirror row_mask:0xf bank_mask:0xf
	s_and_saveexec_b64 s[14:15], vcc
	s_cbranch_execz .LBB0_134
	v_or_b32_e32 v2, 28, v72
	v_ashrrev_i32_e32 v3, 31, v2
	v_lshlrev_b64 v[2:3], 6, v[2:3]
	v_lshl_add_u64 v[2:3], s[18:19], 0, v[2:3]
	s_waitcnt lgkmcnt(0)
	v_add_f32_e32 v0, v0, v1
	global_store_dword v[2:3], v0, off
	s_branch .LBB0_134

; __device__ __forceinline__ float xshfl(float v, int o, int lane) { return __int_as_float(__builtin_amdgcn_ds_bpermute((lane ^ o) << 2, __float_as_int(v))); }
;     __device__ __forceinline__ void run(const f32x4 (&v)[2][2][4][2], const Unit& u, int wr, int wc, int fr, int fq, PG8_LAS unsigned char* lds, int wid, int lane) const {
;     ...
; #pragma unroll
;         for (int ai = 0; ai < 2; ++ai)
; #pragma unroll
;             for (int m = 0; m < 4; ++m) {
;                 float s = 0.f;
; #pragma unroll
;                 for (int bj = 0; bj < 2; ++bj)
; #pragma unroll
;                     for (int n = 0; n < 2; ++n) { const f32x4 x = v[ai][bj][m][n]; s += (x[0] + x[1]) + (x[2] + x[3]); }
;                 s += xshfl(s, 16, lane); s += xshfl(s, 32, lane);
;                 const float mw = s * (1.0f / 64.0f); float q = 0.f;
; #pragma unroll
;                 for (int bj = 0; bj < 2; ++bj)
; #pragma unroll
;                     for (int n = 0; n < 2; ++n) { const f32x4 d = v[ai][bj][m][n] - mw; q += (d[0] * d[0] + d[1] * d[1]) + (d[2] * d[2] + d[3] * d[3]); }
;                 q += xshfl(q, 16, lane); q += xshfl(q, 32, lane);
;                 if (fq == 0) P[(ai * HALF + wr * 64 + m * 16 + fr) * 4 + wc] = (f32x2v){mw, q};
;     __device__ __forceinline__ void fused(f32x4 (&acc)[2][2][4][2], const Unit& u, int wr, int wc, int fr, int fq, PG8_LAS unsigned char* lds, int wid, int lane) const {
;     ...
;         for (int ai = 0; ai < 2; ++ai)
; #pragma unroll
;             for (int m = 0; m < 4; ++m) {
;                 float sbr = 0.5f; if (use_rs) sbr = rs[2 * (wr * 64 + fr) + 2 * (ai * HALF + m * 16) + 1];
; #pragma unroll
;                 for (int bj = 0; bj < 2; ++bj)
; #pragma unroll
;                     for (int n = 0; n < 2; ++n) { const unsigned w0 = bw[ai][m][bj][2 * n], w1 = bw[ai][m][bj][2 * n + 1];
;                         const f32x4 bs = {__uint_as_float(w0 << 16), __uint_as_float(w0 & 0xffff0000u), __uint_as_float(w1 << 16), __uint_as_float(w1 & 0xffff0000u)};
;                         acc[ai][bj][m][n] = bs * 1.4142135623730951f + acc[ai][bj][m][n] * sbr; } }
.LBB0_440:
	s_waitcnt vmcnt(0)
	v_lshlrev_b32_e32 v196, 16, v192
	v_and_b32_e32 v197, 0xffff0000, v192
	v_lshlrev_b32_e32 v192, 16, v193
	v_and_b32_e32 v193, 0xffff0000, v193
	s_waitcnt lgkmcnt(0)
	v_pk_mul_f32 v[130:131], v[130:131], v[216:217] op_sel_hi:[1,0]
	v_pk_mul_f32 v[128:129], v[128:129], v[216:217] op_sel_hi:[1,0]
	s_mov_b32 s4, 0x3fb504f3
	v_pk_fma_f32 v[222:223], v[192:193], s[4:5], v[130:131] op_sel_hi:[1,0,1]
	v_pk_fma_f32 v[224:225], v[196:197], s[4:5], v[128:129] op_sel_hi:[1,0,1]
	v_lshlrev_b32_e32 v128, 16, v194
	v_and_b32_e32 v129, 0xffff0000, v194
	v_lshlrev_b32_e32 v130, 16, v195
	v_and_b32_e32 v131, 0xffff0000, v195
	v_pk_mul_f32 v[126:127], v[126:127], v[216:217] op_sel_hi:[1,0]
	v_pk_mul_f32 v[124:125], v[124:125], v[216:217] op_sel_hi:[1,0]
	v_pk_fma_f32 v[226:227], v[130:131], s[4:5], v[126:127] op_sel_hi:[1,0,1]
	v_pk_fma_f32 v[228:229], v[128:129], s[4:5], v[124:125] op_sel_hi:[1,0,1]
	v_lshlrev_b32_e32 v124, 16, v188
	v_and_b32_e32 v125, 0xffff0000, v188
	v_lshlrev_b32_e32 v126, 16, v189
	v_and_b32_e32 v127, 0xffff0000, v189
	v_pk_mul_f32 v[122:123], v[122:123], v[216:217] op_sel_hi:[1,0]
	v_pk_mul_f32 v[120:121], v[120:121], v[216:217] op_sel_hi:[1,0]
	v_pk_fma_f32 v[192:193], v[126:127], s[4:5], v[122:123] op_sel_hi:[1,0,1]
	v_pk_fma_f32 v[194:195], v[124:125], s[4:5], v[120:121] op_sel_hi:[1,0,1]
	v_lshlrev_b32_e32 v120, 16, v190
	v_and_b32_e32 v121, 0xffff0000, v190
	v_lshlrev_b32_e32 v122, 16, v191
	v_and_b32_e32 v123, 0xffff0000, v191
	v_pk_mul_f32 v[118:119], v[118:119], v[216:217] op_sel_hi:[1,0]
	v_pk_mul_f32 v[116:117], v[116:117], v[216:217] op_sel_hi:[1,0]
	v_pk_fma_f32 v[188:189], v[122:123], s[4:5], v[118:119] op_sel_hi:[1,0,1]
	v_pk_fma_f32 v[190:191], v[120:121], s[4:5], v[116:117] op_sel_hi:[1,0,1]
	v_pk_mov_b32 v[116:117], v[224:225], v[222:223] op_sel:[1,0]
	v_mov_b32_e32 v118, v224
	v_mov_b32_e32 v119, v223
	v_pk_add_f32 v[116:117], v[116:117], v[118:119]
	v_pk_mov_b32 v[118:119], v[228:229], v[226:227] op_sel:[1,0]
	v_mov_b32_e32 v120, v228
	v_mov_b32_e32 v121, v227
	v_pk_add_f32 v[118:119], v[118:119], v[120:121]
	v_add_f32_e32 v116, v116, v117
	v_pk_add_f32 v[118:119], v[118:119], v[118:119] op_sel_hi:[0,1]
	v_add_f32_e32 v117, 0, v116
	v_add_f32_e32 v121, v194, v195
	v_add_f32_e32 v123, v192, v193
	v_mov_b32_e32 v120, v190
	v_mov_b32_e32 v122, v191
	v_mov_b32_e32 v118, v188
	v_mov_b32_e32 v116, v189
	v_pk_add_f32 v[120:121], v[120:121], v[122:123]
	v_pk_add_f32 v[116:117], v[118:119], v[116:117]
	v_lshlrev_b32_e32 v124, 2, v202
	v_pk_add_f32 v[116:117], v[120:121], v[116:117]
	v_xor_b32_e32 v196, 64, v124
	v_add_f32_e32 v116, v116, v117
	v_mov_b32_e32 v117, v116
	s_nop 1
	v_permlane16_swap_b32_e32 v116, v117
	v_xor_b32_e32 v197, 0x80, v124
	s_lshl_b32 s4, s27, 3
	v_cmp_gt_u32_e32 vcc, 16, v202
	s_add_i32 s6, s4, 0
	s_waitcnt lgkmcnt(0)
	v_add_f32_e32 v116, v116, v117
	v_mov_b32_e32 v117, v116
	s_nop 1
	v_permlane32_swap_b32_e32 v116, v117
	s_waitcnt lgkmcnt(0)
	v_add_f32_e32 v116, v116, v117
	v_fmamk_f32 v118, v116, 0xbc800000, v223
	v_fmamk_f32 v120, v116, 0xbc800000, v225
	v_fmamk_f32 v117, v116, 0xbc800000, v222
	v_fmamk_f32 v119, v116, 0xbc800000, v224
	v_mul_f32_e32 v120, v120, v120
	v_mul_f32_e32 v118, v118, v118
	v_fmac_f32_e32 v120, v119, v119
	v_fmac_f32_e32 v118, v117, v117
	v_fmamk_f32 v119, v116, 0xbc800000, v227
	v_fmamk_f32 v121, v116, 0xbc800000, v229
	v_add_f32_e32 v117, v120, v118
	v_fmamk_f32 v118, v116, 0xbc800000, v226
	v_fmamk_f32 v120, v116, 0xbc800000, v228
	v_mul_f32_e32 v121, v121, v121
	v_mul_f32_e32 v119, v119, v119
	v_fmac_f32_e32 v121, v120, v120
	v_fmac_f32_e32 v119, v118, v118
	v_add_f32_e32 v118, v121, v119
	v_fmamk_f32 v119, v116, 0xbc800000, v193
	v_fmamk_f32 v121, v116, 0xbc800000, v195
	v_add_f32_e32 v117, v117, v118
	v_fmamk_f32 v118, v116, 0xbc800000, v192
	v_fmamk_f32 v120, v116, 0xbc800000, v194
	v_mul_f32_e32 v121, v121, v121
	v_mul_f32_e32 v119, v119, v119
	v_fmac_f32_e32 v121, v120, v120
	v_fmac_f32_e32 v119, v118, v118
	v_add_f32_e32 v118, v121, v119
	v_fmamk_f32 v119, v116, 0xbc800000, v189
	v_fmamk_f32 v121, v116, 0xbc800000, v191
	v_add_f32_e32 v117, v118, v117
	v_fmamk_f32 v118, v116, 0xbc800000, v188
	v_fmamk_f32 v120, v116, 0xbc800000, v190
	v_mul_f32_e32 v121, v121, v121
	v_mul_f32_e32 v119, v119, v119
	v_fmac_f32_e32 v121, v120, v120
	v_fmac_f32_e32 v119, v118, v118
	v_add_f32_e32 v118, v121, v119
	v_add_f32_e32 v117, v118, v117
	v_mov_b32_e32 v118, v117
	s_nop 1
	v_permlane16_swap_b32_e32 v117, v118
	s_waitcnt lgkmcnt(0)
	v_add_f32_e32 v117, v117, v118
	v_mov_b32_e32 v118, v117
	s_nop 1
	v_permlane32_swap_b32_e32 v117, v118
	s_and_saveexec_b64 s[4:5], vcc
	s_xor_b64 s[4:5], exec, s[4:5]
	s_cbranch_execz .LBB0_442
	s_lshl_b32 s7, s25, 11
	s_add_i32 s7, s6, s7
	v_mul_f32_e32 v116, 0x3c800000, v116
	v_lshl_add_u32 v119, v241, 5, s7
	s_waitcnt lgkmcnt(0)
	v_add_f32_e32 v117, v117, v118
	ds_write_b64 v119, v[116:117]
; __device__ __forceinline__ float xshfl(float v, int o, int lane) { return __int_as_float(__builtin_amdgcn_ds_bpermute((lane ^ o) << 2, __float_as_int(v))); }
;     __device__ __forceinline__ void run(const f32x4 (&v)[2][2][4][2], const Unit& u, int wr, int wc, int fr, int fq, PG8_LAS unsigned char* lds, int wid, int lane) const {
;     ...
; #pragma unroll
;         for (int ai = 0; ai < 2; ++ai)
; #pragma unroll
;             for (int m = 0; m < 4; ++m) {
;                 float s = 0.f;
; #pragma unroll
;                 for (int bj = 0; bj < 2; ++bj)
; #pragma unroll
;                     for (int n = 0; n < 2; ++n) { const f32x4 x = v[ai][bj][m][n]; s += (x[0] + x[1]) + (x[2] + x[3]); }
;                 s += xshfl(s, 16, lane); s += xshfl(s, 32, lane);
;                 const float mw = s * (1.0f / 64.0f); float q = 0.f;
; #pragma unroll
;                 for (int bj = 0; bj < 2; ++bj)
; #pragma unroll
;                     for (int n = 0; n < 2; ++n) { const f32x4 d = v[ai][bj][m][n] - mw; q += (d[0] * d[0] + d[1] * d[1]) + (d[2] * d[2] + d[3] * d[3]); }
;                 q += xshfl(q, 16, lane); q += xshfl(q, 32, lane);
;                 if (fq == 0) P[(ai * HALF + wr * 64 + m * 16 + fr) * 4 + wc] = (f32x2v){mw, q};
;     __device__ __forceinline__ void fused(f32x4 (&acc)[2][2][4][2], const Unit& u, int wr, int wc, int fr, int fq, PG8_LAS unsigned char* lds, int wid, int lane) const {
;     ...
;         for (int ai = 0; ai < 2; ++ai)
; #pragma unroll
;             for (int m = 0; m < 4; ++m) {
;                 float sbr = 0.5f; if (use_rs) sbr = rs[2 * (wr * 64 + fr) + 2 * (ai * HALF + m * 16) + 1];
; #pragma unroll
;                 for (int bj = 0; bj < 2; ++bj)
; #pragma unroll
;                     for (int n = 0; n < 2; ++n) { const unsigned w0 = bw[ai][m][bj][2 * n], w1 = bw[ai][m][bj][2 * n + 1];
;                         const f32x4 bs = {__uint_as_float(w0 << 16), __uint_as_float(w0 & 0xffff0000u), __uint_as_float(w1 << 16), __uint_as_float(w1 & 0xffff0000u)};
;                         acc[ai][bj][m][n] = bs * 1.4142135623730951f + acc[ai][bj][m][n] * sbr; } }
.LBB0_442:
	s_or_b64 exec, exec, s[4:5]
	v_lshlrev_b32_e32 v116, 16, v184
	v_and_b32_e32 v117, 0xffff0000, v184
	s_waitcnt lgkmcnt(0)
	v_lshlrev_b32_e32 v118, 16, v185
	v_and_b32_e32 v119, 0xffff0000, v185
	v_pk_mul_f32 v[110:111], v[110:111], v[240:241] op_sel_hi:[1,0]
	v_pk_mul_f32 v[108:109], v[108:109], v[240:241] op_sel_hi:[1,0]
	s_mov_b32 s4, 0x3fb504f3
	v_pk_fma_f32 v[216:217], v[118:119], s[4:5], v[110:111] op_sel_hi:[1,0,1]
	v_pk_fma_f32 v[218:219], v[116:117], s[4:5], v[108:109] op_sel_hi:[1,0,1]
	v_lshlrev_b32_e32 v108, 16, v186
	v_and_b32_e32 v109, 0xffff0000, v186
	v_lshlrev_b32_e32 v110, 16, v187
	v_and_b32_e32 v111, 0xffff0000, v187
	v_pk_mul_f32 v[106:107], v[106:107], v[240:241] op_sel_hi:[1,0]
	v_pk_mul_f32 v[104:105], v[104:105], v[240:241] op_sel_hi:[1,0]
	v_pk_fma_f32 v[184:185], v[110:111], s[4:5], v[106:107] op_sel_hi:[1,0,1]
	v_pk_fma_f32 v[186:187], v[108:109], s[4:5], v[104:105] op_sel_hi:[1,0,1]
	v_lshlrev_b32_e32 v104, 16, v180
	v_and_b32_e32 v105, 0xffff0000, v180
	v_lshlrev_b32_e32 v106, 16, v181
	v_and_b32_e32 v107, 0xffff0000, v181
	v_pk_mul_f32 v[102:103], v[102:103], v[240:241] op_sel_hi:[1,0]
	v_pk_mul_f32 v[100:101], v[100:101], v[240:241] op_sel_hi:[1,0]
	v_pk_fma_f32 v[116:117], v[106:107], s[4:5], v[102:103] op_sel_hi:[1,0,1]
	v_pk_fma_f32 v[120:121], v[104:105], s[4:5], v[100:101] op_sel_hi:[1,0,1]
	v_lshlrev_b32_e32 v100, 16, v182
	v_and_b32_e32 v101, 0xffff0000, v182
	v_lshlrev_b32_e32 v102, 16, v183
	v_and_b32_e32 v103, 0xffff0000, v183
	v_pk_mul_f32 v[98:99], v[98:99], v[240:241] op_sel_hi:[1,0]
	v_pk_mul_f32 v[96:97], v[96:97], v[240:241] op_sel_hi:[1,0]
	v_pk_fma_f32 v[104:105], v[102:103], s[4:5], v[98:99] op_sel_hi:[1,0,1]
	v_pk_fma_f32 v[106:107], v[100:101], s[4:5], v[96:97] op_sel_hi:[1,0,1]
	v_pk_mov_b32 v[96:97], v[218:219], v[216:217] op_sel:[1,0]
	v_mov_b32_e32 v98, v218
	v_mov_b32_e32 v99, v217
	v_pk_add_f32 v[96:97], v[96:97], v[98:99]
	v_pk_mov_b32 v[98:99], v[186:187], v[184:185] op_sel:[1,0]
	v_mov_b32_e32 v100, v186
	v_mov_b32_e32 v101, v185
	v_pk_add_f32 v[98:99], v[98:99], v[100:101]
	v_add_f32_e32 v96, v96, v97
	v_pk_add_f32 v[98:99], v[98:99], v[98:99] op_sel_hi:[0,1]
	v_add_f32_e32 v97, 0, v96
	v_add_f32_e32 v101, v120, v121
	v_add_f32_e32 v103, v116, v117
	v_mov_b32_e32 v100, v106
	v_mov_b32_e32 v102, v107
	v_mov_b32_e32 v98, v104
	v_mov_b32_e32 v96, v105
	v_pk_add_f32 v[100:101], v[100:101], v[102:103]
	v_pk_add_f32 v[96:97], v[98:99], v[96:97]
	s_nop 0
	v_pk_add_f32 v[96:97], v[100:101], v[96:97]
	s_nop 0
	v_add_f32_e32 v96, v96, v97
	v_mov_b32_e32 v97, v96
	s_nop 1
	v_permlane16_swap_b32_e32 v96, v97
	s_waitcnt lgkmcnt(0)
	v_add_f32_e32 v96, v96, v97
	v_mov_b32_e32 v97, v96
	s_nop 1
	v_permlane32_swap_b32_e32 v96, v97
	s_waitcnt lgkmcnt(0)
	v_add_f32_e32 v96, v96, v97
	v_fmamk_f32 v98, v96, 0xbc800000, v217
	v_fmamk_f32 v100, v96, 0xbc800000, v219
	v_fmamk_f32 v97, v96, 0xbc800000, v216
	v_fmamk_f32 v99, v96, 0xbc800000, v218
	v_mul_f32_e32 v100, v100, v100
	v_mul_f32_e32 v98, v98, v98
	v_fmac_f32_e32 v100, v99, v99
	v_fmac_f32_e32 v98, v97, v97
	v_fmamk_f32 v99, v96, 0xbc800000, v185
	v_fmamk_f32 v101, v96, 0xbc800000, v187
	v_add_f32_e32 v97, v100, v98
	v_fmamk_f32 v98, v96, 0xbc800000, v184
	v_fmamk_f32 v100, v96, 0xbc800000, v186
	v_mul_f32_e32 v101, v101, v101
	v_mul_f32_e32 v99, v99, v99
	v_fmac_f32_e32 v101, v100, v100
	v_fmac_f32_e32 v99, v98, v98
	v_add_f32_e32 v98, v101, v99
	v_fmamk_f32 v99, v96, 0xbc800000, v117
	v_fmamk_f32 v101, v96, 0xbc800000, v121
	v_add_f32_e32 v97, v97, v98
	v_fmamk_f32 v98, v96, 0xbc800000, v116
	v_fmamk_f32 v100, v96, 0xbc800000, v120
	v_mul_f32_e32 v101, v101, v101
	v_mul_f32_e32 v99, v99, v99
	v_fmac_f32_e32 v101, v100, v100
	v_fmac_f32_e32 v99, v98, v98
	v_add_f32_e32 v98, v101, v99
	v_fmamk_f32 v99, v96, 0xbc800000, v105
	v_fmamk_f32 v101, v96, 0xbc800000, v107
	v_add_f32_e32 v97, v98, v97
	v_fmamk_f32 v98, v96, 0xbc800000, v104
	v_fmamk_f32 v100, v96, 0xbc800000, v106
	v_mul_f32_e32 v101, v101, v101
	v_mul_f32_e32 v99, v99, v99
	v_fmac_f32_e32 v101, v100, v100
	v_fmac_f32_e32 v99, v98, v98
	v_add_f32_e32 v98, v101, v99
	v_add_f32_e32 v97, v98, v97
	v_mov_b32_e32 v98, v97
	s_nop 1
	v_permlane16_swap_b32_e32 v97, v98
	s_waitcnt lgkmcnt(0)
	v_add_f32_e32 v97, v97, v98
	v_mov_b32_e32 v98, v97
	s_nop 1
	v_permlane32_swap_b32_e32 v97, v98
	s_and_saveexec_b64 s[4:5], vcc
	v_readlane_b32 s27, v254, 25
	s_cbranch_execz .LBB0_444
	s_lshl_b32 s7, s25, 11
	s_add_i32 s7, s6, s7
	v_mul_f32_e32 v96, 0x3c800000, v96
	v_lshl_add_u32 v99, v241, 5, s7
	s_waitcnt lgkmcnt(0)
	v_add_f32_e32 v97, v97, v98
	ds_write_b64 v99, v[96:97] offset:512
; __device__ __forceinline__ float xshfl(float v, int o, int lane) { return __int_as_float(__builtin_amdgcn_ds_bpermute((lane ^ o) << 2, __float_as_int(v))); }
;     __device__ __forceinline__ void run(const f32x4 (&v)[2][2][4][2], const Unit& u, int wr, int wc, int fr, int fq, PG8_LAS unsigned char* lds, int wid, int lane) const {
;     ...
;                 float s = 0.f;
; #pragma unroll
;                 for (int bj = 0; bj < 2; ++bj)
; #pragma unroll
;                     for (int n = 0; n < 2; ++n) { const f32x4 x = v[ai][bj][m][n]; s += (x[0] + x[1]) + (x[2] + x[3]); }
;                 s += xshfl(s, 16, lane); s += xshfl(s, 32, lane);
;                 const float mw = s * (1.0f / 64.0f); float q = 0.f;
; #pragma unroll
;                 for (int bj = 0; bj < 2; ++bj)
; #pragma unroll
;                     for (int n = 0; n < 2; ++n) { const f32x4 d = v[ai][bj][m][n] - mw; q += (d[0] * d[0] + d[1] * d[1]) + (d[2] * d[2] + d[3] * d[3]); }
;                 q += xshfl(q, 16, lane); q += xshfl(q, 32, lane);
;                 if (fq == 0) P[(ai * HALF + wr * 64 + m * 16 + fr) * 4 + wc] = (f32x2v){mw, q};
;     __device__ __forceinline__ void fused(f32x4 (&acc)[2][2][4][2], const Unit& u, int wr, int wc, int fr, int fq, PG8_LAS unsigned char* lds, int wid, int lane) const {
;     ...
;                 float sbr = 0.5f; if (use_rs) sbr = rs[2 * (wr * 64 + fr) + 2 * (ai * HALF + m * 16) + 1];
; #pragma unroll
;                 for (int bj = 0; bj < 2; ++bj)
; #pragma unroll
;                     for (int n = 0; n < 2; ++n) { const unsigned w0 = bw[ai][m][bj][2 * n], w1 = bw[ai][m][bj][2 * n + 1];
;                         const f32x4 bs = {__uint_as_float(w0 << 16), __uint_as_float(w0 & 0xffff0000u), __uint_as_float(w1 << 16), __uint_as_float(w1 & 0xffff0000u)};
;                         acc[ai][bj][m][n] = bs * 1.4142135623730951f + acc[ai][bj][m][n] * sbr; } }
.LBB0_444:
	s_or_b64 exec, exec, s[4:5]
	v_lshlrev_b32_e32 v96, 16, v176
	v_and_b32_e32 v97, 0xffff0000, v176
	s_waitcnt lgkmcnt(0)
	v_lshlrev_b32_e32 v98, 16, v177
	v_and_b32_e32 v99, 0xffff0000, v177
	v_pk_mul_f32 v[94:95], v[94:95], v[238:239] op_sel_hi:[1,0]
	v_pk_mul_f32 v[92:93], v[92:93], v[238:239] op_sel_hi:[1,0]
	s_mov_b32 s4, 0x3fb504f3
	v_pk_fma_f32 v[180:181], v[98:99], s[4:5], v[94:95] op_sel_hi:[1,0,1]
	v_pk_fma_f32 v[182:183], v[96:97], s[4:5], v[92:93] op_sel_hi:[1,0,1]
	v_lshlrev_b32_e32 v92, 16, v178
	v_and_b32_e32 v93, 0xffff0000, v178
	v_lshlrev_b32_e32 v94, 16, v179
	v_and_b32_e32 v95, 0xffff0000, v179
	v_pk_mul_f32 v[90:91], v[90:91], v[238:239] op_sel_hi:[1,0]
	v_pk_mul_f32 v[88:89], v[88:89], v[238:239] op_sel_hi:[1,0]
	v_pk_fma_f32 v[176:177], v[94:95], s[4:5], v[90:91] op_sel_hi:[1,0,1]
	v_pk_fma_f32 v[178:179], v[92:93], s[4:5], v[88:89] op_sel_hi:[1,0,1]
	v_lshlrev_b32_e32 v88, 16, v172
	v_and_b32_e32 v89, 0xffff0000, v172
	v_lshlrev_b32_e32 v90, 16, v173
	v_and_b32_e32 v91, 0xffff0000, v173
	v_pk_mul_f32 v[86:87], v[86:87], v[238:239] op_sel_hi:[1,0]
	v_pk_mul_f32 v[84:85], v[84:85], v[238:239] op_sel_hi:[1,0]
	v_pk_fma_f32 v[96:97], v[90:91], s[4:5], v[86:87] op_sel_hi:[1,0,1]
	v_pk_fma_f32 v[98:99], v[88:89], s[4:5], v[84:85] op_sel_hi:[1,0,1]
	v_lshlrev_b32_e32 v84, 16, v174
	v_and_b32_e32 v85, 0xffff0000, v174
	v_lshlrev_b32_e32 v86, 16, v175
	v_and_b32_e32 v87, 0xffff0000, v175
	v_pk_mul_f32 v[82:83], v[82:83], v[238:239] op_sel_hi:[1,0]
	v_pk_mul_f32 v[80:81], v[80:81], v[238:239] op_sel_hi:[1,0]
	v_pk_fma_f32 v[86:87], v[86:87], s[4:5], v[82:83] op_sel_hi:[1,0,1]
	v_pk_fma_f32 v[90:91], v[84:85], s[4:5], v[80:81] op_sel_hi:[1,0,1]
	v_pk_mov_b32 v[80:81], v[182:183], v[180:181] op_sel:[1,0]
	v_mov_b32_e32 v82, v182
	v_mov_b32_e32 v83, v181
	v_pk_add_f32 v[80:81], v[80:81], v[82:83]
	v_pk_mov_b32 v[82:83], v[178:179], v[176:177] op_sel:[1,0]
	v_mov_b32_e32 v84, v178
	v_mov_b32_e32 v85, v177
	v_pk_add_f32 v[82:83], v[82:83], v[84:85]
	v_add_f32_e32 v80, v80, v81
	v_pk_add_f32 v[82:83], v[82:83], v[82:83] op_sel_hi:[0,1]
	v_add_f32_e32 v81, 0, v80
	v_add_f32_e32 v85, v98, v99
	v_add_f32_e32 v89, v96, v97
	v_mov_b32_e32 v84, v90
	v_mov_b32_e32 v88, v91
	v_mov_b32_e32 v82, v86
	v_mov_b32_e32 v80, v87
	v_pk_add_f32 v[84:85], v[84:85], v[88:89]
	v_pk_add_f32 v[80:81], v[82:83], v[80:81]
	s_nop 0
	v_pk_add_f32 v[80:81], v[84:85], v[80:81]
	s_nop 0
	v_add_f32_e32 v80, v80, v81
	v_mov_b32_e32 v81, v80
	s_nop 1
	v_permlane16_swap_b32_e32 v80, v81
	s_waitcnt lgkmcnt(0)
	v_add_f32_e32 v80, v80, v81
	v_mov_b32_e32 v81, v80
	s_nop 1
	v_permlane32_swap_b32_e32 v80, v81
	s_waitcnt lgkmcnt(0)
	v_add_f32_e32 v80, v80, v81
	v_fmamk_f32 v82, v80, 0xbc800000, v181
	v_fmamk_f32 v84, v80, 0xbc800000, v183
	v_fmamk_f32 v81, v80, 0xbc800000, v180
	v_fmamk_f32 v83, v80, 0xbc800000, v182
	v_mul_f32_e32 v84, v84, v84
	v_mul_f32_e32 v82, v82, v82
	v_fmac_f32_e32 v84, v83, v83
	v_fmac_f32_e32 v82, v81, v81
	v_fmamk_f32 v83, v80, 0xbc800000, v177
	v_fmamk_f32 v85, v80, 0xbc800000, v179
	v_add_f32_e32 v81, v84, v82
	v_fmamk_f32 v82, v80, 0xbc800000, v176
	v_fmamk_f32 v84, v80, 0xbc800000, v178
	v_mul_f32_e32 v85, v85, v85
	v_mul_f32_e32 v83, v83, v83
	v_fmac_f32_e32 v85, v84, v84
	v_fmac_f32_e32 v83, v82, v82
	v_add_f32_e32 v82, v85, v83
	v_fmamk_f32 v83, v80, 0xbc800000, v97
	v_fmamk_f32 v85, v80, 0xbc800000, v99
	v_add_f32_e32 v81, v81, v82
	v_fmamk_f32 v82, v80, 0xbc800000, v96
	v_fmamk_f32 v84, v80, 0xbc800000, v98
	v_mul_f32_e32 v85, v85, v85
	v_mul_f32_e32 v83, v83, v83
	v_fmac_f32_e32 v85, v84, v84
	v_fmac_f32_e32 v83, v82, v82
	v_add_f32_e32 v82, v85, v83
	v_fmamk_f32 v83, v80, 0xbc800000, v87
	v_fmamk_f32 v85, v80, 0xbc800000, v91
	v_add_f32_e32 v81, v82, v81
	v_fmamk_f32 v82, v80, 0xbc800000, v86
	v_fmamk_f32 v84, v80, 0xbc800000, v90
	v_mul_f32_e32 v85, v85, v85
	v_mul_f32_e32 v83, v83, v83
	v_fmac_f32_e32 v85, v84, v84
	v_fmac_f32_e32 v83, v82, v82
	v_add_f32_e32 v82, v85, v83
	v_add_f32_e32 v81, v82, v81
	v_mov_b32_e32 v82, v81
	s_nop 1
	v_permlane16_swap_b32_e32 v81, v82
	s_waitcnt lgkmcnt(0)
	v_add_f32_e32 v81, v81, v82
	v_mov_b32_e32 v82, v81
	s_nop 1
	v_permlane32_swap_b32_e32 v81, v82
	s_and_saveexec_b64 s[4:5], vcc
	s_cbranch_execz .LBB0_446
	s_lshl_b32 s7, s25, 11
	s_add_i32 s7, s6, s7
	v_mul_f32_e32 v80, 0x3c800000, v80
	v_lshl_add_u32 v83, v241, 5, s7
	s_waitcnt lgkmcnt(0)
	v_add_f32_e32 v81, v81, v82
	ds_write_b64 v83, v[80:81] offset:1024
; __device__ __forceinline__ float xshfl(float v, int o, int lane) { return __int_as_float(__builtin_amdgcn_ds_bpermute((lane ^ o) << 2, __float_as_int(v))); }
;     __device__ __forceinline__ void run(const f32x4 (&v)[2][2][4][2], const Unit& u, int wr, int wc, int fr, int fq, PG8_LAS unsigned char* lds, int wid, int lane) const {
;     ...
;                 float s = 0.f;
; #pragma unroll
;                 for (int bj = 0; bj < 2; ++bj)
; #pragma unroll
;                     for (int n = 0; n < 2; ++n) { const f32x4 x = v[ai][bj][m][n]; s += (x[0] + x[1]) + (x[2] + x[3]); }
;                 s += xshfl(s, 16, lane); s += xshfl(s, 32, lane);
;                 const float mw = s * (1.0f / 64.0f); float q = 0.f;
; #pragma unroll
;                 for (int bj = 0; bj < 2; ++bj)
; #pragma unroll
;                     for (int n = 0; n < 2; ++n) { const f32x4 d = v[ai][bj][m][n] - mw; q += (d[0] * d[0] + d[1] * d[1]) + (d[2] * d[2] + d[3] * d[3]); }
;                 q += xshfl(q, 16, lane); q += xshfl(q, 32, lane);
;                 if (fq == 0) P[(ai * HALF + wr * 64 + m * 16 + fr) * 4 + wc] = (f32x2v){mw, q};
;     __device__ __forceinline__ void fused(f32x4 (&acc)[2][2][4][2], const Unit& u, int wr, int wc, int fr, int fq, PG8_LAS unsigned char* lds, int wid, int lane) const {
;     ...
;                 float sbr = 0.5f; if (use_rs) sbr = rs[2 * (wr * 64 + fr) + 2 * (ai * HALF + m * 16) + 1];
; #pragma unroll
;                 for (int bj = 0; bj < 2; ++bj)
; #pragma unroll
;                     for (int n = 0; n < 2; ++n) { const unsigned w0 = bw[ai][m][bj][2 * n], w1 = bw[ai][m][bj][2 * n + 1];
;                         const f32x4 bs = {__uint_as_float(w0 << 16), __uint_as_float(w0 & 0xffff0000u), __uint_as_float(w1 << 16), __uint_as_float(w1 & 0xffff0000u)};
;                         acc[ai][bj][m][n] = bs * 1.4142135623730951f + acc[ai][bj][m][n] * sbr; } }
.LBB0_446:
	s_or_b64 exec, exec, s[4:5]
	v_lshlrev_b32_e32 v80, 16, v168
	v_and_b32_e32 v81, 0xffff0000, v168
	s_waitcnt lgkmcnt(0)
	v_lshlrev_b32_e32 v82, 16, v169
	v_and_b32_e32 v83, 0xffff0000, v169
	v_pk_mul_f32 v[78:79], v[78:79], v[236:237] op_sel_hi:[1,0]
	v_pk_mul_f32 v[76:77], v[76:77], v[236:237] op_sel_hi:[1,0]
	s_mov_b32 s4, 0x3fb504f3
	v_pk_fma_f32 v[172:173], v[82:83], s[4:5], v[78:79] op_sel_hi:[1,0,1]
	v_pk_fma_f32 v[174:175], v[80:81], s[4:5], v[76:77] op_sel_hi:[1,0,1]
	v_lshlrev_b32_e32 v76, 16, v170
	v_and_b32_e32 v77, 0xffff0000, v170
	v_lshlrev_b32_e32 v78, 16, v171
	v_and_b32_e32 v79, 0xffff0000, v171
	v_pk_mul_f32 v[74:75], v[74:75], v[236:237] op_sel_hi:[1,0]
	v_pk_mul_f32 v[72:73], v[72:73], v[236:237] op_sel_hi:[1,0]
	v_pk_fma_f32 v[168:169], v[78:79], s[4:5], v[74:75] op_sel_hi:[1,0,1]
	v_pk_fma_f32 v[170:171], v[76:77], s[4:5], v[72:73] op_sel_hi:[1,0,1]
	v_lshlrev_b32_e32 v72, 16, v164
	v_and_b32_e32 v73, 0xffff0000, v164
	v_lshlrev_b32_e32 v74, 16, v165
	v_and_b32_e32 v75, 0xffff0000, v165
	v_pk_mul_f32 v[70:71], v[70:71], v[236:237] op_sel_hi:[1,0]
	v_pk_mul_f32 v[68:69], v[68:69], v[236:237] op_sel_hi:[1,0]
	v_pk_fma_f32 v[76:77], v[74:75], s[4:5], v[70:71] op_sel_hi:[1,0,1]
	v_pk_fma_f32 v[78:79], v[72:73], s[4:5], v[68:69] op_sel_hi:[1,0,1]
	v_lshlrev_b32_e32 v68, 16, v166
	v_and_b32_e32 v69, 0xffff0000, v166
	v_lshlrev_b32_e32 v70, 16, v167
	v_and_b32_e32 v71, 0xffff0000, v167
	v_pk_mul_f32 v[66:67], v[66:67], v[236:237] op_sel_hi:[1,0]
	v_pk_mul_f32 v[64:65], v[64:65], v[236:237] op_sel_hi:[1,0]
	v_pk_fma_f32 v[72:73], v[70:71], s[4:5], v[66:67] op_sel_hi:[1,0,1]
	v_pk_fma_f32 v[74:75], v[68:69], s[4:5], v[64:65] op_sel_hi:[1,0,1]
	v_pk_mov_b32 v[64:65], v[174:175], v[172:173] op_sel:[1,0]
	v_mov_b32_e32 v66, v174
	v_mov_b32_e32 v67, v173
	v_pk_add_f32 v[64:65], v[64:65], v[66:67]
	v_pk_mov_b32 v[66:67], v[170:171], v[168:169] op_sel:[1,0]
	v_mov_b32_e32 v68, v170
	v_mov_b32_e32 v69, v169
	v_pk_add_f32 v[66:67], v[66:67], v[68:69]
	v_add_f32_e32 v64, v64, v65
	v_pk_add_f32 v[66:67], v[66:67], v[66:67] op_sel_hi:[0,1]
	v_add_f32_e32 v65, 0, v64
	v_add_f32_e32 v69, v78, v79
	v_add_f32_e32 v71, v76, v77
	v_mov_b32_e32 v68, v74
	v_mov_b32_e32 v70, v75
	v_mov_b32_e32 v66, v72
	v_mov_b32_e32 v64, v73
	v_pk_add_f32 v[68:69], v[68:69], v[70:71]
	v_pk_add_f32 v[64:65], v[66:67], v[64:65]
	s_nop 0
	v_pk_add_f32 v[64:65], v[68:69], v[64:65]
	s_nop 0
	v_add_f32_e32 v64, v64, v65
	v_mov_b32_e32 v65, v64
	s_nop 1
	v_permlane16_swap_b32_e32 v64, v65
	s_waitcnt lgkmcnt(0)
	v_add_f32_e32 v64, v64, v65
	v_mov_b32_e32 v65, v64
	s_nop 1
	v_permlane32_swap_b32_e32 v64, v65
	s_waitcnt lgkmcnt(0)
	v_add_f32_e32 v64, v64, v65
	v_fmamk_f32 v66, v64, 0xbc800000, v173
	v_fmamk_f32 v68, v64, 0xbc800000, v175
	v_fmamk_f32 v65, v64, 0xbc800000, v172
	v_fmamk_f32 v67, v64, 0xbc800000, v174
	v_mul_f32_e32 v68, v68, v68
	v_mul_f32_e32 v66, v66, v66
	v_fmac_f32_e32 v68, v67, v67
	v_fmac_f32_e32 v66, v65, v65
	v_fmamk_f32 v67, v64, 0xbc800000, v169
	v_fmamk_f32 v69, v64, 0xbc800000, v171
	v_add_f32_e32 v65, v68, v66
	v_fmamk_f32 v66, v64, 0xbc800000, v168
	v_fmamk_f32 v68, v64, 0xbc800000, v170
	v_mul_f32_e32 v69, v69, v69
	v_mul_f32_e32 v67, v67, v67
	v_fmac_f32_e32 v69, v68, v68
	v_fmac_f32_e32 v67, v66, v66
	v_add_f32_e32 v66, v69, v67
	v_fmamk_f32 v67, v64, 0xbc800000, v77
	v_fmamk_f32 v69, v64, 0xbc800000, v79
	v_add_f32_e32 v65, v65, v66
	v_fmamk_f32 v66, v64, 0xbc800000, v76
	v_fmamk_f32 v68, v64, 0xbc800000, v78
	v_mul_f32_e32 v69, v69, v69
	v_mul_f32_e32 v67, v67, v67
	v_fmac_f32_e32 v69, v68, v68
	v_fmac_f32_e32 v67, v66, v66
	v_add_f32_e32 v66, v69, v67
	v_fmamk_f32 v67, v64, 0xbc800000, v73
	v_fmamk_f32 v69, v64, 0xbc800000, v75
	v_add_f32_e32 v65, v66, v65
	v_fmamk_f32 v66, v64, 0xbc800000, v72
	v_fmamk_f32 v68, v64, 0xbc800000, v74
	v_mul_f32_e32 v69, v69, v69
	v_mul_f32_e32 v67, v67, v67
	v_fmac_f32_e32 v69, v68, v68
	v_fmac_f32_e32 v67, v66, v66
	v_add_f32_e32 v66, v69, v67
	v_add_f32_e32 v65, v66, v65
	v_mov_b32_e32 v66, v65
	s_nop 1
	v_permlane16_swap_b32_e32 v65, v66
	s_waitcnt lgkmcnt(0)
	v_add_f32_e32 v65, v65, v66
	v_mov_b32_e32 v66, v65
	s_nop 1
	v_permlane32_swap_b32_e32 v65, v66
	s_and_saveexec_b64 s[4:5], vcc
	s_cbranch_execz .LBB0_448
	s_lshl_b32 s7, s25, 11
	s_add_i32 s7, s6, s7
	v_mul_f32_e32 v64, 0x3c800000, v64
	v_lshl_add_u32 v67, v241, 5, s7
	s_waitcnt lgkmcnt(0)
	v_add_f32_e32 v65, v65, v66
	ds_write_b64 v67, v[64:65] offset:1536
; __device__ __forceinline__ float xshfl(float v, int o, int lane) { return __int_as_float(__builtin_amdgcn_ds_bpermute((lane ^ o) << 2, __float_as_int(v))); }
;     __device__ __forceinline__ void run(const f32x4 (&v)[2][2][4][2], const Unit& u, int wr, int wc, int fr, int fq, PG8_LAS unsigned char* lds, int wid, int lane) const {
;     ...
;                 float s = 0.f;
; #pragma unroll
;                 for (int bj = 0; bj < 2; ++bj)
; #pragma unroll
;                     for (int n = 0; n < 2; ++n) { const f32x4 x = v[ai][bj][m][n]; s += (x[0] + x[1]) + (x[2] + x[3]); }
;                 s += xshfl(s, 16, lane); s += xshfl(s, 32, lane);
;                 const float mw = s * (1.0f / 64.0f); float q = 0.f;
; #pragma unroll
;                 for (int bj = 0; bj < 2; ++bj)
; #pragma unroll
;                     for (int n = 0; n < 2; ++n) { const f32x4 d = v[ai][bj][m][n] - mw; q += (d[0] * d[0] + d[1] * d[1]) + (d[2] * d[2] + d[3] * d[3]); }
;                 q += xshfl(q, 16, lane); q += xshfl(q, 32, lane);
;                 if (fq == 0) P[(ai * HALF + wr * 64 + m * 16 + fr) * 4 + wc] = (f32x2v){mw, q};
;     __device__ __forceinline__ void fused(f32x4 (&acc)[2][2][4][2], const Unit& u, int wr, int wc, int fr, int fq, PG8_LAS unsigned char* lds, int wid, int lane) const {
;     ...
;                 float sbr = 0.5f; if (use_rs) sbr = rs[2 * (wr * 64 + fr) + 2 * (ai * HALF + m * 16) + 1];
; #pragma unroll
;                 for (int bj = 0; bj < 2; ++bj)
; #pragma unroll
;                     for (int n = 0; n < 2; ++n) { const unsigned w0 = bw[ai][m][bj][2 * n], w1 = bw[ai][m][bj][2 * n + 1];
;                         const f32x4 bs = {__uint_as_float(w0 << 16), __uint_as_float(w0 & 0xffff0000u), __uint_as_float(w1 << 16), __uint_as_float(w1 & 0xffff0000u)};
;                         acc[ai][bj][m][n] = bs * 1.4142135623730951f + acc[ai][bj][m][n] * sbr; } }
.LBB0_448:
	s_or_b64 exec, exec, s[4:5]
	v_lshlrev_b32_e32 v64, 16, v160
	v_and_b32_e32 v65, 0xffff0000, v160
	s_waitcnt lgkmcnt(0)
	v_lshlrev_b32_e32 v66, 16, v161
	v_and_b32_e32 v67, 0xffff0000, v161
	v_pk_mul_f32 v[62:63], v[62:63], v[234:235] op_sel_hi:[1,0]
	v_pk_mul_f32 v[60:61], v[60:61], v[234:235] op_sel_hi:[1,0]
	s_mov_b32 s4, 0x3fb504f3
	v_pk_fma_f32 v[128:129], v[66:67], s[4:5], v[62:63] op_sel_hi:[1,0,1]
	v_pk_fma_f32 v[130:131], v[64:65], s[4:5], v[60:61] op_sel_hi:[1,0,1]
	v_lshlrev_b32_e32 v60, 16, v162
	v_and_b32_e32 v61, 0xffff0000, v162
	v_lshlrev_b32_e32 v62, 16, v163
	v_and_b32_e32 v63, 0xffff0000, v163
	v_pk_mul_f32 v[58:59], v[58:59], v[234:235] op_sel_hi:[1,0]
	v_pk_mul_f32 v[56:57], v[56:57], v[234:235] op_sel_hi:[1,0]
	v_pk_fma_f32 v[124:125], v[62:63], s[4:5], v[58:59] op_sel_hi:[1,0,1]
	v_pk_fma_f32 v[126:127], v[60:61], s[4:5], v[56:57] op_sel_hi:[1,0,1]
	v_lshlrev_b32_e32 v56, 16, v156
	v_and_b32_e32 v57, 0xffff0000, v156
	v_lshlrev_b32_e32 v58, 16, v157
	v_and_b32_e32 v59, 0xffff0000, v157
	v_pk_mul_f32 v[54:55], v[54:55], v[234:235] op_sel_hi:[1,0]
	v_pk_mul_f32 v[52:53], v[52:53], v[234:235] op_sel_hi:[1,0]
	v_pk_fma_f32 v[68:69], v[58:59], s[4:5], v[54:55] op_sel_hi:[1,0,1]
	v_pk_fma_f32 v[70:71], v[56:57], s[4:5], v[52:53] op_sel_hi:[1,0,1]
	v_lshlrev_b32_e32 v52, 16, v158
	v_and_b32_e32 v53, 0xffff0000, v158
	v_lshlrev_b32_e32 v54, 16, v159
	v_and_b32_e32 v55, 0xffff0000, v159
	v_pk_mul_f32 v[50:51], v[50:51], v[234:235] op_sel_hi:[1,0]
	v_pk_mul_f32 v[48:49], v[48:49], v[234:235] op_sel_hi:[1,0]
	v_pk_fma_f32 v[64:65], v[54:55], s[4:5], v[50:51] op_sel_hi:[1,0,1]
	v_pk_fma_f32 v[66:67], v[52:53], s[4:5], v[48:49] op_sel_hi:[1,0,1]
	v_pk_mov_b32 v[48:49], v[130:131], v[128:129] op_sel:[1,0]
	v_mov_b32_e32 v50, v130
	v_mov_b32_e32 v51, v129
	v_pk_add_f32 v[48:49], v[48:49], v[50:51]
	v_pk_mov_b32 v[50:51], v[126:127], v[124:125] op_sel:[1,0]
	v_mov_b32_e32 v52, v126
	v_mov_b32_e32 v53, v125
	v_pk_add_f32 v[50:51], v[50:51], v[52:53]
	v_add_f32_e32 v48, v48, v49
	v_pk_add_f32 v[50:51], v[50:51], v[50:51] op_sel_hi:[0,1]
	v_add_f32_e32 v49, 0, v48
	v_add_f32_e32 v53, v70, v71
	v_add_f32_e32 v55, v68, v69
	v_mov_b32_e32 v52, v66
	v_mov_b32_e32 v54, v67
	v_mov_b32_e32 v50, v64
	v_mov_b32_e32 v48, v65
	v_pk_add_f32 v[52:53], v[52:53], v[54:55]
	v_pk_add_f32 v[48:49], v[50:51], v[48:49]
	s_nop 0
	v_pk_add_f32 v[48:49], v[52:53], v[48:49]
	s_nop 0
	v_add_f32_e32 v48, v48, v49
	v_mov_b32_e32 v49, v48
	s_nop 1
	v_permlane16_swap_b32_e32 v48, v49
	s_waitcnt lgkmcnt(0)
	v_add_f32_e32 v48, v48, v49
	v_mov_b32_e32 v49, v48
	s_nop 1
	v_permlane32_swap_b32_e32 v48, v49
	s_waitcnt lgkmcnt(0)
	v_add_f32_e32 v48, v48, v49
	v_fmamk_f32 v50, v48, 0xbc800000, v129
	v_fmamk_f32 v52, v48, 0xbc800000, v131
	v_fmamk_f32 v49, v48, 0xbc800000, v128
	v_fmamk_f32 v51, v48, 0xbc800000, v130
	v_mul_f32_e32 v52, v52, v52
	v_mul_f32_e32 v50, v50, v50
	v_fmac_f32_e32 v52, v51, v51
	v_fmac_f32_e32 v50, v49, v49
	v_fmamk_f32 v51, v48, 0xbc800000, v125
	v_fmamk_f32 v53, v48, 0xbc800000, v127
	v_add_f32_e32 v49, v52, v50
	v_fmamk_f32 v50, v48, 0xbc800000, v124
	v_fmamk_f32 v52, v48, 0xbc800000, v126
	v_mul_f32_e32 v53, v53, v53
	v_mul_f32_e32 v51, v51, v51
	v_fmac_f32_e32 v53, v52, v52
	v_fmac_f32_e32 v51, v50, v50
	v_add_f32_e32 v50, v53, v51
	v_fmamk_f32 v51, v48, 0xbc800000, v69
	v_fmamk_f32 v53, v48, 0xbc800000, v71
	v_add_f32_e32 v49, v49, v50
	v_fmamk_f32 v50, v48, 0xbc800000, v68
	v_fmamk_f32 v52, v48, 0xbc800000, v70
	v_mul_f32_e32 v53, v53, v53
	v_mul_f32_e32 v51, v51, v51
	v_fmac_f32_e32 v53, v52, v52
	v_fmac_f32_e32 v51, v50, v50
	v_add_f32_e32 v50, v53, v51
	v_fmamk_f32 v51, v48, 0xbc800000, v65
	v_fmamk_f32 v53, v48, 0xbc800000, v67
	v_add_f32_e32 v49, v50, v49
	v_fmamk_f32 v50, v48, 0xbc800000, v64
	v_fmamk_f32 v52, v48, 0xbc800000, v66
	v_mul_f32_e32 v53, v53, v53
	v_mul_f32_e32 v51, v51, v51
	v_fmac_f32_e32 v53, v52, v52
	v_fmac_f32_e32 v51, v50, v50
	v_add_f32_e32 v50, v53, v51
	v_add_f32_e32 v49, v50, v49
	v_mov_b32_e32 v50, v49
	s_nop 1
	v_permlane16_swap_b32_e32 v49, v50
	s_waitcnt lgkmcnt(0)
	v_add_f32_e32 v49, v49, v50
	v_mov_b32_e32 v50, v49
	s_nop 1
	v_permlane32_swap_b32_e32 v49, v50
	s_and_saveexec_b64 s[4:5], vcc
	s_cbranch_execz .LBB0_450
	s_lshl_b32 s7, s25, 11
	s_add_i32 s7, s6, s7
	v_mul_f32_e32 v48, 0x3c800000, v48
	v_lshl_add_u32 v51, v241, 5, s7
	s_waitcnt lgkmcnt(0)
	v_add_f32_e32 v49, v49, v50
	ds_write_b64 v51, v[48:49] offset:4096
; __device__ __forceinline__ float xshfl(float v, int o, int lane) { return __int_as_float(__builtin_amdgcn_ds_bpermute((lane ^ o) << 2, __float_as_int(v))); }
;     __device__ __forceinline__ void run(const f32x4 (&v)[2][2][4][2], const Unit& u, int wr, int wc, int fr, int fq, PG8_LAS unsigned char* lds, int wid, int lane) const {
;     ...
;                 float s = 0.f;
; #pragma unroll
;                 for (int bj = 0; bj < 2; ++bj)
; #pragma unroll
;                     for (int n = 0; n < 2; ++n) { const f32x4 x = v[ai][bj][m][n]; s += (x[0] + x[1]) + (x[2] + x[3]); }
;                 s += xshfl(s, 16, lane); s += xshfl(s, 32, lane);
;                 const float mw = s * (1.0f / 64.0f); float q = 0.f;
; #pragma unroll
;                 for (int bj = 0; bj < 2; ++bj)
; #pragma unroll
;                     for (int n = 0; n < 2; ++n) { const f32x4 d = v[ai][bj][m][n] - mw; q += (d[0] * d[0] + d[1] * d[1]) + (d[2] * d[2] + d[3] * d[3]); }
;                 q += xshfl(q, 16, lane); q += xshfl(q, 32, lane);
;                 if (fq == 0) P[(ai * HALF + wr * 64 + m * 16 + fr) * 4 + wc] = (f32x2v){mw, q};
;     __device__ __forceinline__ void fused(f32x4 (&acc)[2][2][4][2], const Unit& u, int wr, int wc, int fr, int fq, PG8_LAS unsigned char* lds, int wid, int lane) const {
;     ...
;                 float sbr = 0.5f; if (use_rs) sbr = rs[2 * (wr * 64 + fr) + 2 * (ai * HALF + m * 16) + 1];
; #pragma unroll
;                 for (int bj = 0; bj < 2; ++bj)
; #pragma unroll
;                     for (int n = 0; n < 2; ++n) { const unsigned w0 = bw[ai][m][bj][2 * n], w1 = bw[ai][m][bj][2 * n + 1];
;                         const f32x4 bs = {__uint_as_float(w0 << 16), __uint_as_float(w0 & 0xffff0000u), __uint_as_float(w1 << 16), __uint_as_float(w1 & 0xffff0000u)};
;                         acc[ai][bj][m][n] = bs * 1.4142135623730951f + acc[ai][bj][m][n] * sbr; } }
.LBB0_450:
	s_or_b64 exec, exec, s[4:5]
	v_lshlrev_b32_e32 v48, 16, v152
	v_and_b32_e32 v49, 0xffff0000, v152
	s_waitcnt lgkmcnt(0)
	v_lshlrev_b32_e32 v50, 16, v153
	v_and_b32_e32 v51, 0xffff0000, v153
	v_pk_mul_f32 v[46:47], v[46:47], v[232:233] op_sel_hi:[1,0]
	v_pk_mul_f32 v[44:45], v[44:45], v[232:233] op_sel_hi:[1,0]
	s_mov_b32 s4, 0x3fb504f3
	v_pk_fma_f32 v[118:119], v[50:51], s[4:5], v[46:47] op_sel_hi:[1,0,1]
	v_pk_fma_f32 v[122:123], v[48:49], s[4:5], v[44:45] op_sel_hi:[1,0,1]
	v_lshlrev_b32_e32 v44, 16, v154
	v_and_b32_e32 v45, 0xffff0000, v154
	v_lshlrev_b32_e32 v46, 16, v155
	v_and_b32_e32 v47, 0xffff0000, v155
	v_pk_mul_f32 v[42:43], v[42:43], v[232:233] op_sel_hi:[1,0]
	v_pk_mul_f32 v[40:41], v[40:41], v[232:233] op_sel_hi:[1,0]
	v_pk_fma_f32 v[108:109], v[46:47], s[4:5], v[42:43] op_sel_hi:[1,0,1]
	v_pk_fma_f32 v[110:111], v[44:45], s[4:5], v[40:41] op_sel_hi:[1,0,1]
	v_lshlrev_b32_e32 v40, 16, v148
	v_and_b32_e32 v41, 0xffff0000, v148
	v_lshlrev_b32_e32 v42, 16, v149
	v_and_b32_e32 v43, 0xffff0000, v149
	v_pk_mul_f32 v[38:39], v[38:39], v[232:233] op_sel_hi:[1,0]
	v_pk_mul_f32 v[36:37], v[36:37], v[232:233] op_sel_hi:[1,0]
	v_pk_fma_f32 v[60:61], v[42:43], s[4:5], v[38:39] op_sel_hi:[1,0,1]
	v_pk_fma_f32 v[62:63], v[40:41], s[4:5], v[36:37] op_sel_hi:[1,0,1]
	v_lshlrev_b32_e32 v36, 16, v150
	v_and_b32_e32 v37, 0xffff0000, v150
	v_lshlrev_b32_e32 v38, 16, v151
	v_and_b32_e32 v39, 0xffff0000, v151
	v_pk_mul_f32 v[34:35], v[34:35], v[232:233] op_sel_hi:[1,0]
	v_pk_mul_f32 v[32:33], v[32:33], v[232:233] op_sel_hi:[1,0]
	v_pk_fma_f32 v[56:57], v[38:39], s[4:5], v[34:35] op_sel_hi:[1,0,1]
	v_pk_fma_f32 v[58:59], v[36:37], s[4:5], v[32:33] op_sel_hi:[1,0,1]
	v_pk_mov_b32 v[32:33], v[122:123], v[118:119] op_sel:[1,0]
	v_mov_b32_e32 v34, v122
	v_mov_b32_e32 v35, v119
	v_pk_add_f32 v[32:33], v[32:33], v[34:35]
	v_pk_mov_b32 v[34:35], v[110:111], v[108:109] op_sel:[1,0]
	v_mov_b32_e32 v36, v110
	v_mov_b32_e32 v37, v109
	v_pk_add_f32 v[34:35], v[34:35], v[36:37]
	v_add_f32_e32 v32, v32, v33
	v_pk_add_f32 v[34:35], v[34:35], v[34:35] op_sel_hi:[0,1]
	v_add_f32_e32 v33, 0, v32
	v_add_f32_e32 v37, v62, v63
	v_add_f32_e32 v39, v60, v61
	v_mov_b32_e32 v36, v58
	v_mov_b32_e32 v38, v59
	v_mov_b32_e32 v34, v56
	v_mov_b32_e32 v32, v57
	v_pk_add_f32 v[36:37], v[36:37], v[38:39]
	v_pk_add_f32 v[32:33], v[34:35], v[32:33]
	s_nop 0
	v_pk_add_f32 v[32:33], v[36:37], v[32:33]
	s_nop 0
	v_add_f32_e32 v32, v32, v33
	v_mov_b32_e32 v33, v32
	s_nop 1
	v_permlane16_swap_b32_e32 v32, v33
	s_waitcnt lgkmcnt(0)
	v_add_f32_e32 v32, v32, v33
	v_mov_b32_e32 v33, v32
	s_nop 1
	v_permlane32_swap_b32_e32 v32, v33
	s_waitcnt lgkmcnt(0)
	v_add_f32_e32 v32, v32, v33
	v_fmamk_f32 v34, v32, 0xbc800000, v119
	v_fmamk_f32 v36, v32, 0xbc800000, v123
	v_fmamk_f32 v33, v32, 0xbc800000, v118
	v_fmamk_f32 v35, v32, 0xbc800000, v122
	v_mul_f32_e32 v36, v36, v36
	v_mul_f32_e32 v34, v34, v34
	v_fmac_f32_e32 v36, v35, v35
	v_fmac_f32_e32 v34, v33, v33
	v_fmamk_f32 v35, v32, 0xbc800000, v109
	v_fmamk_f32 v37, v32, 0xbc800000, v111
	v_add_f32_e32 v33, v36, v34
	v_fmamk_f32 v34, v32, 0xbc800000, v108
	v_fmamk_f32 v36, v32, 0xbc800000, v110
	v_mul_f32_e32 v37, v37, v37
	v_mul_f32_e32 v35, v35, v35
	v_fmac_f32_e32 v37, v36, v36
	v_fmac_f32_e32 v35, v34, v34
	v_add_f32_e32 v34, v37, v35
	v_fmamk_f32 v35, v32, 0xbc800000, v61
	v_fmamk_f32 v37, v32, 0xbc800000, v63
	v_add_f32_e32 v33, v33, v34
	v_fmamk_f32 v34, v32, 0xbc800000, v60
	v_fmamk_f32 v36, v32, 0xbc800000, v62
	v_mul_f32_e32 v37, v37, v37
	v_mul_f32_e32 v35, v35, v35
	v_fmac_f32_e32 v37, v36, v36
	v_fmac_f32_e32 v35, v34, v34
	v_add_f32_e32 v34, v37, v35
	v_fmamk_f32 v35, v32, 0xbc800000, v57
	v_fmamk_f32 v37, v32, 0xbc800000, v59
	v_add_f32_e32 v33, v34, v33
	v_fmamk_f32 v34, v32, 0xbc800000, v56
	v_fmamk_f32 v36, v32, 0xbc800000, v58
	v_mul_f32_e32 v37, v37, v37
	v_mul_f32_e32 v35, v35, v35
	v_fmac_f32_e32 v37, v36, v36
	v_fmac_f32_e32 v35, v34, v34
	v_add_f32_e32 v34, v37, v35
	v_add_f32_e32 v33, v34, v33
	v_mov_b32_e32 v34, v33
	s_nop 1
	v_permlane16_swap_b32_e32 v33, v34
	s_waitcnt lgkmcnt(0)
	v_add_f32_e32 v33, v33, v34
	v_mov_b32_e32 v34, v33
	s_nop 1
	v_permlane32_swap_b32_e32 v33, v34
	s_and_saveexec_b64 s[4:5], vcc
	s_cbranch_execz .LBB0_452
	s_lshl_b32 s7, s25, 11
	s_add_i32 s7, s6, s7
	v_mul_f32_e32 v32, 0x3c800000, v32
	v_lshl_add_u32 v35, v241, 5, s7
	s_waitcnt lgkmcnt(0)
	v_add_f32_e32 v33, v33, v34
	ds_write_b64 v35, v[32:33] offset:4608
; __device__ __forceinline__ float xshfl(float v, int o, int lane) { return __int_as_float(__builtin_amdgcn_ds_bpermute((lane ^ o) << 2, __float_as_int(v))); }
;     __device__ __forceinline__ void run(const f32x4 (&v)[2][2][4][2], const Unit& u, int wr, int wc, int fr, int fq, PG8_LAS unsigned char* lds, int wid, int lane) const {
;     ...
;                 float s = 0.f;
; #pragma unroll
;                 for (int bj = 0; bj < 2; ++bj)
; #pragma unroll
;                     for (int n = 0; n < 2; ++n) { const f32x4 x = v[ai][bj][m][n]; s += (x[0] + x[1]) + (x[2] + x[3]); }
;                 s += xshfl(s, 16, lane); s += xshfl(s, 32, lane);
;                 const float mw = s * (1.0f / 64.0f); float q = 0.f;
; #pragma unroll
;                 for (int bj = 0; bj < 2; ++bj)
; #pragma unroll
;                     for (int n = 0; n < 2; ++n) { const f32x4 d = v[ai][bj][m][n] - mw; q += (d[0] * d[0] + d[1] * d[1]) + (d[2] * d[2] + d[3] * d[3]); }
;                 q += xshfl(q, 16, lane); q += xshfl(q, 32, lane);
;                 if (fq == 0) P[(ai * HALF + wr * 64 + m * 16 + fr) * 4 + wc] = (f32x2v){mw, q};
;     __device__ __forceinline__ void fused(f32x4 (&acc)[2][2][4][2], const Unit& u, int wr, int wc, int fr, int fq, PG8_LAS unsigned char* lds, int wid, int lane) const {
;     ...
;                 float sbr = 0.5f; if (use_rs) sbr = rs[2 * (wr * 64 + fr) + 2 * (ai * HALF + m * 16) + 1];
; #pragma unroll
;                 for (int bj = 0; bj < 2; ++bj)
; #pragma unroll
;                     for (int n = 0; n < 2; ++n) { const unsigned w0 = bw[ai][m][bj][2 * n], w1 = bw[ai][m][bj][2 * n + 1];
;                         const f32x4 bs = {__uint_as_float(w0 << 16), __uint_as_float(w0 & 0xffff0000u), __uint_as_float(w1 << 16), __uint_as_float(w1 & 0xffff0000u)};
;                         acc[ai][bj][m][n] = bs * 1.4142135623730951f + acc[ai][bj][m][n] * sbr; } }
.LBB0_452:
	s_or_b64 exec, exec, s[4:5]
	v_lshlrev_b32_e32 v32, 16, v144
	v_and_b32_e32 v33, 0xffff0000, v144
	s_waitcnt lgkmcnt(0)
	v_lshlrev_b32_e32 v34, 16, v145
	v_and_b32_e32 v35, 0xffff0000, v145
	v_pk_mul_f32 v[30:31], v[30:31], v[230:231] op_sel_hi:[1,0]
	v_pk_mul_f32 v[28:29], v[28:29], v[230:231] op_sel_hi:[1,0]
	s_mov_b32 s4, 0x3fb504f3
	v_pk_fma_f32 v[100:101], v[34:35], s[4:5], v[30:31] op_sel_hi:[1,0,1]
	v_pk_fma_f32 v[102:103], v[32:33], s[4:5], v[28:29] op_sel_hi:[1,0,1]
	v_lshlrev_b32_e32 v28, 16, v146
	v_and_b32_e32 v29, 0xffff0000, v146
	v_lshlrev_b32_e32 v30, 16, v147
	v_and_b32_e32 v31, 0xffff0000, v147
	v_pk_mul_f32 v[26:27], v[26:27], v[230:231] op_sel_hi:[1,0]
	v_pk_mul_f32 v[24:25], v[24:25], v[230:231] op_sel_hi:[1,0]
	v_pk_fma_f32 v[92:93], v[30:31], s[4:5], v[26:27] op_sel_hi:[1,0,1]
	v_pk_fma_f32 v[94:95], v[28:29], s[4:5], v[24:25] op_sel_hi:[1,0,1]
	v_lshlrev_b32_e32 v24, 16, v140
	v_and_b32_e32 v25, 0xffff0000, v140
	v_lshlrev_b32_e32 v26, 16, v141
	v_and_b32_e32 v27, 0xffff0000, v141
	v_pk_mul_f32 v[22:23], v[22:23], v[230:231] op_sel_hi:[1,0]
	v_pk_mul_f32 v[20:21], v[20:21], v[230:231] op_sel_hi:[1,0]
	v_pk_fma_f32 v[52:53], v[26:27], s[4:5], v[22:23] op_sel_hi:[1,0,1]
	v_pk_fma_f32 v[54:55], v[24:25], s[4:5], v[20:21] op_sel_hi:[1,0,1]
	v_lshlrev_b32_e32 v20, 16, v142
	v_and_b32_e32 v21, 0xffff0000, v142
	v_lshlrev_b32_e32 v22, 16, v143
	v_and_b32_e32 v23, 0xffff0000, v143
	v_pk_mul_f32 v[18:19], v[18:19], v[230:231] op_sel_hi:[1,0]
	v_pk_mul_f32 v[16:17], v[16:17], v[230:231] op_sel_hi:[1,0]
	v_pk_fma_f32 v[48:49], v[22:23], s[4:5], v[18:19] op_sel_hi:[1,0,1]
	v_pk_fma_f32 v[50:51], v[20:21], s[4:5], v[16:17] op_sel_hi:[1,0,1]
	v_pk_mov_b32 v[16:17], v[102:103], v[100:101] op_sel:[1,0]
	v_mov_b32_e32 v18, v102
	v_mov_b32_e32 v19, v101
	v_pk_add_f32 v[16:17], v[16:17], v[18:19]
	v_pk_mov_b32 v[18:19], v[94:95], v[92:93] op_sel:[1,0]
	v_mov_b32_e32 v20, v94
	v_mov_b32_e32 v21, v93
	v_pk_add_f32 v[18:19], v[18:19], v[20:21]
	v_add_f32_e32 v16, v16, v17
	v_pk_add_f32 v[18:19], v[18:19], v[18:19] op_sel_hi:[0,1]
	v_add_f32_e32 v17, 0, v16
	v_add_f32_e32 v21, v54, v55
	v_add_f32_e32 v23, v52, v53
	v_mov_b32_e32 v20, v50
	v_mov_b32_e32 v22, v51
	v_mov_b32_e32 v18, v48
	v_mov_b32_e32 v16, v49
	v_pk_add_f32 v[20:21], v[20:21], v[22:23]
	v_pk_add_f32 v[16:17], v[18:19], v[16:17]
	s_nop 0
	v_pk_add_f32 v[16:17], v[20:21], v[16:17]
	s_nop 0
	v_add_f32_e32 v16, v16, v17
	v_mov_b32_e32 v17, v16
	s_nop 1
	v_permlane16_swap_b32_e32 v16, v17
	s_waitcnt lgkmcnt(0)
	v_add_f32_e32 v16, v16, v17
	v_mov_b32_e32 v17, v16
	s_nop 1
	v_permlane32_swap_b32_e32 v16, v17
	s_waitcnt lgkmcnt(0)
	v_add_f32_e32 v16, v16, v17
	v_fmamk_f32 v18, v16, 0xbc800000, v101
	v_fmamk_f32 v20, v16, 0xbc800000, v103
	v_fmamk_f32 v17, v16, 0xbc800000, v100
	v_fmamk_f32 v19, v16, 0xbc800000, v102
	v_mul_f32_e32 v20, v20, v20
	v_mul_f32_e32 v18, v18, v18
	v_fmac_f32_e32 v20, v19, v19
	v_fmac_f32_e32 v18, v17, v17
	v_fmamk_f32 v19, v16, 0xbc800000, v93
	v_fmamk_f32 v21, v16, 0xbc800000, v95
	v_add_f32_e32 v17, v20, v18
	v_fmamk_f32 v18, v16, 0xbc800000, v92
	v_fmamk_f32 v20, v16, 0xbc800000, v94
	v_mul_f32_e32 v21, v21, v21
	v_mul_f32_e32 v19, v19, v19
	v_fmac_f32_e32 v21, v20, v20
	v_fmac_f32_e32 v19, v18, v18
	v_add_f32_e32 v18, v21, v19
	v_fmamk_f32 v19, v16, 0xbc800000, v53
	v_fmamk_f32 v21, v16, 0xbc800000, v55
	v_add_f32_e32 v17, v17, v18
	v_fmamk_f32 v18, v16, 0xbc800000, v52
	v_fmamk_f32 v20, v16, 0xbc800000, v54
	v_mul_f32_e32 v21, v21, v21
	v_mul_f32_e32 v19, v19, v19
	v_fmac_f32_e32 v21, v20, v20
	v_fmac_f32_e32 v19, v18, v18
	v_add_f32_e32 v18, v21, v19
	v_fmamk_f32 v19, v16, 0xbc800000, v49
	v_fmamk_f32 v21, v16, 0xbc800000, v51
	v_add_f32_e32 v17, v18, v17
	v_fmamk_f32 v18, v16, 0xbc800000, v48
	v_fmamk_f32 v20, v16, 0xbc800000, v50
	v_mul_f32_e32 v21, v21, v21
	v_mul_f32_e32 v19, v19, v19
	v_fmac_f32_e32 v21, v20, v20
	v_fmac_f32_e32 v19, v18, v18
	v_add_f32_e32 v18, v21, v19
	v_add_f32_e32 v17, v18, v17
	v_mov_b32_e32 v18, v17
	s_nop 1
	v_permlane16_swap_b32_e32 v17, v18
	s_waitcnt lgkmcnt(0)
	v_add_f32_e32 v17, v17, v18
	v_mov_b32_e32 v18, v17
	s_nop 1
	v_permlane32_swap_b32_e32 v17, v18
	s_and_saveexec_b64 s[4:5], vcc
	s_cbranch_execz .LBB0_454
	s_lshl_b32 s7, s25, 11
	s_add_i32 s7, s6, s7
	v_mul_f32_e32 v16, 0x3c800000, v16
	v_lshl_add_u32 v19, v241, 5, s7
	s_waitcnt lgkmcnt(0)
	v_add_f32_e32 v17, v17, v18
	ds_write_b64 v19, v[16:17] offset:5120
; __device__ __forceinline__ float xshfl(float v, int o, int lane) { return __int_as_float(__builtin_amdgcn_ds_bpermute((lane ^ o) << 2, __float_as_int(v))); }
;     __device__ __forceinline__ void run(const f32x4 (&v)[2][2][4][2], const Unit& u, int wr, int wc, int fr, int fq, PG8_LAS unsigned char* lds, int wid, int lane) const {
;     ...
;                 float s = 0.f;
; #pragma unroll
;                 for (int bj = 0; bj < 2; ++bj)
; #pragma unroll
;                     for (int n = 0; n < 2; ++n) { const f32x4 x = v[ai][bj][m][n]; s += (x[0] + x[1]) + (x[2] + x[3]); }
;                 s += xshfl(s, 16, lane); s += xshfl(s, 32, lane);
;                 const float mw = s * (1.0f / 64.0f); float q = 0.f;
; #pragma unroll
;                 for (int bj = 0; bj < 2; ++bj)
; #pragma unroll
;                     for (int n = 0; n < 2; ++n) { const f32x4 d = v[ai][bj][m][n] - mw; q += (d[0] * d[0] + d[1] * d[1]) + (d[2] * d[2] + d[3] * d[3]); }
;                 q += xshfl(q, 16, lane); q += xshfl(q, 32, lane);
;                 if (fq == 0) P[(ai * HALF + wr * 64 + m * 16 + fr) * 4 + wc] = (f32x2v){mw, q};
;     __device__ __forceinline__ void fused(f32x4 (&acc)[2][2][4][2], const Unit& u, int wr, int wc, int fr, int fq, PG8_LAS unsigned char* lds, int wid, int lane) const {
;     ...
;                 float sbr = 0.5f; if (use_rs) sbr = rs[2 * (wr * 64 + fr) + 2 * (ai * HALF + m * 16) + 1];
; #pragma unroll
;                 for (int bj = 0; bj < 2; ++bj)
; #pragma unroll
;                     for (int n = 0; n < 2; ++n) { const unsigned w0 = bw[ai][m][bj][2 * n], w1 = bw[ai][m][bj][2 * n + 1];
;                         const f32x4 bs = {__uint_as_float(w0 << 16), __uint_as_float(w0 & 0xffff0000u), __uint_as_float(w1 << 16), __uint_as_float(w1 & 0xffff0000u)};
;                         acc[ai][bj][m][n] = bs * 1.4142135623730951f + acc[ai][bj][m][n] * sbr; } }
.LBB0_454:
	s_or_b64 exec, exec, s[4:5]
	v_lshlrev_b32_e32 v16, 16, v136
	v_and_b32_e32 v17, 0xffff0000, v136
	s_waitcnt lgkmcnt(0)
	v_lshlrev_b32_e32 v18, 16, v137
	v_and_b32_e32 v19, 0xffff0000, v137
	v_pk_mul_f32 v[14:15], v[14:15], v[112:113] op_sel_hi:[1,0]
	v_pk_mul_f32 v[12:13], v[12:13], v[112:113] op_sel_hi:[1,0]
	s_mov_b32 s4, 0x3fb504f3
	v_pk_fma_f32 v[84:85], v[18:19], s[4:5], v[14:15] op_sel_hi:[1,0,1]
	v_pk_fma_f32 v[88:89], v[16:17], s[4:5], v[12:13] op_sel_hi:[1,0,1]
	v_lshlrev_b32_e32 v12, 16, v138
	v_and_b32_e32 v13, 0xffff0000, v138
	v_lshlrev_b32_e32 v14, 16, v139
	v_and_b32_e32 v15, 0xffff0000, v139
	v_pk_mul_f32 v[10:11], v[10:11], v[112:113] op_sel_hi:[1,0]
	v_pk_mul_f32 v[8:9], v[8:9], v[112:113] op_sel_hi:[1,0]
	v_pk_fma_f32 v[80:81], v[14:15], s[4:5], v[10:11] op_sel_hi:[1,0,1]
	v_pk_fma_f32 v[82:83], v[12:13], s[4:5], v[8:9] op_sel_hi:[1,0,1]
	v_lshlrev_b32_e32 v8, 16, v132
	v_and_b32_e32 v9, 0xffff0000, v132
	v_lshlrev_b32_e32 v10, 16, v133
	v_and_b32_e32 v11, 0xffff0000, v133
	v_pk_mul_f32 v[6:7], v[6:7], v[112:113] op_sel_hi:[1,0]
	v_pk_mul_f32 v[4:5], v[4:5], v[112:113] op_sel_hi:[1,0]
	v_pk_fma_f32 v[44:45], v[10:11], s[4:5], v[6:7] op_sel_hi:[1,0,1]
	v_pk_fma_f32 v[46:47], v[8:9], s[4:5], v[4:5] op_sel_hi:[1,0,1]
	v_lshlrev_b32_e32 v4, 16, v134
	v_and_b32_e32 v5, 0xffff0000, v134
	v_lshlrev_b32_e32 v6, 16, v135
	v_and_b32_e32 v7, 0xffff0000, v135
	v_pk_mul_f32 v[2:3], v[2:3], v[112:113] op_sel_hi:[1,0]
	v_pk_mul_f32 v[0:1], v[0:1], v[112:113] op_sel_hi:[1,0]
	v_pk_fma_f32 v[40:41], v[6:7], s[4:5], v[2:3] op_sel_hi:[1,0,1]
	v_pk_fma_f32 v[42:43], v[4:5], s[4:5], v[0:1] op_sel_hi:[1,0,1]
	v_pk_mov_b32 v[0:1], v[88:89], v[84:85] op_sel:[1,0]
	v_mov_b32_e32 v2, v88
	v_mov_b32_e32 v3, v85
	v_pk_add_f32 v[0:1], v[0:1], v[2:3]
	v_pk_mov_b32 v[2:3], v[82:83], v[80:81] op_sel:[1,0]
	v_mov_b32_e32 v4, v82
	v_mov_b32_e32 v5, v81
	v_pk_add_f32 v[2:3], v[2:3], v[4:5]
	v_add_f32_e32 v0, v0, v1
	v_pk_add_f32 v[2:3], v[2:3], v[2:3] op_sel_hi:[0,1]
	v_add_f32_e32 v1, 0, v0
	v_add_f32_e32 v5, v46, v47
	v_add_f32_e32 v7, v44, v45
	v_mov_b32_e32 v4, v42
	v_mov_b32_e32 v6, v43
	v_mov_b32_e32 v2, v40
	v_mov_b32_e32 v0, v41
	v_pk_add_f32 v[4:5], v[4:5], v[6:7]
	v_pk_add_f32 v[0:1], v[2:3], v[0:1]
	s_nop 0
	v_pk_add_f32 v[0:1], v[4:5], v[0:1]
	s_nop 0
	v_add_f32_e32 v0, v0, v1
	v_mov_b32_e32 v1, v0
	s_nop 1
	v_permlane16_swap_b32_e32 v0, v1
	s_waitcnt lgkmcnt(0)
	v_add_f32_e32 v0, v0, v1
	v_mov_b32_e32 v1, v0
	s_nop 1
	v_permlane32_swap_b32_e32 v0, v1
	s_waitcnt lgkmcnt(0)
	v_add_f32_e32 v0, v0, v1
	v_fmamk_f32 v2, v0, 0xbc800000, v85
	v_fmamk_f32 v4, v0, 0xbc800000, v89
	v_fmamk_f32 v1, v0, 0xbc800000, v84
	v_fmamk_f32 v3, v0, 0xbc800000, v88
	v_mul_f32_e32 v4, v4, v4
	v_mul_f32_e32 v2, v2, v2
	v_fmac_f32_e32 v4, v3, v3
	v_fmac_f32_e32 v2, v1, v1
	v_fmamk_f32 v3, v0, 0xbc800000, v81
	v_fmamk_f32 v5, v0, 0xbc800000, v83
	v_add_f32_e32 v1, v4, v2
	v_fmamk_f32 v2, v0, 0xbc800000, v80
	v_fmamk_f32 v4, v0, 0xbc800000, v82
	v_mul_f32_e32 v5, v5, v5
	v_mul_f32_e32 v3, v3, v3
	v_fmac_f32_e32 v5, v4, v4
	v_fmac_f32_e32 v3, v2, v2
	v_add_f32_e32 v2, v5, v3
	v_fmamk_f32 v3, v0, 0xbc800000, v45
	v_fmamk_f32 v5, v0, 0xbc800000, v47
	v_add_f32_e32 v1, v1, v2
	v_fmamk_f32 v2, v0, 0xbc800000, v44
	v_fmamk_f32 v4, v0, 0xbc800000, v46
	v_mul_f32_e32 v5, v5, v5
	v_mul_f32_e32 v3, v3, v3
	v_fmac_f32_e32 v5, v4, v4
	v_fmac_f32_e32 v3, v2, v2
	v_add_f32_e32 v2, v5, v3
	v_fmamk_f32 v3, v0, 0xbc800000, v41
	v_fmamk_f32 v5, v0, 0xbc800000, v43
	v_add_f32_e32 v1, v2, v1
	v_fmamk_f32 v2, v0, 0xbc800000, v40
	v_fmamk_f32 v4, v0, 0xbc800000, v42
	v_mul_f32_e32 v5, v5, v5
	v_mul_f32_e32 v3, v3, v3
	v_fmac_f32_e32 v5, v4, v4
	v_fmac_f32_e32 v3, v2, v2
	v_add_f32_e32 v2, v5, v3
	v_add_f32_e32 v1, v2, v1
	v_mov_b32_e32 v2, v1
	s_nop 1
	v_permlane16_swap_b32_e32 v1, v2
	s_waitcnt lgkmcnt(0)
	v_add_f32_e32 v1, v1, v2
	v_mov_b32_e32 v2, v1
	s_nop 1
	v_permlane32_swap_b32_e32 v1, v2
	s_and_saveexec_b64 s[4:5], vcc
	s_cbranch_execz .LBB0_456
	s_lshl_b32 s7, s25, 11
	s_add_i32 s6, s6, s7
	v_mul_f32_e32 v0, 0x3c800000, v0
	v_lshl_add_u32 v3, v241, 5, s6
	s_waitcnt lgkmcnt(0)
	v_add_f32_e32 v1, v1, v2
	ds_write_b64 v3, v[0:1] offset:5632
